# write-through (sc1) stores in P2 and in the P3 late-tile epilogues: little dirty L2 data left for the grid barriers' write-back
# speedup vs baseline: 1.0084x; 1.0033x over previous
; #define GAS __attribute__((address_space(1)))
; #define LAS __attribute__((address_space(3)))
; #define LDS_BAR() do { asm volatile("s_waitcnt lgkmcnt(0)" ::: "memory"); __builtin_amdgcn_s_barrier(); asm volatile("" ::: "memory"); } while (0)
; __device__ __forceinline__ u64_t pack4(const f32x4 v) { return (u64_t)pk2(v[0], v[1]) | ((u64_t)pk2(v[2], v[3]) << 32); }
; __device__ __forceinline__ void p2_hg_unit(LAS unsigned char* lds, bf16_t* region, bf16_t* oloc, float* dec, int tid_in, int lane_in, int wave_in, HgRaw& R, const bf16_t* next_region, const bool ST = true) {
;     ...
;     for (int e = 0; e < 2; ++e) { const int idx = wave * 2 + e, si = idx >> 2, tj = idx & 3;
;         f32x4 acc = (f32x4){0.f, 0.f, 0.f, 0.f};
;         if (si <= tj) acc = mma_nt<128>(KT + si * 16 * 136, 136, QT + tj * 16 * 136, 136, acc, r, g);
;         const int t = 16 * tj + r, s0 = 16 * si + 4 * g;
; #pragma unroll
;         for (int i = 0; i < 4; ++i) acc[i] = (s0 + i <= t) ? acc[i] : 0.f;
;         *(LAS u64_t*)(PP + t * 72 + s0) = pack4(acc); }
; #pragma unroll
;     for (int e = 0; e < 2; ++e) { const int id = tid + 512 * e, mt = id >> 8, kb = (id >> 6) & 3, l = id & 63, r_ = l & 15, g_ = l >> 4;
;         const LAS bf16_t* src = QT + (16 * mt + r_) * 136 + 32 * kb + 4 * g_;
;         const u64_t lo = *(const LAS u64_t*)src, hi = *(const LAS u64_t*)(src + 16);
;         if (ST) *(GAS v4u*)(region + (size_t)id * 8) = (v4u){(unsigned)lo, (unsigned)(lo >> 32), (unsigned)hi, (unsigned)(hi >> 32)}; }
;     LDS_BAR();
.LBB0_406:
	v_lshl_or_b32 v93, s48, 4, v1
	v_cmp_le_i32_e32 vcc, v98, v93
	v_lshlrev_b32_e32 v95, 3, v99
	v_lshlrev_b32_e32 v112, 1, v95
	s_nop 2
	v_cndmask_b32_e32 v88, 0, v88, vcc
	v_cmp_lt_i32_e32 vcc, v98, v93
	s_nop 1
	v_cndmask_b32_e32 v89, 0, v89, vcc
	v_cmp_le_i32_e32 vcc, v100, v93
	v_cvt_pk_bf16_f32 v88, v88, v89
	s_nop 0
	v_cndmask_b32_e32 v90, 0, v90, vcc
	v_cmp_le_i32_e32 vcc, v92, v93
	s_nop 1
	v_cndmask_b32_e32 v91, 0, v91, vcc
	v_cvt_pk_bf16_f32 v89, v90, v91
	v_mad_u32_u24 v90, v93, s70, v97
	ds_write_b64 v90, v[88:89]
	v_lshrrev_b32_e32 v88, 1, v114
	v_and_b32_e32 v89, 0xc0, v114
	v_and_b32_e32 v88, 24, v88
	v_add3_u32 v92, 0, v89, v88
	v_and_or_b32 v88, v115, s71, v1
	v_mad_u64_u32 v[88:89], s[48:49], v88, s69, v[92:93]
	ds_read2_b64 v[88:91], v88 offset1:4
	s_add_u32 s48, s60, s10
	v_ashrrev_i32_e32 v115, 31, v114
	s_addc_u32 s49, s61, s11
	v_lshl_add_u64 v[96:97], v[114:115], 4, s[48:49]
	v_add_co_u32_e32 v96, vcc, s72, v96
	s_lshl_b32 s41, s41, 2
	s_nop 0
	v_addc_co_u32_e32 v97, vcc, 0, v97, vcc
	s_waitcnt lgkmcnt(0)
	global_store_dwordx4 v[96:97], v[88:91], off sc1
	v_add_u32_e32 v96, 0x200, v114
	v_ashrrev_i32_e32 v97, 31, v96
	v_lshrrev_b32_e32 v88, 4, v96
	v_and_or_b32 v88, v88, s71, v1
	v_mad_u64_u32 v[88:89], s[50:51], v88, s69, v[92:93]
	ds_read2_b64 v[88:91], v88 offset1:4
	v_lshl_add_u64 v[92:93], v[96:97], 4, s[48:49]
	v_add_co_u32_e32 v92, vcc, s72, v92
	s_and_b32 s41, s41, 4
	s_nop 0
	v_addc_co_u32_e32 v93, vcc, 0, v93, vcc
	s_waitcnt lgkmcnt(0)
	global_store_dwordx4 v[92:93], v[88:91], off sc1
	s_mul_i32 s50, s4, 0x900
	s_add_i32 s50, s50, 0
	v_lshlrev_b32_e32 v88, 7, v1
	v_sub_u32_e32 v88, v94, v88
	v_add_u32_e32 v115, v88, v112
	s_mul_i32 s79, s41, 0x900
	s_waitcnt lgkmcnt(0)
	s_barrier
; #define GAS __attribute__((address_space(1)))
; #define LDS_BAR() do { asm volatile("s_waitcnt lgkmcnt(0)" ::: "memory"); __builtin_amdgcn_s_barrier(); asm volatile("" ::: "memory"); } while (0)
; __device__ __forceinline__ u64_t pack4(const f32x4 v) { return (u64_t)pk2(v[0], v[1]) | ((u64_t)pk2(v[2], v[3]) << 32); }
; __device__ __forceinline__ void p2_hg_unit(LAS unsigned char* lds, bf16_t* region, bf16_t* oloc, float* dec, int tid_in, int lane_in, int wave_in, HgRaw& R, const bf16_t* next_region, const bool ST = true) {
;     ...
;     if (next_region) hg_load_raw(R, next_region, tid);
;     ...
;     for (int e = 0; e < 4; ++e) { const int tile = wave * 4 + e, ti = tile >> 3, vj = tile & 7;
;         f32x4 acc = (f32x4){0.f, 0.f, 0.f, 0.f};
;         acc = mma_nt<64>(VT + vj * 16 * 72, 72, PP + ti * 16 * 72, 72, acc, r, g);
;         if (ST) *(GAS u64_t*)(oloc + (size_t)((vj * 4 + ti) * 64 + lane) * 4) = pack4(acc); }
; #pragma unroll
;     for (int e = 0; e < 4; ++e) { const int vj = 4 * (wave & 1) + e, kb = wave >> 1; f32x4 a0 = (f32x4){0.f, 0.f, 0.f, 0.f}, a1 = a0;
;         a0 = mma_nt<64>(KH + (2 * kb) * 16 * 72, 72, VT + vj * 16 * 72, 72, a0, r, g);
;         a1 = mma_nt<64>(KH + (2 * kb + 1) * 16 * 72, 72, VT + vj * 16 * 72, 72, a1, r, g);
;         const u64_t lo = pack4(a0), hi = pack4(a1);
;         if (ST) *(GAS v4u*)(region + 8192 + (size_t)((vj * 4 + kb) * 64 + lane) * 8) = (v4u){(unsigned)lo, (unsigned)(lo >> 32), (unsigned)hi, (unsigned)(hi >> 32)}; }
;     LDS_BAR();
	s_add_i32 s50, s50, 0x11800
	v_add_u32_e32 v92, s79, v115
	v_mul_u32_u24_e32 v1, 0x90, v1
	ds_read_b128 v[88:91], v92 offset:53248
	v_add3_u32 v100, s50, v1, v112
	s_add_u32 s50, s60, s74
	s_addc_u32 s51, s61, s75
	s_add_i32 s80, s79, 0x900
	v_add_u32_e32 v116, s80, v115
	s_add_i32 s80, s79, 0x1200
	v_add_u32_e32 v128, s80, v115
	ds_read_b128 v[92:95], v92 offset:53312
	ds_read_b128 v[96:99], v100
	ds_read_b128 v[100:103], v100 offset:64
	ds_read_b128 v[108:111], v116 offset:53248
	ds_read_b128 v[116:119], v116 offset:53312
	ds_read_b128 v[124:127], v128 offset:53248
	s_addk_i32 s79, 0x1b00
	v_add_u32_e32 v140, s79, v115
	ds_read_b128 v[136:139], v140 offset:53248
	ds_read_b128 v[128:131], v128 offset:53312
	s_waitcnt lgkmcnt(6)
	v_mfma_f32_16x16x32_bf16 v[104:107], v[88:91], v[96:99], 0
	v_and_b32_e32 v114, 63, v114
	v_lshl_or_b32 v144, s4, 6, v114
	s_mulk_i32 s4, 0x1200
	s_waitcnt lgkmcnt(5)
	v_mfma_f32_16x16x32_bf16 v[104:107], v[92:95], v[100:103], v[104:107]
	v_lshl_add_u32 v152, s41, 8, v144
	s_add_i32 s4, s4, 0
	v_ashrrev_i32_e32 v153, 31, v152
	s_waitcnt lgkmcnt(2)
	v_mfma_f32_16x16x32_bf16 v[132:135], v[124:127], v[96:99], 0
	v_add3_u32 v1, s4, v1, v112
	s_nop 1
	v_cvt_pk_bf16_f32 v114, v104, v105
	v_cvt_pk_bf16_f32 v115, v106, v107
	s_waitcnt lgkmcnt(0)
	v_mfma_f32_16x16x32_bf16 v[104:107], v[128:131], v[100:103], v[132:135]
	ds_read_b128 v[144:147], v1 offset:34880
	v_add_u32_e32 v154, 0x100, v152
	v_ashrrev_i32_e32 v155, 31, v154
	ds_read_b128 v[132:135], v140 offset:53312
	v_mfma_f32_16x16x32_bf16 v[120:123], v[108:111], v[96:99], 0
	ds_read_b128 v[140:143], v1 offset:34816
	v_lshl_add_u64 v[156:157], v[154:155], 3, s[50:51]
	s_nop 0
	v_cvt_pk_bf16_f32 v104, v104, v105
	v_mfma_f32_16x16x32_bf16 v[96:99], v[136:139], v[96:99], 0
	v_cvt_pk_bf16_f32 v105, v106, v107
	s_add_u32 s46, s46, s22
	s_addc_u32 s47, s47, s23
	v_mfma_f32_16x16x32_bf16 v[120:123], v[116:119], v[100:103], v[120:123]
	s_add_u32 s74, s74, s36
	s_addc_u32 s75, s75, s37
	s_add_u32 s10, s10, s38
	s_waitcnt lgkmcnt(1)
	v_mfma_f32_16x16x32_bf16 v[96:99], v[132:135], v[100:103], v[96:99]
	v_lshl_add_u64 v[100:101], v[152:153], 3, s[50:51]
	global_store_dwordx2 v[100:101], v[114:115], off sc1
	ds_read_b128 v[100:103], v1 offset:37120
	v_cvt_pk_bf16_f32 v114, v120, v121
	v_cvt_pk_bf16_f32 v115, v122, v123
	ds_read_b128 v[120:123], v1 offset:37184
	s_waitcnt lgkmcnt(2)
	v_mfma_f32_16x16x32_bf16 v[148:151], v[140:143], v[88:91], 0
	global_store_dwordx2 v[156:157], v[114:115], off sc1
	v_add_u32_e32 v114, 0x200, v152
	v_ashrrev_i32_e32 v115, 31, v114
	s_waitcnt lgkmcnt(1)
	v_mfma_f32_16x16x32_bf16 v[88:91], v[100:103], v[88:91], 0
	v_lshl_add_u64 v[106:107], v[114:115], 3, s[50:51]
	global_store_dwordx2 v[106:107], v[104:105], off sc1
	v_cvt_pk_bf16_f32 v104, v96, v97
	v_mfma_f32_16x16x32_bf16 v[148:151], v[144:147], v[92:95], v[148:151]
	v_cvt_pk_bf16_f32 v105, v98, v99
	v_add_u32_e32 v156, 0x300, v152
	v_ashrrev_i32_e32 v157, 31, v156
	s_waitcnt lgkmcnt(0)
	v_mfma_f32_16x16x32_bf16 v[88:91], v[120:123], v[92:95], v[88:91]
	v_lshl_add_u64 v[106:107], v[156:157], 3, s[50:51]
	global_store_dwordx2 v[106:107], v[104:105], off sc1
	s_nop 0
	v_cvt_pk_bf16_f32 v104, v148, v149
	v_mfma_f32_16x16x32_bf16 v[92:95], v[140:143], v[108:111], 0
	v_cvt_pk_bf16_f32 v105, v150, v151
	s_nop 1
	v_cvt_pk_bf16_f32 v106, v88, v89
	v_cvt_pk_bf16_f32 v107, v90, v91
	v_mfma_f32_16x16x32_bf16 v[96:99], v[100:103], v[108:111], 0
	v_lshl_add_u64 v[108:109], v[152:153], 4, s[48:49]
	v_add_co_u32_e32 v108, vcc, s73, v108
	v_mfma_f32_16x16x32_bf16 v[92:95], v[144:147], v[116:119], v[92:95]
	s_nop 0
	v_addc_co_u32_e32 v109, vcc, 0, v109, vcc
	global_store_dwordx4 v[108:109], v[104:107], off sc1
	v_mfma_f32_16x16x32_bf16 v[96:99], v[120:123], v[116:119], v[96:99]
	v_lshl_add_u64 v[108:109], v[154:155], 4, s[48:49]
	s_nop 2
	v_cvt_pk_bf16_f32 v92, v92, v93
	v_cvt_pk_bf16_f32 v93, v94, v95
	v_mfma_f32_16x16x32_bf16 v[88:91], v[140:143], v[124:127], 0
	v_add_co_u32_e32 v108, vcc, s73, v108
	v_cvt_pk_bf16_f32 v94, v96, v97
	v_mfma_f32_16x16x32_bf16 v[104:107], v[100:103], v[124:127], 0
	v_cvt_pk_bf16_f32 v95, v98, v99
	v_addc_co_u32_e32 v109, vcc, 0, v109, vcc
	v_mfma_f32_16x16x32_bf16 v[88:91], v[144:147], v[128:131], v[88:91]
	global_store_dwordx4 v[108:109], v[92:95], off sc1
	s_addc_u32 s11, s11, s39
	s_waitcnt vmcnt(11)
	v_mov_b64_e32 v[110:111], v[74:75]
	v_mfma_f32_16x16x32_bf16 v[96:99], v[120:123], v[128:131], v[104:107]
	s_cmp_gt_i32 s40, s98
	s_nop 1
	v_cvt_pk_bf16_f32 v88, v88, v89
	v_cvt_pk_bf16_f32 v89, v90, v91
	v_mfma_f32_16x16x32_bf16 v[104:107], v[140:143], v[136:139], 0
	v_mov_b64_e32 v[108:109], v[72:73]
	s_nop 0
	v_cvt_pk_bf16_f32 v90, v96, v97
	v_cvt_pk_bf16_f32 v91, v98, v99
	v_mfma_f32_16x16x32_bf16 v[96:99], v[100:103], v[136:139], 0
	v_mfma_f32_16x16x32_bf16 v[92:95], v[144:147], v[132:135], v[104:107]
	s_nop 2
	v_lshl_add_u64 v[104:105], v[114:115], 4, s[48:49]
	v_add_co_u32_e32 v100, vcc, s73, v104
	s_nop 2
	v_cvt_pk_bf16_f32 v92, v92, v93
	v_addc_co_u32_e32 v101, vcc, 0, v105, vcc
	global_store_dwordx4 v[100:101], v[88:91], off sc1
	v_cvt_pk_bf16_f32 v93, v94, v95
	s_waitcnt vmcnt(11)
	v_mov_b64_e32 v[106:107], v[78:79]
	v_mfma_f32_16x16x32_bf16 v[88:91], v[120:123], v[132:135], v[96:99]
	v_mov_b64_e32 v[102:103], v[64:65]
	v_mov_b64_e32 v[104:105], v[76:77]
	v_mov_b64_e32 v[100:101], v[62:63]
	v_mov_b64_e32 v[98:99], v[70:71]
	v_mov_b64_e32 v[96:97], v[68:69]
	s_nop 2
	v_cvt_pk_bf16_f32 v94, v88, v89
	v_lshl_add_u64 v[88:89], v[156:157], 4, s[48:49]
	v_add_co_u32_e32 v88, vcc, s73, v88
	v_cvt_pk_bf16_f32 v95, v90, v91
	s_nop 0
	v_addc_co_u32_e32 v89, vcc, 0, v89, vcc
	global_store_dwordx4 v[88:89], v[92:95], off sc1
	s_waitcnt lgkmcnt(0)
	s_barrier
	s_waitcnt vmcnt(10)
	v_mov_b64_e32 v[90:91], v[86:87]
	v_mov_b64_e32 v[94:95], v[82:83]
	v_mov_b64_e32 v[88:89], v[84:85]
	v_mov_b64_e32 v[92:93], v[80:81]
	s_cbranch_scc1 .LBB0_423

; #define LAS __attribute__((address_space(3)))
; #define LDS_BAR() do { asm volatile("s_waitcnt lgkmcnt(0)" ::: "memory"); __builtin_amdgcn_s_barrier(); asm volatile("" ::: "memory"); } while (0)
; __device__ __forceinline__ void p2_hg_unit(LAS unsigned char* lds, bf16_t* region, bf16_t* oloc, float* dec, int tid_in, int lane_in, int wave_in, HgRaw& R, const bf16_t* next_region, const bool ST = true) {
;     ...
;     {
;         const int c_ = tid & 127, q_ = tid >> 7; LAS float* TQ = (LAS float*)KHR; float x_[8], t_ = 0.f;
; #pragma unroll
;         for (int k = 0; k < 8; ++k) { x_[k] = PS[(8 * q_ + k) * 128 + c_]; t_ += x_[k]; }
;         TQ[q_ * 128 + c_] = t_;
;         LDS_BAR();
;         float run = 0.f;
; #pragma unroll
;         for (int p = 0; p < 3; ++p) run += (p < q_) ? TQ[p * 128 + c_] : 0.f;
; #pragma unroll
;         for (int k = 0; k < 8; ++k) { PS[(8 * q_ + k) * 128 + c_] = run; run += x_[k]; }
;         if (q_ == 3) PS[32 * 128 + c_] = run;
;     }
;     __syncthreads();
;     f32x4 pre[2], tot[2];
; #pragma unroll
;     for (int hh = 0; hh < 2; ++hh) { pre[hh] = *(const LAS f32x4*)(PS + rg * 128 + 8 * cg + 4 * hh); tot[hh] = *(const LAS f32x4*)(PS + 32 * 128 + 8 * cg + 4 * hh); }
;     {
;         f32x4 qt[2][2], kt[2][2], kh[2][2];
; #pragma unroll
;         for (int hh = 0; hh < 2; ++hh) { f32x4 bi = pre[hh];
; #pragma unroll
;             for (int rr = 0; rr < 2; ++rr) { bi += lf[rr][hh];
; #pragma unroll
;                 for (int i = 0; i < 4; ++i) { const float kk = 1.f - __expf(lf[rr][hh][i]); qt[rr][hh][i] = q[rr][hh][i] * __expf(bi[i]); kt[rr][hh][i] = kk * __expf(-bi[i]); kh[rr][hh][i] = kk * __expf(tot[hh][i] - bi[i]); } } }
.LBB0_411:
	s_or_b64 exec, exec, s[48:49]
	v_cmp_lt_i32_e32 vcc, 1, v132
	s_and_saveexec_b64 s[48:49], vcc
	ds_read_b32 v135, v137 offset:512
	s_or_b64 exec, exec, s[48:49]
	v_cmp_lt_i32_e32 vcc, 2, v132
	v_mov_b32_e32 v138, 0
	s_and_saveexec_b64 s[48:49], vcc
	ds_read_b32 v138, v137 offset:1024
	s_or_b64 exec, exec, s[48:49]
	s_waitcnt lgkmcnt(0)
	v_add_f32_e32 v135, v136, v135
	v_add_f32_e32 v135, v135, v138
	v_add_f32_e32 v120, v120, v135
	ds_write2st64_b32 v134, v135, v120 offset1:2
	v_add_f32_e32 v120, v121, v120
	v_add_f32_e32 v121, v128, v120
	ds_write2st64_b32 v134, v120, v121 offset0:4 offset1:6
	v_add_f32_e32 v120, v129, v121
	v_add_f32_e32 v121, v130, v120
	ds_write2st64_b32 v134, v120, v121 offset0:8 offset1:10
	v_add_f32_e32 v120, v131, v121
	v_add_f32_e32 v106, v106, v120
	v_cmp_eq_u32_e32 vcc, 3, v132
	ds_write2st64_b32 v134, v120, v106 offset0:12 offset1:14
	s_and_saveexec_b64 s[48:49], vcc
	v_lshl_add_u32 v120, v133, 2, s76
	v_add_f32_e32 v106, v107, v106
	ds_write_b32 v120, v106 offset:16384
	s_or_b64 exec, exec, s[48:49]
	s_waitcnt lgkmcnt(0)
	s_barrier
	ds_read_b128 v[128:131], v112
	v_lshlrev_b32_e32 v144, 16, v96
	v_and_b32_e32 v145, 0xffff0000, v96
	v_lshl_add_u32 v96, v1, 5, 0
	v_add_u32_e32 v96, 0x17c00, v96
	v_lshlrev_b32_e32 v106, 16, v100
	v_and_b32_e32 v107, 0xffff0000, v100
	v_lshlrev_b32_e32 v138, 16, v101
	v_and_b32_e32 v139, 0xffff0000, v101
	v_lshlrev_b32_e32 v140, 16, v102
	v_and_b32_e32 v141, 0xffff0000, v102
	v_lshlrev_b32_e32 v142, 16, v103
	v_and_b32_e32 v143, 0xffff0000, v103
	v_lshlrev_b32_e32 v146, 16, v97
	v_and_b32_e32 v147, 0xffff0000, v97
	v_lshlrev_b32_e32 v148, 16, v98
	v_and_b32_e32 v149, 0xffff0000, v98
	v_lshlrev_b32_e32 v120, 16, v99
	v_and_b32_e32 v121, 0xffff0000, v99
	ds_read_b128 v[134:137], v112 offset:16
	ds_read_b128 v[100:103], v96
	ds_read_b128 v[96:99], v96 offset:16
	s_waitcnt lgkmcnt(3)
	v_pk_add_f32 v[128:129], v[128:129], v[126:127]
	v_mul_f32_e32 v112, 0x3fb8aa3b, v126
	v_exp_f32_e32 v126, v112
	v_mul_f32_e32 v112, 0x3fb8aa3b, v128
	v_exp_f32_e32 v150, v112
	v_mul_f32_e32 v112, 0xbfb8aa3b, v128
	v_exp_f32_e32 v152, v112
	s_waitcnt lgkmcnt(1)
	v_sub_f32_e32 v112, v100, v128
	v_mul_f32_e32 v112, 0x3fb8aa3b, v112
	v_exp_f32_e32 v154, v112
	v_mul_f32_e32 v112, 0x3fb8aa3b, v127
	v_exp_f32_e32 v127, v112
	v_mul_f32_e32 v112, 0x3fb8aa3b, v129
	v_sub_f32_e32 v153, v101, v129
	v_exp_f32_e32 v151, v112
	v_mul_f32_e32 v112, 0xbfb8aa3b, v129
	v_mul_f32_e32 v153, 0x3fb8aa3b, v153
	v_exp_f32_e32 v155, v153
	v_exp_f32_e32 v153, v112
	v_pk_add_f32 v[130:131], v[130:131], v[124:125]
	v_mul_f32_e32 v112, 0x3fb8aa3b, v124
	v_pk_add_f32 v[126:127], v[126:127], 1.0 op_sel_hi:[1,0] neg_lo:[1,0] neg_hi:[1,0]
	v_exp_f32_e32 v124, v112
	v_mul_f32_e32 v112, 0x3fb8aa3b, v130
	v_pk_mul_f32 v[150:151], v[150:151], v[106:107]
	v_pk_mul_f32 v[106:107], v[126:127], v[154:155]
	v_pk_mul_f32 v[126:127], v[126:127], v[152:153]
	v_exp_f32_e32 v152, v112
	v_mul_f32_e32 v112, 0xbfb8aa3b, v130
	v_exp_f32_e32 v154, v112
	v_sub_f32_e32 v112, v102, v130
	v_mul_f32_e32 v112, 0x3fb8aa3b, v112
	v_exp_f32_e32 v156, v112
	v_mul_f32_e32 v112, 0x3fb8aa3b, v125
	v_exp_f32_e32 v125, v112
	v_mul_f32_e32 v112, 0x3fb8aa3b, v131
	v_sub_f32_e32 v155, v103, v131
	v_exp_f32_e32 v153, v112
	v_mul_f32_e32 v112, 0xbfb8aa3b, v131
	v_mul_f32_e32 v155, 0x3fb8aa3b, v155
	v_exp_f32_e32 v157, v155
	v_exp_f32_e32 v155, v112
	v_pk_add_f32 v[128:129], v[128:129], v[122:123]
	v_mul_f32_e32 v112, 0x3fb8aa3b, v122
	v_pk_add_f32 v[124:125], v[124:125], 1.0 op_sel_hi:[1,0] neg_lo:[1,0] neg_hi:[1,0]
	v_exp_f32_e32 v122, v112
	v_mul_f32_e32 v112, 0x3fb8aa3b, v128
	v_pk_mul_f32 v[138:139], v[152:153], v[138:139]
	v_pk_mul_f32 v[152:153], v[124:125], v[156:157]
	v_pk_mul_f32 v[124:125], v[124:125], v[154:155]
	v_exp_f32_e32 v154, v112
	v_mul_f32_e32 v112, 0xbfb8aa3b, v128
	v_exp_f32_e32 v156, v112
	v_sub_f32_e32 v112, v100, v128
	v_mul_f32_e32 v112, 0x3fb8aa3b, v112
	v_exp_f32_e32 v128, v112
	v_mul_f32_e32 v112, 0x3fb8aa3b, v123
	v_exp_f32_e32 v123, v112
	v_mul_f32_e32 v112, 0x3fb8aa3b, v129
	v_exp_f32_e32 v155, v112
	v_mul_f32_e32 v112, 0xbfb8aa3b, v129
	v_sub_f32_e32 v129, v101, v129
	v_mul_f32_e32 v129, 0x3fb8aa3b, v129
	v_exp_f32_e32 v129, v129
	v_exp_f32_e32 v157, v112
	v_pk_add_f32 v[130:131], v[130:131], v[118:119]
	v_mul_f32_e32 v112, 0x3fb8aa3b, v118
	v_exp_f32_e32 v118, v112
	v_mul_f32_e32 v112, 0x3fb8aa3b, v130
	v_pk_mul_f32 v[144:145], v[154:155], v[144:145]
	v_pk_add_f32 v[122:123], v[122:123], 1.0 op_sel_hi:[1,0] neg_lo:[1,0] neg_hi:[1,0]
	v_exp_f32_e32 v154, v112
	v_mul_f32_e32 v112, 0xbfb8aa3b, v130
	v_pk_mul_f32 v[128:129], v[122:123], v[128:129]
	v_pk_mul_f32 v[122:123], v[122:123], v[156:157]
	v_exp_f32_e32 v156, v112
	v_sub_f32_e32 v112, v102, v130
	v_mul_f32_e32 v112, 0x3fb8aa3b, v112
	v_exp_f32_e32 v130, v112
	v_mul_f32_e32 v112, 0x3fb8aa3b, v119
	v_exp_f32_e32 v119, v112
	v_mul_f32_e32 v112, 0x3fb8aa3b, v131
	v_exp_f32_e32 v155, v112
	v_mul_f32_e32 v112, 0xbfb8aa3b, v131
	v_sub_f32_e32 v131, v103, v131
	v_mul_f32_e32 v131, 0x3fb8aa3b, v131
	v_exp_f32_e32 v131, v131
	v_exp_f32_e32 v157, v112
	v_pk_add_f32 v[134:135], v[134:135], v[116:117]
	v_mul_f32_e32 v112, 0x3fb8aa3b, v116
	v_exp_f32_e32 v116, v112
	v_mul_f32_e32 v112, 0x3fb8aa3b, v134
	v_pk_mul_f32 v[146:147], v[154:155], v[146:147]
	v_pk_add_f32 v[118:119], v[118:119], 1.0 op_sel_hi:[1,0] neg_lo:[1,0] neg_hi:[1,0]
	v_exp_f32_e32 v154, v112
	v_mul_f32_e32 v112, 0xbfb8aa3b, v134
	v_pk_mul_f32 v[130:131], v[118:119], v[130:131]
	v_pk_mul_f32 v[118:119], v[118:119], v[156:157]
	v_exp_f32_e32 v156, v112
	s_waitcnt lgkmcnt(0)
; __device__ __forceinline__ u32x4 pack8(const f32x4 a, const f32x4 b) { u32x4 w; w.x = cvt_pk_bf16(a[0], a[1]); w.y = cvt_pk_bf16(a[2], a[3]); w.z = cvt_pk_bf16(b[0], b[1]); w.w = cvt_pk_bf16(b[2], b[3]); return w; }
; #define GAS __attribute__((address_space(1)))
; #define LAS __attribute__((address_space(3)))
; __device__ __forceinline__ void p2_hg_unit(LAS unsigned char* lds, bf16_t* region, bf16_t* oloc, float* dec, int tid_in, int lane_in, int wave_in, HgRaw& R, const bf16_t* next_region, const bool ST = true) {
;     ...
;         for (int hh = 0; hh < 2; ++hh) { f32x4 bi = pre[hh];
; #pragma unroll
;             for (int rr = 0; rr < 2; ++rr) { bi += lf[rr][hh];
; #pragma unroll
;                 for (int i = 0; i < 4; ++i) { const float kk = 1.f - __expf(lf[rr][hh][i]); qt[rr][hh][i] = q[rr][hh][i] * __expf(bi[i]); kt[rr][hh][i] = kk * __expf(-bi[i]); kh[rr][hh][i] = kk * __expf(tot[hh][i] - bi[i]); } } }
; #pragma unroll
;         for (int rr = 0; rr < 2; ++rr) { *(LAS v4u*)(QT + (t0 + rr) * 136 + 8 * cg) = pack8(qt[rr][0], qt[rr][1]); *(LAS v4u*)(KT + (t0 + rr) * 136 + 8 * cg) = pack8(kt[rr][0], kt[rr][1]); }
; #pragma unroll
;         for (int rr = 0; rr < 2; ++rr) { *(LAS v4u*)(KHR + (t0 + rr) * 136 + 8 * cg) = pack8(kh[rr][0], kh[rr][1]); *(LAS v4u*)(VR + (t0 + rr) * 136 + 8 * cg) = R_v[rr]; }
;         if (rg == 0 && ST) {
; #pragma unroll
;             for (int hh = 0; hh < 2; ++hh) { f32x4 dv;
; #pragma unroll
;                 for (int i = 0; i < 4; ++i) dv[i] = __expf(tot[hh][i]);
;                 *(GAS f32x4*)(dec + 8 * cg + 4 * hh) = dv; } }
	v_sub_f32_e32 v112, v96, v134
	v_mul_f32_e32 v112, 0x3fb8aa3b, v112
	v_exp_f32_e32 v158, v112
	v_mul_f32_e32 v112, 0x3fb8aa3b, v117
	v_exp_f32_e32 v117, v112
	v_mul_f32_e32 v112, 0x3fb8aa3b, v135
	v_sub_f32_e32 v157, v97, v135
	v_exp_f32_e32 v155, v112
	v_mul_f32_e32 v112, 0xbfb8aa3b, v135
	v_mul_f32_e32 v157, 0x3fb8aa3b, v157
	v_exp_f32_e32 v159, v157
	v_exp_f32_e32 v157, v112
	v_pk_add_f32 v[136:137], v[136:137], v[110:111]
	v_pk_add_f32 v[116:117], v[116:117], 1.0 op_sel_hi:[1,0] neg_lo:[1,0] neg_hi:[1,0]
	v_mul_f32_e32 v112, 0x3fb8aa3b, v136
	v_pk_mul_f32 v[140:141], v[154:155], v[140:141]
	v_pk_mul_f32 v[154:155], v[116:117], v[158:159]
	v_pk_mul_f32 v[116:117], v[116:117], v[156:157]
	v_exp_f32_e32 v156, v112
	v_mul_f32_e32 v112, 0xbfb8aa3b, v136
	v_exp_f32_e32 v158, v112
	v_sub_f32_e32 v112, v98, v136
	v_mul_f32_e32 v112, 0x3fb8aa3b, v112
	v_mul_f32_e32 v110, 0x3fb8aa3b, v110
	v_exp_f32_e32 v160, v112
	v_mul_f32_e32 v111, 0x3fb8aa3b, v111
	v_mul_f32_e32 v112, 0x3fb8aa3b, v137
	v_sub_f32_e32 v159, v99, v137
	v_exp_f32_e32 v110, v110
	v_exp_f32_e32 v111, v111
	v_exp_f32_e32 v157, v112
	v_mul_f32_e32 v112, 0xbfb8aa3b, v137
	v_mul_f32_e32 v159, 0x3fb8aa3b, v159
	v_exp_f32_e32 v161, v159
	v_exp_f32_e32 v159, v112
	v_pk_add_f32 v[134:135], v[134:135], v[108:109]
	v_pk_add_f32 v[110:111], v[110:111], 1.0 op_sel_hi:[1,0] neg_lo:[1,0] neg_hi:[1,0]
	v_mul_f32_e32 v112, 0x3fb8aa3b, v134
	v_pk_mul_f32 v[142:143], v[156:157], v[142:143]
	v_pk_mul_f32 v[156:157], v[110:111], v[160:161]
	v_pk_mul_f32 v[158:159], v[110:111], v[158:159]
	v_pk_add_f32 v[110:111], v[136:137], v[104:105]
	v_exp_f32_e32 v136, v112
	v_mul_f32_e32 v112, 0xbfb8aa3b, v134
	v_exp_f32_e32 v160, v112
	v_sub_f32_e32 v112, v96, v134
	v_mul_f32_e32 v112, 0x3fb8aa3b, v112
	v_exp_f32_e32 v134, v112
	v_mul_f32_e32 v112, 0x3fb8aa3b, v135
	v_mul_f32_e32 v108, 0x3fb8aa3b, v108
	v_mul_f32_e32 v109, 0x3fb8aa3b, v109
	v_exp_f32_e32 v137, v112
	v_mul_f32_e32 v112, 0xbfb8aa3b, v135
	v_sub_f32_e32 v135, v97, v135
	v_exp_f32_e32 v108, v108
	v_exp_f32_e32 v109, v109
	v_mul_f32_e32 v135, 0x3fb8aa3b, v135
	v_exp_f32_e32 v135, v135
	v_exp_f32_e32 v161, v112
	v_pk_add_f32 v[108:109], v[108:109], 1.0 op_sel_hi:[1,0] neg_lo:[1,0] neg_hi:[1,0]
	v_pk_mul_f32 v[136:137], v[136:137], v[148:149]
	v_pk_mul_f32 v[134:135], v[108:109], v[134:135]
	v_pk_mul_f32 v[148:149], v[108:109], v[160:161]
	v_mul_f32_e32 v109, 0xbfb8aa3b, v110
	v_exp_f32_e32 v160, v109
	v_sub_f32_e32 v109, v98, v110
	v_mul_f32_e32 v109, 0x3fb8aa3b, v109
	v_mul_f32_e32 v104, 0x3fb8aa3b, v104
	v_mul_f32_e32 v108, 0x3fb8aa3b, v110
	v_exp_f32_e32 v110, v109
	v_mul_f32_e32 v105, 0x3fb8aa3b, v105
	v_mul_f32_e32 v109, 0x3fb8aa3b, v111
	v_mul_f32_e32 v112, 0xbfb8aa3b, v111
	v_sub_f32_e32 v111, v99, v111
	v_exp_f32_e32 v104, v104
	v_exp_f32_e32 v108, v108
	v_exp_f32_e32 v105, v105
	v_exp_f32_e32 v109, v109
	v_mul_f32_e32 v111, 0x3fb8aa3b, v111
	v_exp_f32_e32 v111, v111
	v_exp_f32_e32 v161, v112
	v_pk_mul_f32 v[120:121], v[108:109], v[120:121]
	v_pk_add_f32 v[104:105], v[104:105], 1.0 op_sel_hi:[1,0] neg_lo:[1,0] neg_hi:[1,0]
	v_lshlrev_b32_e32 v112, 4, v1
	v_cvt_pk_bf16_f32 v109, v138, v139
	v_mul_lo_u32 v138, v115, s33
	v_pk_mul_f32 v[162:163], v[104:105], v[110:111]
	v_cvt_pk_bf16_f32 v108, v150, v151
	v_cvt_pk_bf16_f32 v110, v140, v141
	v_cvt_pk_bf16_f32 v111, v142, v143
	v_add3_u32 v139, 0, v112, v138
	ds_write_b128 v139, v[108:111]
	v_cvt_pk_bf16_f32 v108, v126, v127
	v_cvt_pk_bf16_f32 v109, v124, v125
	v_cvt_pk_bf16_f32 v110, v116, v117
	v_cvt_pk_bf16_f32 v111, v158, v159
	v_pk_mul_f32 v[104:105], v[104:105], v[160:161]
	ds_write_b128 v139, v[108:111] offset:17408
	v_cvt_pk_bf16_f32 v108, v144, v145
	v_cvt_pk_bf16_f32 v109, v146, v147
	v_cvt_pk_bf16_f32 v110, v136, v137
	v_cvt_pk_bf16_f32 v111, v120, v121
	ds_write_b128 v139, v[108:111] offset:272
	v_cvt_pk_bf16_f32 v108, v122, v123
	v_cvt_pk_bf16_f32 v109, v118, v119
	v_cvt_pk_bf16_f32 v110, v148, v149
	v_cvt_pk_bf16_f32 v111, v104, v105
	ds_write_b128 v139, v[108:111] offset:17680
	v_cvt_pk_bf16_f32 v104, v106, v107
	v_cvt_pk_bf16_f32 v105, v152, v153
	v_cvt_pk_bf16_f32 v106, v154, v155
	v_cvt_pk_bf16_f32 v107, v156, v157
	v_add3_u32 v108, s77, v112, v138
	ds_write_b128 v108, v[104:107]
	v_add3_u32 v104, s78, v112, v138
	ds_write_b128 v104, v[92:95]
	v_cvt_pk_bf16_f32 v92, v128, v129
	v_cvt_pk_bf16_f32 v93, v130, v131
	v_cvt_pk_bf16_f32 v94, v134, v135
	v_cvt_pk_bf16_f32 v95, v162, v163
	v_cmp_gt_u32_e32 vcc, 16, v114
	ds_write_b128 v108, v[92:95] offset:272
	ds_write_b128 v104, v[88:91] offset:272
	s_and_saveexec_b64 s[48:49], vcc
	s_cbranch_execz .LBB0_419
	s_add_u32 s50, s60, s46
	v_mul_f32_e32 v88, 0x3fb8aa3b, v100
	v_mul_f32_e32 v89, 0x3fb8aa3b, v101
	v_mul_f32_e32 v90, 0x3fb8aa3b, v102
	v_mul_f32_e32 v91, 0x3fb8aa3b, v103
	v_lshlrev_b32_e32 v112, 3, v114
	s_addc_u32 s51, s61, s47
	v_exp_f32_e32 v88, v88
	v_exp_f32_e32 v89, v89
	v_exp_f32_e32 v90, v90
	v_exp_f32_e32 v91, v91
	v_mul_f32_e32 v92, 0x3fb8aa3b, v96
	v_mul_f32_e32 v93, 0x3fb8aa3b, v97
	v_mul_f32_e32 v94, 0x3fb8aa3b, v98
	v_mul_f32_e32 v95, 0x3fb8aa3b, v99
	v_lshl_add_u64 v[104:105], v[112:113], 2, s[50:51]
	v_exp_f32_e32 v92, v92
	v_exp_f32_e32 v93, v93
	v_exp_f32_e32 v94, v94
	v_exp_f32_e32 v95, v95
	v_add_co_u32_e32 v100, vcc, s66, v104
	s_nop 1
	v_addc_co_u32_e32 v101, vcc, 0, v105, vcc
	global_store_dwordx4 v[100:101], v[88:91], off sc1
	global_store_dwordx4 v[100:101], v[92:95], off offset:16 sc1

; #define LAS __attribute__((address_space(3)))
; #define LDS_BAR() do { asm volatile("s_waitcnt lgkmcnt(0)" ::: "memory"); __builtin_amdgcn_s_barrier(); asm volatile("" ::: "memory"); } while (0)
; #define MFMA16(a, b, c) __builtin_amdgcn_mfma_f32_16x16x32_bf16((a), (b), (c), 0, 0, 0)
; __device__ __forceinline__ u64_t pack4(const f32x4 v) { return (u64_t)pk2(v[0], v[1]) | ((u64_t)pk2(v[2], v[3]) << 32); }
;     ...
;     {
;         LAS bf16_t* XT = (wave < 4) ? VBT : KBT; const int cbase = 32 * (wave & 3);
; #pragma unroll
;         for (int a = 0; a < 4; ++a) {
; #pragma unroll
;             for (int ct = 0; ct < 2; ++ct) { LAS bf16_t* xc = XT + (cbase + 16 * ct + r) * 72;
;                 f32x4 acc = unpack4(*(const LAS u64_t*)(xc + 16 * a + 4 * g));
;                 if (a >= 1) { bf16x8 la = *(const LAS bf16x8*)(NLB + (16 * a + r) * 72 + 8 * g); if (a == 1 && g >= 2) la = (bf16x8){0, 0, 0, 0, 0, 0, 0, 0};
;                     acc = MFMA16(la, *(const LAS bf16x8*)(xc + 8 * g), acc); }
;                 if (a == 3) { bf16x8 la = *(const LAS bf16x8*)(NLB + (48 + r) * 72 + 32 + 8 * g); if (g >= 2) la = (bf16x8){0, 0, 0, 0, 0, 0, 0, 0};
;                     acc = MFMA16(la, *(const LAS bf16x8*)(xc + 32 + 8 * g), acc); }
;                 const u64_t yb = pack4(acc), td = *(const LAS u64_t*)(TDB + (16 * a + r) * 16 + 4 * g);
;                 const v4u b2 = (v4u){(unsigned)yb, (unsigned)(yb >> 32), 0u, 0u}, a2 = (v4u){(unsigned)td, (unsigned)(td >> 32), 0u, 0u};
;                 const f32x4 xa = MFMA16(__builtin_bit_cast(bf16x8, a2), __builtin_bit_cast(bf16x8, b2), ((f32x4){0.f, 0.f, 0.f, 0.f}));
;                 *(LAS u64_t*)(xc + 16 * a + 4 * g) = pack4(xa); }
;             asm volatile("s_waitcnt lgkmcnt(0)" ::: "memory");
;         }
;         LDS_BAR();
;     }
.LBB0_424:
	s_cmp_lt_i32 s66, 4
	s_cselect_b32 s4, s84, 0xd000
	s_lshl_b32 s6, s66, 5
	s_and_b32 s6, s6, 0x60
	v_or_b32_e32 v64, s6, v94
	s_add_i32 s4, s4, 0
	v_lshlrev_b32_e32 v73, 1, v101
	v_mul_u32_u24_e32 v64, 0x90, v64
	v_add3_u32 v88, s4, v64, v73
	v_add_u32_e32 v78, s82, v73
	s_waitcnt lgkmcnt(0)
	s_barrier
	ds_read_b64 v[66:67], v88
	ds_read_b64 v[74:75], v88 offset:2304
	v_add_u32_e32 v77, v78, v95
	ds_read_b64 v[64:65], v77
	v_lshlrev_b32_e32 v76, 3, v102
	s_waitcnt lgkmcnt(2)
	v_lshlrev_b32_e32 v68, 16, v66
	v_and_b32_e32 v69, 0xffff0000, v66
	v_lshlrev_b32_e32 v70, 16, v67
	v_and_b32_e32 v71, 0xffff0000, v67
	v_mov_b32_e32 v66, v63
	v_mov_b32_e32 v67, v63
	v_cvt_pk_bf16_f32 v68, v68, v69
	v_cvt_pk_bf16_f32 v69, v70, v71
	v_mov_b32_e32 v70, v63
	v_mov_b32_e32 v71, v63
	v_lshlrev_b32_e32 v72, 1, v76
	v_cmp_lt_u32_e32 vcc, 31, v98
	s_waitcnt lgkmcnt(0)
	v_mfma_f32_16x16x32_bf16 v[64:67], v[64:67], v[68:71], 0
	v_lshlrev_b32_e32 v68, 16, v74
	v_and_b32_e32 v69, 0xffff0000, v74
	v_lshlrev_b32_e32 v70, 16, v75
	v_and_b32_e32 v71, 0xffff0000, v75
	v_cvt_pk_bf16_f32 v68, v68, v69
	s_nop 2
	v_cvt_pk_bf16_f32 v64, v64, v65
	v_cvt_pk_bf16_f32 v65, v66, v67
	ds_write_b64 v88, v[64:65]
	ds_read_b64 v[64:65], v77
	v_mov_b32_e32 v66, v63
	v_mov_b32_e32 v67, v63
	v_cvt_pk_bf16_f32 v69, v70, v71
	v_mov_b32_e32 v70, v63
	v_mov_b32_e32 v71, v63
	v_add_u32_e32 v90, v88, v76
	v_lshl_add_u32 v91, v94, 5, v78
	s_waitcnt lgkmcnt(0)
	v_mfma_f32_16x16x32_bf16 v[64:67], v[64:67], v[68:71], 0
	v_mov_b32_e32 v80, v63
	v_mov_b32_e32 v81, v63
	s_mul_i32 s4, s66, 0x900
	s_add_i32 s6, s68, s4
	s_nop 3
	v_cvt_pk_bf16_f32 v64, v64, v65
	v_cvt_pk_bf16_f32 v65, v66, v67
	ds_write_b64 v88, v[64:65] offset:2304
	v_add_u32_e32 v64, s80, v72
	s_waitcnt lgkmcnt(0)
	v_mad_u32_u24 v89, v94, s85, v64
	ds_read_b64 v[70:71], v88 offset:32
	ds_read_b128 v[64:67], v89 offset:2304
	ds_read_b64 v[82:83], v88 offset:2336
	ds_read_b128 v[74:77], v90
	ds_read_b64 v[78:79], v91 offset:512
	s_mul_i32 s9, s33, 0x1200
	s_waitcnt lgkmcnt(3)
	v_cndmask_b32_e64 v67, v67, 0, vcc
	v_cndmask_b32_e64 v66, v66, 0, vcc
	v_cndmask_b32_e64 v65, v65, 0, vcc
	v_cndmask_b32_e64 v64, v64, 0, vcc
	v_lshlrev_b32_e32 v68, 16, v70
	v_and_b32_e32 v69, 0xffff0000, v70
	v_lshlrev_b32_e32 v70, 16, v71
	v_and_b32_e32 v71, 0xffff0000, v71
	s_waitcnt lgkmcnt(1)
	s_nop 0
	v_mfma_f32_16x16x32_bf16 v[64:67], v[64:67], v[74:77], v[68:71]
	s_nop 2
	v_lshlrev_b32_e32 v68, 16, v82
	v_and_b32_e32 v69, 0xffff0000, v82
	s_nop 2
	v_cvt_pk_bf16_f32 v64, v64, v65
	v_cvt_pk_bf16_f32 v65, v66, v67
	v_mov_b32_e32 v66, v63
	v_mov_b32_e32 v67, v63
	v_lshlrev_b32_e32 v70, 16, v83
	v_and_b32_e32 v71, 0xffff0000, v83
	s_waitcnt lgkmcnt(0)
	v_mfma_f32_16x16x32_bf16 v[64:67], v[78:81], v[64:67], 0
	s_nop 7
	v_cvt_pk_bf16_f32 v64, v64, v65
	v_cvt_pk_bf16_f32 v65, v66, v67
	ds_write_b64 v88, v[64:65] offset:32
	ds_read_b128 v[64:67], v89 offset:2304
	ds_read_b128 v[74:77], v90 offset:2304
	ds_read_b64 v[78:79], v91 offset:512
	s_waitcnt lgkmcnt(2)
	v_cndmask_b32_e64 v67, v67, 0, vcc
	v_cndmask_b32_e64 v66, v66, 0, vcc
	v_cndmask_b32_e64 v65, v65, 0, vcc
	v_cndmask_b32_e64 v64, v64, 0, vcc
	s_waitcnt lgkmcnt(1)
	s_nop 0
	v_mfma_f32_16x16x32_bf16 v[64:67], v[64:67], v[74:77], v[68:71]
	s_nop 7
	v_cvt_pk_bf16_f32 v64, v64, v65
	v_cvt_pk_bf16_f32 v65, v66, v67
	v_mov_b32_e32 v66, v63
	v_mov_b32_e32 v67, v63
	s_waitcnt lgkmcnt(0)
	s_nop 0
	v_mfma_f32_16x16x32_bf16 v[64:67], v[78:81], v[64:67], 0
	s_nop 7
	v_cvt_pk_bf16_f32 v64, v64, v65
	v_cvt_pk_bf16_f32 v65, v66, v67
	ds_write_b64 v88, v[64:65] offset:2336
	s_waitcnt lgkmcnt(0)
	ds_read_b64 v[70:71], v88 offset:64
	ds_read_b128 v[64:67], v89 offset:4608
	ds_read_b64 v[82:83], v88 offset:2368
	ds_read_b128 v[74:77], v90
	ds_read_b64 v[78:79], v91 offset:1024
	s_waitcnt lgkmcnt(4)
	v_lshlrev_b32_e32 v68, 16, v70
	v_and_b32_e32 v69, 0xffff0000, v70
	v_lshlrev_b32_e32 v70, 16, v71
	v_and_b32_e32 v71, 0xffff0000, v71
	s_waitcnt lgkmcnt(1)
	s_nop 0
	v_mfma_f32_16x16x32_bf16 v[64:67], v[64:67], v[74:77], v[68:71]
	s_nop 2
	v_lshlrev_b32_e32 v68, 16, v82
	v_and_b32_e32 v69, 0xffff0000, v82
	s_nop 2
	v_cvt_pk_bf16_f32 v64, v64, v65
	v_cvt_pk_bf16_f32 v65, v66, v67
	v_mov_b32_e32 v66, v63
	v_mov_b32_e32 v67, v63
	v_lshlrev_b32_e32 v70, 16, v83
	v_and_b32_e32 v71, 0xffff0000, v83
	s_waitcnt lgkmcnt(0)
	v_mfma_f32_16x16x32_bf16 v[64:67], v[78:81], v[64:67], 0
	s_nop 7
	v_cvt_pk_bf16_f32 v64, v64, v65
	v_cvt_pk_bf16_f32 v65, v66, v67
	ds_write_b64 v88, v[64:65] offset:64
	ds_read_b128 v[64:67], v89 offset:4608
	ds_read_b128 v[74:77], v90 offset:2304
	ds_read_b64 v[78:79], v91 offset:1024
	s_waitcnt lgkmcnt(1)
	v_mfma_f32_16x16x32_bf16 v[64:67], v[64:67], v[74:77], v[68:71]
	s_nop 7
	v_cvt_pk_bf16_f32 v64, v64, v65
	v_cvt_pk_bf16_f32 v65, v66, v67
	v_mov_b32_e32 v66, v63
	v_mov_b32_e32 v67, v63
	s_waitcnt lgkmcnt(0)
	s_nop 0
	v_mfma_f32_16x16x32_bf16 v[64:67], v[78:81], v[64:67], 0
	s_nop 7
	v_cvt_pk_bf16_f32 v64, v64, v65
	v_cvt_pk_bf16_f32 v65, v66, v67
	ds_write_b64 v88, v[64:65] offset:2368
	s_waitcnt lgkmcnt(0)
	ds_read_b64 v[70:71], v88 offset:96
	ds_read_b128 v[64:67], v89 offset:6912
	ds_read_b64 v[86:87], v88 offset:2400
	ds_read_b128 v[74:77], v90
	ds_read_b128 v[78:81], v89 offset:6976
	ds_read_b128 v[82:85], v90 offset:64
	s_waitcnt lgkmcnt(5)
	v_lshlrev_b32_e32 v68, 16, v70
	v_and_b32_e32 v69, 0xffff0000, v70
	v_lshlrev_b32_e32 v70, 16, v71
	v_and_b32_e32 v71, 0xffff0000, v71
	s_waitcnt lgkmcnt(2)
	s_nop 0
	v_mfma_f32_16x16x32_bf16 v[64:67], v[64:67], v[74:77], v[68:71]
	ds_read_b64 v[74:75], v91 offset:1536
	v_mov_b32_e32 v76, v63
	v_mov_b32_e32 v77, v63
	s_waitcnt lgkmcnt(2)
; #define GAS __attribute__((address_space(1)))
; #define LAS __attribute__((address_space(3)))
; __device__ __forceinline__ unsigned long long rt() { return __builtin_amdgcn_s_memrealtime(); }
; #define MFMA16(a, b, c) __builtin_amdgcn_mfma_f32_16x16x32_bf16((a), (b), (c), 0, 0, 0)
;     ...
;                 if (a >= 1) { bf16x8 la = *(const LAS bf16x8*)(NLB + (16 * a + r) * 72 + 8 * g); if (a == 1 && g >= 2) la = (bf16x8){0, 0, 0, 0, 0, 0, 0, 0};
;                     acc = MFMA16(la, *(const LAS bf16x8*)(xc + 8 * g), acc); }
;                 if (a == 3) { bf16x8 la = *(const LAS bf16x8*)(NLB + (48 + r) * 72 + 32 + 8 * g); if (g >= 2) la = (bf16x8){0, 0, 0, 0, 0, 0, 0, 0};
;                     acc = MFMA16(la, *(const LAS bf16x8*)(xc + 32 + 8 * g), acc); }
;                 const u64_t yb = pack4(acc), td = *(const LAS u64_t*)(TDB + (16 * a + r) * 16 + 4 * g);
;                 const v4u b2 = (v4u){(unsigned)yb, (unsigned)(yb >> 32), 0u, 0u}, a2 = (v4u){(unsigned)td, (unsigned)(td >> 32), 0u, 0u};
;                 const f32x4 xa = MFMA16(__builtin_bit_cast(bf16x8, a2), __builtin_bit_cast(bf16x8, b2), ((f32x4){0.f, 0.f, 0.f, 0.f}));
;                 *(LAS u64_t*)(xc + 16 * a + 4 * g) = pack4(xa); }
;             asm volatile("s_waitcnt lgkmcnt(0)" ::: "memory");
;         }
;         LDS_BAR();
;     }
;     if (PROBE_STG == 4) { __syncthreads(); const unsigned long long t1_ = rt(); while (rt() - t1_ < t1_ - stg_t0) __builtin_amdgcn_s_sleep(4); __syncthreads(); }
;     if (PROBE_STG == 5) stg_t0 = rt();
;     const LAS bf16_t* UT = VBT; const LAS bf16_t* WT = KBT;
;     if (PROBE_STG == 5) { __syncthreads(); const unsigned long long t1_ = rt(); while (rt() - t1_ < t1_ - stg_t0) __builtin_amdgcn_s_sleep(4); __syncthreads(); }
;     if (PROBE_STG == 6) stg_t0 = rt();
; #pragma unroll
;     for (int kb = 0; kb < 4; ++kb) { f32x4 t0 = (f32x4){0.f, 0.f, 0.f, 0.f}, t1 = t0;
;         t0 = mma_nt<64>(WT + (2 * kb) * 16 * 72, 72, KHT + wave * 16 * 72, 72, t0, r, g);
;         t1 = mma_nt<64>(WT + (2 * kb + 1) * 16 * 72, 72, KHT + wave * 16 * 72, 72, t1, r, g);
;         const u64_t lo = pack4(-t0), hi = pack4(-t1);
;         if (ST) *(GAS v4u*)(region + 8192 + (size_t)((wave * 4 + kb) * 64 + lane) * 8) = (v4u){(unsigned)lo, (unsigned)(lo >> 32), (unsigned)hi, (unsigned)(hi >> 32)}; asm volatile("" ::: "memory"); }
	v_cndmask_b32_e64 v71, v81, 0, vcc
	v_cndmask_b32_e64 v70, v80, 0, vcc
	v_cndmask_b32_e64 v69, v79, 0, vcc
	v_cndmask_b32_e64 v68, v78, 0, vcc
	s_waitcnt lgkmcnt(1)
	s_nop 0
	v_mfma_f32_16x16x32_bf16 v[64:67], v[68:71], v[82:85], v[64:67]
	v_lshlrev_b32_e32 v68, 16, v86
	v_and_b32_e32 v69, 0xffff0000, v86
	v_lshlrev_b32_e32 v70, 16, v87
	s_nop 4
	v_cvt_pk_bf16_f32 v64, v64, v65
	v_cvt_pk_bf16_f32 v65, v66, v67
	v_mov_b32_e32 v66, v63
	v_mov_b32_e32 v67, v63
	v_and_b32_e32 v71, 0xffff0000, v87
	s_waitcnt lgkmcnt(0)
	v_mfma_f32_16x16x32_bf16 v[64:67], v[74:77], v[64:67], 0
	s_nop 7
	v_cvt_pk_bf16_f32 v64, v64, v65
	v_cvt_pk_bf16_f32 v65, v66, v67
	ds_write_b64 v88, v[64:65] offset:96
	ds_read_b128 v[64:67], v89 offset:6912
	ds_read_b128 v[74:77], v90 offset:2304
	ds_read_b128 v[78:81], v89 offset:6976
	ds_read_b128 v[82:85], v90 offset:2368
	s_waitcnt lgkmcnt(2)
	v_mfma_f32_16x16x32_bf16 v[64:67], v[64:67], v[74:77], v[68:71]
	s_waitcnt lgkmcnt(1)
	s_nop 1
	v_cndmask_b32_e64 v71, v81, 0, vcc
	v_cndmask_b32_e64 v70, v80, 0, vcc
	v_cndmask_b32_e64 v69, v79, 0, vcc
	v_cndmask_b32_e64 v68, v78, 0, vcc
	ds_read_b64 v[76:77], v91 offset:1536
	v_mov_b32_e32 v78, v63
	s_waitcnt lgkmcnt(1)
	v_mfma_f32_16x16x32_bf16 v[64:67], v[68:71], v[82:85], v[64:67]
	v_mov_b32_e32 v79, v63
	v_mul_u32_u24_e32 v74, 0x90, v94
	v_add3_u32 v75, 0, v74, v72
	s_nop 4
	v_cvt_pk_bf16_f32 v64, v64, v65
	v_cvt_pk_bf16_f32 v65, v66, v67
	v_mov_b32_e32 v66, v63
	v_mov_b32_e32 v67, v63
	v_add3_u32 v92, s6, v74, v72
	s_add_u32 s6, s60, s14
	s_waitcnt lgkmcnt(0)
	v_mfma_f32_16x16x32_bf16 v[64:67], v[76:79], v[64:67], 0
	s_addc_u32 s7, s61, s15
	s_add_i32 s9, s68, s9
	v_add3_u32 v96, s9, v74, v72
	s_lshl_b32 s8, s66, 2
	s_and_b32 s8, s8, 4
	s_nop 2
	v_cvt_pk_bf16_f32 v64, v64, v65
	v_cvt_pk_bf16_f32 v65, v66, v67
	ds_write_b64 v88, v[64:65] offset:2400
	s_waitcnt lgkmcnt(0)
	s_waitcnt lgkmcnt(0)
	s_barrier
	ds_read_b128 v[64:67], v75 offset:53248
	ds_read_b128 v[68:71], v75 offset:53312
	ds_read_b128 v[76:79], v92
	ds_read_b128 v[80:83], v92 offset:64
	ds_read_b128 v[84:87], v75 offset:55552
	ds_read_b128 v[88:91], v75 offset:55616
	s_waitcnt lgkmcnt(3)
	v_mfma_f32_16x16x32_bf16 v[64:67], v[64:67], v[76:79], 0
	s_mul_i32 s10, s8, 0x900
	s_waitcnt lgkmcnt(1)
	v_mfma_f32_16x16x32_bf16 v[76:79], v[84:87], v[76:79], 0
	v_mfma_f32_16x16x32_bf16 v[66:69], v[68:71], v[80:83], v[64:67]
	s_waitcnt lgkmcnt(0)
	v_mfma_f32_16x16x32_bf16 v[76:79], v[88:91], v[80:83], v[76:79]
	s_nop 1
	v_lshl_or_b32 v64, s66, 8, v98
	s_nop 2
	v_xor_b32_e32 v65, 0x80000000, v69
	v_xor_b32_e32 v68, 0x80000000, v68
	v_xor_b32_e32 v67, 0x80000000, v67
	v_xor_b32_e32 v66, 0x80000000, v66
	v_cvt_pk_bf16_f32 v66, v66, v67
	v_cvt_pk_bf16_f32 v67, v68, v65
	v_xor_b32_e32 v65, 0x80000000, v79
	v_xor_b32_e32 v69, 0x80000000, v78
	v_xor_b32_e32 v68, 0x80000000, v77
	v_xor_b32_e32 v70, 0x80000000, v76
	v_cvt_pk_bf16_f32 v69, v69, v65
	v_ashrrev_i32_e32 v65, 31, v64
	v_cvt_pk_bf16_f32 v68, v70, v68
	v_lshl_add_u64 v[70:71], v[64:65], 4, s[6:7]
	v_add_co_u32_e32 v70, vcc, s86, v70
	s_nop 1
	v_addc_co_u32_e32 v71, vcc, 0, v71, vcc
	global_store_dwordx4 v[70:71], v[66:69], off sc1
	ds_read_b128 v[66:69], v75 offset:57856
	ds_read_b128 v[76:79], v75 offset:57920
	ds_read_b128 v[80:83], v92
	ds_read_b128 v[84:87], v92 offset:64
	s_waitcnt lgkmcnt(1)
	v_mfma_f32_16x16x32_bf16 v[66:69], v[66:69], v[80:83], 0
	ds_read_b128 v[88:91], v75 offset:60160
	s_waitcnt lgkmcnt(1)
	v_mfma_f32_16x16x32_bf16 v[66:69], v[76:79], v[84:87], v[66:69]
	ds_read_b128 v[76:79], v75 offset:60224
	s_waitcnt lgkmcnt(1)
	v_mfma_f32_16x16x32_bf16 v[80:83], v[88:91], v[80:83], 0
	s_nop 4
	v_xor_b32_e32 v69, 0x80000000, v69
	s_waitcnt lgkmcnt(0)
	v_mfma_f32_16x16x32_bf16 v[76:79], v[76:79], v[84:87], v[80:83]
	v_xor_b32_e32 v70, 0x80000000, v68
	v_xor_b32_e32 v67, 0x80000000, v67
	v_xor_b32_e32 v66, 0x80000000, v66
	v_cvt_pk_bf16_f32 v68, v66, v67
	v_cvt_pk_bf16_f32 v69, v70, v69
	s_nop 2
	v_xor_b32_e32 v66, 0x80000000, v79
	v_xor_b32_e32 v67, 0x80000000, v78
	v_xor_b32_e32 v70, 0x80000000, v77
	v_xor_b32_e32 v71, 0x80000000, v76
	v_cvt_pk_bf16_f32 v70, v71, v70
	v_cvt_pk_bf16_f32 v71, v67, v66
	v_or_b32_e32 v66, 64, v64
	v_ashrrev_i32_e32 v67, 31, v66
	v_lshl_add_u64 v[76:77], v[66:67], 4, s[6:7]
	v_add_co_u32_e32 v76, vcc, s86, v76
	s_nop 1
	v_addc_co_u32_e32 v77, vcc, 0, v77, vcc
	global_store_dwordx4 v[76:77], v[68:71], off sc1
	ds_read_b128 v[68:71], v75 offset:62464
	ds_read_b128 v[76:79], v75 offset:62528
	ds_read_b128 v[80:83], v92
	ds_read_b128 v[84:87], v92 offset:64
	s_waitcnt lgkmcnt(1)
	v_mfma_f32_16x16x32_bf16 v[68:71], v[68:71], v[80:83], 0
	ds_read_b128 v[88:91], v75 offset:64768
	s_waitcnt lgkmcnt(1)
	v_mfma_f32_16x16x32_bf16 v[68:71], v[76:79], v[84:87], v[68:71]
	ds_read_b128 v[76:79], v75 offset:64832
	s_waitcnt lgkmcnt(1)
	v_mfma_f32_16x16x32_bf16 v[80:83], v[88:91], v[80:83], 0
	s_nop 4
	v_xor_b32_e32 v69, 0x80000000, v69
	s_waitcnt lgkmcnt(0)
	v_mfma_f32_16x16x32_bf16 v[76:79], v[76:79], v[84:87], v[80:83]
	v_xor_b32_e32 v68, 0x80000000, v68
	v_xor_b32_e32 v71, 0x80000000, v71
	v_xor_b32_e32 v70, 0x80000000, v70
	v_cvt_pk_bf16_f32 v80, v68, v69
	v_cvt_pk_bf16_f32 v81, v70, v71
	s_nop 2
	v_xor_b32_e32 v68, 0x80000000, v79
	v_xor_b32_e32 v69, 0x80000000, v78
	v_cvt_pk_bf16_f32 v83, v69, v68
	v_or_b32_e32 v68, 0x80, v64
	v_xor_b32_e32 v70, 0x80000000, v77
	v_xor_b32_e32 v71, 0x80000000, v76
	v_ashrrev_i32_e32 v69, 31, v68
	v_cvt_pk_bf16_f32 v82, v71, v70
	v_lshl_add_u64 v[70:71], v[68:69], 4, s[6:7]
	v_add_co_u32_e32 v70, vcc, s86, v70
	s_nop 1
	v_addc_co_u32_e32 v71, vcc, 0, v71, vcc
	global_store_dwordx4 v[70:71], v[80:83], off sc1
	v_add3_u32 v70, s87, v74, v72
	ds_read_b128 v[76:79], v70
	ds_read_b128 v[80:83], v92
	ds_read_b128 v[84:87], v70 offset:64
	ds_read_b128 v[88:91], v92 offset:64
	v_add3_u32 v70, s88, v74, v72
	s_waitcnt lgkmcnt(2)
; #define GAS __attribute__((address_space(1)))
; #define LAS __attribute__((address_space(3)))
; __device__ __forceinline__ u64_t pack4(const f32x4 v) { return (u64_t)pk2(v[0], v[1]) | ((u64_t)pk2(v[2], v[3]) << 32); }
;     ...
;     for (int kb = 0; kb < 4; ++kb) { f32x4 t0 = (f32x4){0.f, 0.f, 0.f, 0.f}, t1 = t0;
;         t0 = mma_nt<64>(WT + (2 * kb) * 16 * 72, 72, KHT + wave * 16 * 72, 72, t0, r, g);
;         t1 = mma_nt<64>(WT + (2 * kb + 1) * 16 * 72, 72, KHT + wave * 16 * 72, 72, t1, r, g);
;         const u64_t lo = pack4(-t0), hi = pack4(-t1);
;         if (ST) *(GAS v4u*)(region + 8192 + (size_t)((wave * 4 + kb) * 64 + lane) * 8) = (v4u){(unsigned)lo, (unsigned)(lo >> 32), (unsigned)hi, (unsigned)(hi >> 32)}; asm volatile("" ::: "memory"); }
; #pragma unroll
;     for (int e = 0; e < 4; ++e) { const int vj = 4 * (wave & 1) + e, kb = wave >> 1; f32x4 a0 = (f32x4){0.f, 0.f, 0.f, 0.f}, a1 = a0;
;         a0 = mma_nt<64>(KHT + (2 * kb) * 16 * 72, 72, UT + vj * 16 * 72, 72, a0, r, g);
;         a1 = mma_nt<64>(KHT + (2 * kb + 1) * 16 * 72, 72, UT + vj * 16 * 72, 72, a1, r, g);
;         const u64_t lo = pack4(a0), hi = pack4(a1);
;         if (ST) *(GAS v4u*)(BNB + (size_t)unit * 16384 + (size_t)((vj * 4 + kb) * 64 + lane) * 8) = (v4u){(unsigned)lo, (unsigned)(lo >> 32), (unsigned)hi, (unsigned)(hi >> 32)}; asm volatile("" ::: "memory"); }
; #pragma unroll
;     for (int e = 0; e < 2; ++e) { const int p = wave * 2 + e, mt = p >> 2, kb = p & 3; f32x4 t0 = (f32x4){0.f, 0.f, 0.f, 0.f}, t1 = t0;
;         t0 = mma_nt<64>(WT + (2 * kb) * 16 * 72, 72, QKL + mt * 16 * 72, 72, t0, r, g);
;         t1 = mma_nt<64>(WT + (2 * kb + 1) * 16 * 72, 72, QKL + mt * 16 * 72, 72, t1, r, g);
;         const int t = 16 * mt + r; const float eg = __expf(GC[t]) * RQ[t];
;         const f32x4 q0 = unpack4(*(const LAS u64_t*)(QN + t * 136 + 32 * kb + 4 * g)), q1 = unpack4(*(const LAS u64_t*)(QN + t * 136 + 32 * kb + 16 + 4 * g));
	v_mfma_f32_16x16x32_bf16 v[76:79], v[76:79], v[80:83], 0
	ds_read_b128 v[92:95], v70
	s_waitcnt lgkmcnt(1)
	v_mfma_f32_16x16x32_bf16 v[76:79], v[84:87], v[88:91], v[76:79]
	ds_read_b128 v[84:87], v70 offset:64
	s_waitcnt lgkmcnt(1)
	v_mfma_f32_16x16x32_bf16 v[80:83], v[92:95], v[80:83], 0
	s_nop 4
	v_xor_b32_e32 v70, 0x80000000, v79
	s_waitcnt lgkmcnt(0)
	v_mfma_f32_16x16x32_bf16 v[80:83], v[84:87], v[88:91], v[80:83]
	v_xor_b32_e32 v71, 0x80000000, v78
	v_xor_b32_e32 v77, 0x80000000, v77
	v_xor_b32_e32 v76, 0x80000000, v76
	v_cvt_pk_bf16_f32 v76, v76, v77
	v_cvt_pk_bf16_f32 v77, v71, v70
	s_nop 2
	v_xor_b32_e32 v70, 0x80000000, v83
	v_xor_b32_e32 v71, 0x80000000, v82
	v_xor_b32_e32 v78, 0x80000000, v81
	v_xor_b32_e32 v79, 0x80000000, v80
	v_cvt_pk_bf16_f32 v78, v79, v78
	v_cvt_pk_bf16_f32 v79, v71, v70
	v_or_b32_e32 v70, 0xc0, v64
	v_ashrrev_i32_e32 v71, 31, v70
	v_lshl_add_u64 v[80:81], v[70:71], 4, s[6:7]
	v_add_co_u32_e32 v80, vcc, s86, v80
	v_add_u32_e32 v88, s10, v75
	s_nop 0
	v_addc_co_u32_e32 v81, vcc, 0, v81, vcc
	global_store_dwordx4 v[80:81], v[76:79], off sc1
	ds_read_b128 v[76:79], v96
	ds_read_b128 v[80:83], v96 offset:64
	ds_read_b128 v[84:87], v88 offset:34816
	ds_read_b128 v[88:91], v88 offset:34880
	s_waitcnt lgkmcnt(1)
	v_mfma_f32_16x16x32_bf16 v[76:79], v[76:79], v[84:87], 0
	ds_read_b128 v[92:95], v96 offset:2304
	s_waitcnt lgkmcnt(1)
	v_mfma_f32_16x16x32_bf16 v[76:79], v[80:83], v[88:91], v[76:79]
	ds_read_b128 v[80:83], v96 offset:2368
	s_waitcnt lgkmcnt(1)
	v_mfma_f32_16x16x32_bf16 v[84:87], v[92:95], v[84:87], 0
	v_lshl_or_b32 v92, s33, 6, v98
	v_lshl_add_u32 v102, s8, 8, v92
	s_add_u32 s8, s60, s3
	s_waitcnt lgkmcnt(0)
	v_mfma_f32_16x16x32_bf16 v[80:83], v[80:83], v[88:91], v[84:87]
	v_ashrrev_i32_e32 v103, 31, v102
	s_addc_u32 s9, s61, s73
	v_cvt_pk_bf16_f32 v76, v76, v77
	v_cvt_pk_bf16_f32 v77, v78, v79
	s_add_i32 s11, s10, 0x900
	s_nop 2
	v_cvt_pk_bf16_f32 v78, v80, v81
	v_cvt_pk_bf16_f32 v79, v82, v83
	v_lshl_add_u64 v[80:81], v[102:103], 4, s[8:9]
	global_store_dwordx4 v[80:81], v[76:79], off sc1
	ds_read_b128 v[76:79], v96
	v_add_u32_e32 v88, s11, v75
	ds_read_b128 v[80:83], v96 offset:64
	ds_read_b128 v[84:87], v88 offset:34816
	ds_read_b128 v[88:91], v88 offset:34880
	s_waitcnt lgkmcnt(1)
	v_mfma_f32_16x16x32_bf16 v[76:79], v[76:79], v[84:87], 0
	ds_read_b128 v[92:95], v96 offset:2304
	s_add_i32 s11, s10, 0x1200
	s_addk_i32 s10, 0x1b00
	s_waitcnt lgkmcnt(1)
	v_mfma_f32_16x16x32_bf16 v[76:79], v[80:83], v[88:91], v[76:79]
	ds_read_b128 v[80:83], v96 offset:2368
	v_lshl_or_b32 v98, s33, 8, v98
	s_add_i32 s4, s4, 0
	s_waitcnt lgkmcnt(1)
	v_mfma_f32_16x16x32_bf16 v[84:87], v[92:95], v[84:87], 0
	s_nop 2
	v_cvt_pk_bf16_f32 v76, v76, v77
	s_waitcnt lgkmcnt(0)
	v_mfma_f32_16x16x32_bf16 v[80:83], v[80:83], v[88:91], v[84:87]
	v_cvt_pk_bf16_f32 v77, v78, v79
	v_add_u32_e32 v88, s11, v75
	v_add_u32_e32 v75, s10, v75
	s_nop 4
	v_cvt_pk_bf16_f32 v78, v80, v81
	v_add_u32_e32 v80, 0x100, v102
	v_ashrrev_i32_e32 v81, 31, v80
	v_cvt_pk_bf16_f32 v79, v82, v83
	v_lshl_add_u64 v[80:81], v[80:81], 4, s[8:9]
	global_store_dwordx4 v[80:81], v[76:79], off sc1
	ds_read_b128 v[76:79], v96
	ds_read_b128 v[80:83], v96 offset:64
	ds_read_b128 v[84:87], v88 offset:34816
	ds_read_b128 v[88:91], v88 offset:34880
	s_waitcnt lgkmcnt(1)
	v_mfma_f32_16x16x32_bf16 v[76:79], v[76:79], v[84:87], 0
	ds_read_b128 v[92:95], v96 offset:2304
	s_waitcnt lgkmcnt(1)
	v_mfma_f32_16x16x32_bf16 v[76:79], v[80:83], v[88:91], v[76:79]
	ds_read_b128 v[80:83], v96 offset:2368
	s_waitcnt lgkmcnt(1)
	v_mfma_f32_16x16x32_bf16 v[84:87], v[92:95], v[84:87], 0
	s_nop 4
	v_cvt_pk_bf16_f32 v76, v76, v77
	s_waitcnt lgkmcnt(0)
	v_mfma_f32_16x16x32_bf16 v[80:83], v[80:83], v[88:91], v[84:87]
	v_cvt_pk_bf16_f32 v77, v78, v79
	s_nop 6
	v_cvt_pk_bf16_f32 v78, v80, v81
	v_add_u32_e32 v80, 0x200, v102
	v_ashrrev_i32_e32 v81, 31, v80
	v_cvt_pk_bf16_f32 v79, v82, v83
	v_lshl_add_u64 v[80:81], v[80:81], 4, s[8:9]
	global_store_dwordx4 v[80:81], v[76:79], off sc1
	ds_read_b128 v[76:79], v96
	ds_read_b128 v[80:83], v96 offset:64
	ds_read_b128 v[84:87], v75 offset:34816
	ds_read_b128 v[88:91], v75 offset:34880
	s_waitcnt lgkmcnt(1)
	v_mfma_f32_16x16x32_bf16 v[76:79], v[76:79], v[84:87], 0
	ds_read_b128 v[92:95], v96 offset:2304
	s_waitcnt lgkmcnt(1)
	v_mfma_f32_16x16x32_bf16 v[76:79], v[80:83], v[88:91], v[76:79]
	ds_read_b128 v[80:83], v96 offset:2368
	s_waitcnt lgkmcnt(1)
	v_mfma_f32_16x16x32_bf16 v[84:87], v[92:95], v[84:87], 0
	s_nop 4
	v_cvt_pk_bf16_f32 v76, v76, v77
	s_waitcnt lgkmcnt(0)
	v_mfma_f32_16x16x32_bf16 v[80:83], v[80:83], v[88:91], v[84:87]
	v_cvt_pk_bf16_f32 v77, v78, v79
	s_nop 6
	v_cvt_pk_bf16_f32 v78, v80, v81
	v_add_u32_e32 v80, 0x300, v102
	v_ashrrev_i32_e32 v81, 31, v80
	v_cvt_pk_bf16_f32 v79, v82, v83
	v_lshl_add_u64 v[80:81], v[80:81], 4, s[8:9]
	s_mul_i32 s9, s42, 0x1200
	global_store_dwordx4 v[80:81], v[76:79], off sc1
	s_add_i32 s9, s9, 0
	v_add3_u32 v75, s9, v74, v72
	ds_read_b128 v[76:79], v75 offset:53248
	s_mul_i32 s8, s33, 0x900
	s_add_i32 s8, s81, s8
	v_add3_u32 v96, s8, v74, v72
	ds_read_b128 v[80:83], v96
	ds_read_b128 v[84:87], v75 offset:53312
	ds_read_b128 v[88:91], v96 offset:64
	ds_read_b128 v[92:95], v75 offset:55552
	ds_read_b32 v101, v99
	s_waitcnt lgkmcnt(4)
	v_mfma_f32_16x16x32_bf16 v[76:79], v[76:79], v[80:83], 0
	v_lshl_add_u32 v102, v100, 2, 0
	v_add_u32_e32 v102, 0x1ec00, v102
	ds_read_b32 v103, v102
	s_waitcnt lgkmcnt(3)
	v_mfma_f32_16x16x32_bf16 v[76:79], v[84:87], v[88:91], v[76:79]
	v_mul_lo_u32 v84, v100, s74
	v_add_u32_e32 v100, 0, v84
	ds_read_b128 v[84:87], v75 offset:55616
	s_lshl_b32 s8, s42, 6
	s_waitcnt lgkmcnt(3)
; #define GAS __attribute__((address_space(1)))
; #define LAS __attribute__((address_space(3)))
; __device__ __forceinline__ unsigned long long rt() { return __builtin_amdgcn_s_memrealtime(); }
; #define LDS_BAR() do { asm volatile("s_waitcnt lgkmcnt(0)" ::: "memory"); __builtin_amdgcn_s_barrier(); asm volatile("" ::: "memory"); } while (0)
; __device__ __forceinline__ u64_t pack4(const f32x4 v) { return (u64_t)pk2(v[0], v[1]) | ((u64_t)pk2(v[2], v[3]) << 32); }
;     ...
;     for (int e = 0; e < 2; ++e) { const int p = wave * 2 + e, mt = p >> 2, kb = p & 3; f32x4 t0 = (f32x4){0.f, 0.f, 0.f, 0.f}, t1 = t0;
;         t0 = mma_nt<64>(WT + (2 * kb) * 16 * 72, 72, QKL + mt * 16 * 72, 72, t0, r, g);
;         t1 = mma_nt<64>(WT + (2 * kb + 1) * 16 * 72, 72, QKL + mt * 16 * 72, 72, t1, r, g);
;         const int t = 16 * mt + r; const float eg = __expf(GC[t]) * RQ[t];
;         const f32x4 q0 = unpack4(*(const LAS u64_t*)(QN + t * 136 + 32 * kb + 4 * g)), q1 = unpack4(*(const LAS u64_t*)(QN + t * 136 + 32 * kb + 16 + 4 * g));
;         const u64_t lo = pack4(q0 * eg - t0), hi = pack4(q1 * eg - t1);
;         if (ST) *(GAS v4u*)(region + (size_t)((mt * 4 + kb) * 64 + lane) * 8) = (v4u){(unsigned)lo, (unsigned)(lo >> 32), (unsigned)hi, (unsigned)(hi >> 32)}; asm volatile("" ::: "memory"); }
; #pragma unroll
;     for (int ti = 0; ti < 4; ++ti) { f32x4 acc = (f32x4){0.f, 0.f, 0.f, 0.f};
;         acc = mma_nt<64>(UT + wave * 16 * 72, 72, QKL + ti * 16 * 72, 72, acc, r, g);
;         if (ST) *(GAS u64_t*)(OLD + (size_t)unit * 8192 + (size_t)((wave * 4 + ti) * 64 + lane) * 4) = pack4(acc); asm volatile("" ::: "memory"); }
;     if (PROBE_STG == 6) { __syncthreads(); const unsigned long long t1_ = rt(); while (rt() - t1_ < t1_ - stg_t0) __builtin_amdgcn_s_sleep(4); __syncthreads(); }
;     LDS_BAR();
	v_mfma_f32_16x16x32_bf16 v[80:83], v[92:95], v[80:83], 0
	v_add3_u32 v92, v100, s8, v73
	v_add_u32_e32 v92, 0x4000, v92
	s_waitcnt lgkmcnt(1)
	v_mul_f32_e32 v75, 0x3fb8aa3b, v103
	ds_read2_b64 v[92:95], v92 offset0:128 offset1:132
	v_exp_f32_e32 v75, v75
	s_waitcnt lgkmcnt(1)
	v_mfma_f32_16x16x32_bf16 v[80:83], v[84:87], v[88:91], v[80:83]
	v_xor_b32_e32 v79, 0x80000000, v79
	v_mul_f32_e32 v84, v101, v75
	s_waitcnt lgkmcnt(0)
	v_lshlrev_b32_e32 v86, 16, v92
	v_and_b32_e32 v87, 0xffff0000, v92
	v_lshlrev_b32_e32 v88, 16, v93
	v_and_b32_e32 v89, 0xffff0000, v93
	v_xor_b32_e32 v78, 0x80000000, v78
	v_pk_fma_f32 v[78:79], v[84:85], v[88:89], v[78:79] op_sel_hi:[0,1,1]
	v_pk_fma_f32 v[76:77], v[84:85], v[86:87], v[76:77] op_sel_hi:[0,1,1] neg_lo:[0,0,1] neg_hi:[0,0,1]
	v_lshlrev_b32_e32 v90, 16, v94
	v_and_b32_e32 v91, 0xffff0000, v94
	v_lshlrev_b32_e32 v92, 16, v95
	v_and_b32_e32 v93, 0xffff0000, v95
	v_cvt_pk_bf16_f32 v76, v76, v77
	v_cvt_pk_bf16_f32 v77, v78, v79
	v_xor_b32_e32 v79, 0x80000000, v83
	v_xor_b32_e32 v78, 0x80000000, v82
	v_pk_fma_f32 v[82:83], v[84:85], v[92:93], v[78:79] op_sel_hi:[0,1,1]
	v_pk_fma_f32 v[78:79], v[84:85], v[90:91], v[80:81] op_sel_hi:[0,1,1] neg_lo:[0,0,1] neg_hi:[0,0,1]
	v_or_b32_e32 v80, s8, v98
	v_ashrrev_i32_e32 v81, 31, v80
	v_lshl_add_u64 v[80:81], v[80:81], 4, s[6:7]
	v_add_co_u32_e32 v80, vcc, s89, v80
	v_cvt_pk_bf16_f32 v78, v78, v79
	v_cvt_pk_bf16_f32 v79, v82, v83
	v_addc_co_u32_e32 v81, vcc, 0, v81, vcc
	global_store_dwordx4 v[80:81], v[76:79], off sc1
	s_addk_i32 s9, 0x1200
	v_add3_u32 v75, s9, v74, v72
	ds_read_b128 v[76:79], v75 offset:53248
	ds_read_b128 v[80:83], v96
	ds_read_b128 v[84:87], v75 offset:53312
	ds_read_b32 v99, v99
	s_waitcnt lgkmcnt(2)
	v_mfma_f32_16x16x32_bf16 v[76:79], v[76:79], v[80:83], 0
	ds_read_b128 v[88:91], v96 offset:64
	ds_read_b32 v96, v102
	s_lshl_b32 s8, s67, 6
	v_add3_u32 v73, v100, s8, v73
	s_waitcnt lgkmcnt(1)
	v_mfma_f32_16x16x32_bf16 v[76:79], v[84:87], v[88:91], v[76:79]
	ds_read_b128 v[84:87], v75 offset:55552
	ds_read_b128 v[92:95], v75 offset:55616
	v_add_u32_e32 v73, 0x4000, v73
	s_waitcnt lgkmcnt(2)
	v_mul_f32_e32 v75, 0x3fb8aa3b, v96
	s_waitcnt lgkmcnt(1)
	v_mfma_f32_16x16x32_bf16 v[80:83], v[84:87], v[80:83], 0
	ds_read2_b64 v[84:87], v73 offset0:128 offset1:132
	v_exp_f32_e32 v75, v75
	v_xor_b32_e32 v79, 0x80000000, v79
	s_waitcnt lgkmcnt(1)
	v_mfma_f32_16x16x32_bf16 v[80:83], v[92:95], v[88:91], v[80:83]
	v_xor_b32_e32 v78, 0x80000000, v78
	v_mul_f32_e32 v88, v99, v75
	s_waitcnt lgkmcnt(0)
	v_lshlrev_b32_e32 v90, 16, v84
	v_and_b32_e32 v91, 0xffff0000, v84
	v_lshlrev_b32_e32 v84, 16, v85
	v_and_b32_e32 v85, 0xffff0000, v85
	v_pk_fma_f32 v[78:79], v[88:89], v[84:85], v[78:79] op_sel_hi:[0,1,1]
	v_pk_fma_f32 v[76:77], v[88:89], v[90:91], v[76:77] op_sel_hi:[0,1,1] neg_lo:[0,0,1] neg_hi:[0,0,1]
	v_lshlrev_b32_e32 v92, 16, v86
	v_and_b32_e32 v93, 0xffff0000, v86
	v_lshlrev_b32_e32 v86, 16, v87
	v_and_b32_e32 v87, 0xffff0000, v87
	v_cvt_pk_bf16_f32 v76, v76, v77
	v_cvt_pk_bf16_f32 v77, v78, v79
	v_xor_b32_e32 v79, 0x80000000, v83
	v_xor_b32_e32 v78, 0x80000000, v82
	v_pk_fma_f32 v[82:83], v[88:89], v[86:87], v[78:79] op_sel_hi:[0,1,1]
	v_pk_fma_f32 v[78:79], v[88:89], v[92:93], v[80:81] op_sel_hi:[0,1,1] neg_lo:[0,0,1] neg_hi:[0,0,1]
	v_or_b32_e32 v80, s8, v98
	v_ashrrev_i32_e32 v81, 31, v80
	v_lshl_add_u64 v[80:81], v[80:81], 4, s[6:7]
	v_add_co_u32_e32 v80, vcc, s89, v80
	v_cvt_pk_bf16_f32 v78, v78, v79
	v_cvt_pk_bf16_f32 v79, v82, v83
	v_addc_co_u32_e32 v81, vcc, 0, v81, vcc
	global_store_dwordx4 v[80:81], v[76:79], off sc1
	v_add3_u32 v88, s4, v74, v72
	ds_read_b128 v[76:79], v88 offset:34816
	v_add3_u32 v89, s81, v74, v72
	ds_read_b128 v[72:75], v88 offset:34880
	ds_read_b128 v[80:83], v89
	ds_read_b128 v[84:87], v89 offset:64
	s_waitcnt lgkmcnt(1)
	v_mfma_f32_16x16x32_bf16 v[76:79], v[76:79], v[80:83], 0
	s_add_u32 s6, s60, s71
	s_addc_u32 s7, s61, s72
	v_lshl_add_u64 v[64:65], v[64:65], 3, s[6:7]
	s_waitcnt lgkmcnt(0)
	v_mfma_f32_16x16x32_bf16 v[72:75], v[72:75], v[84:87], v[76:79]
	v_lshl_add_u64 v[66:67], v[66:67], 3, s[6:7]
	s_add_u32 s69, s69, s22
	s_addc_u32 s70, s70, s23
	s_add_u32 s71, s71, s36
	s_addc_u32 s72, s72, s37
	s_nop 2
	v_cvt_pk_bf16_f32 v72, v72, v73
	v_cvt_pk_bf16_f32 v73, v74, v75
	global_store_dwordx2 v[64:65], v[72:73], off sc1
	ds_read_b128 v[72:75], v88 offset:34816
	ds_read_b128 v[76:79], v88 offset:34880
	ds_read_b128 v[80:83], v89 offset:2304
	ds_read_b128 v[84:87], v89 offset:2368
	s_waitcnt lgkmcnt(1)
	v_mfma_f32_16x16x32_bf16 v[72:75], v[72:75], v[80:83], 0
	s_add_u32 s3, s3, s40
	s_addc_u32 s73, s73, s41
	s_add_u32 s14, s14, s38
	s_waitcnt lgkmcnt(0)
	v_mfma_f32_16x16x32_bf16 v[72:75], v[76:79], v[84:87], v[72:75]
	s_addc_u32 s15, s15, s39
	s_and_b64 vcc, exec, s[48:49]
	s_nop 5
	v_cvt_pk_bf16_f32 v64, v72, v73
	v_cvt_pk_bf16_f32 v65, v74, v75
	global_store_dwordx2 v[66:67], v[64:65], off sc1
	ds_read_b128 v[64:67], v88 offset:34816
	ds_read_b128 v[72:75], v88 offset:34880
	ds_read_b128 v[76:79], v89 offset:4608
	ds_read_b128 v[80:83], v89 offset:4672
	s_waitcnt lgkmcnt(1)
	v_mfma_f32_16x16x32_bf16 v[64:67], v[64:67], v[76:79], 0
	s_waitcnt lgkmcnt(0)
	v_mfma_f32_16x16x32_bf16 v[64:67], v[72:75], v[80:83], v[64:67]
	s_nop 7
	v_cvt_pk_bf16_f32 v64, v64, v65
	v_cvt_pk_bf16_f32 v65, v66, v67
	v_lshl_add_u64 v[66:67], v[68:69], 3, s[6:7]
	global_store_dwordx2 v[66:67], v[64:65], off sc1
	ds_read_b128 v[64:67], v88 offset:34816
	ds_read_b128 v[72:75], v88 offset:34880
	ds_read_b128 v[76:79], v89 offset:6912
	ds_read_b128 v[80:83], v89 offset:6976
	s_waitcnt lgkmcnt(1)
	v_mfma_f32_16x16x32_bf16 v[64:67], v[64:67], v[76:79], 0
	s_waitcnt lgkmcnt(0)
	v_mfma_f32_16x16x32_bf16 v[64:67], v[72:75], v[80:83], v[64:67]
	s_nop 7
	v_cvt_pk_bf16_f32 v64, v64, v65
	v_cvt_pk_bf16_f32 v65, v66, v67
	v_lshl_add_u64 v[66:67], v[70:71], 3, s[6:7]
	global_store_dwordx2 v[66:67], v[64:65], off sc1
	s_waitcnt lgkmcnt(0)
	s_barrier
	s_waitcnt vmcnt(14)
	v_mov_b32_e32 v67, v62
	v_mov_b32_e32 v66, v97
	s_cbranch_vccnz .LBB0_610

;     ...
;     __syncthreads();
;     const float glast = GC[63];
;     if (tid == 0 && ST) decD[(size_t)unit * 128] = __expf(glast);
.LBB0_566:
	s_or_b64 exec, exec, s[6:7]
	v_mov_b32_e32 v64, s76
	s_waitcnt lgkmcnt(0)
	s_barrier
	ds_read_b32 v103, v64
	v_cmp_eq_u32_e32 vcc, 0, v96
	s_and_saveexec_b64 s[6:7], vcc
	s_cbranch_execz .LBB0_568
	s_waitcnt lgkmcnt(0)
	v_mul_f32_e32 v64, 0x3fb8aa3b, v103
	v_exp_f32_e32 v64, v64
	s_add_u32 s8, s60, s69
	s_addc_u32 s9, s61, s70
	global_store_dword v63, v64, s[8:9] sc1

; __device__ __forceinline__ u32x4 pack8(const f32x4 a, const f32x4 b) { u32x4 w; w.x = cvt_pk_bf16(a[0], a[1]); w.y = cvt_pk_bf16(a[2], a[3]); w.z = cvt_pk_bf16(b[0], b[1]); w.w = cvt_pk_bf16(b[2], b[3]); return w; }
;     __device__ __forceinline__ void operator()(const f32x4 (&acc)[2][2][4][2], const Unit& u, int wr, int wc, int fr, int fq) const {
;     ...
;         if (pn >= 16) {
; #pragma unroll
;             for (int ai = 0; ai < 2; ++ai)
; #pragma unroll
;                 for (int m = 0; m < 4; ++m) { const int r = row0 + ai * HALF + m * 16;
;                     f32x4 ra[2], gb[2];
; #pragma unroll
;                     for (int n = 0; n < 2; ++n)
; #pragma unroll
;                         for (int i = 0; i < 4; ++i) { const float ea = __expf(-acc[ai][0][m][n][i]), eb = __expf(-fmaxf(acc[ai][1][m][n][i], -60.f));
;                             gb[n][i] = __builtin_amdgcn_rcpf(1.f + eb); ra[n][i] = (1.f + eb) * __builtin_amdgcn_rcpf(1.f + ea); }
;                     bf16_t* gp = gab + (size_t)r * 2048 + (pn - 16) * 128 + c8;
;                     *(u32x4*)gp = pack8(ra[0], ra[1]); *(u32x4*)(gp + 1024) = pack8(gb[0], gb[1]); }
.LBB0_697:
	s_and_b64 vcc, exec, s[6:7]
	s_cbranch_vccz .LBB0_814
	v_mul_f32_e32 v126, 0xbfb8aa3b, v126
	v_mul_f32_e32 v127, 0xbfb8aa3b, v127
	v_exp_f32_e32 v126, v126
	v_exp_f32_e32 v127, v127
	v_max_f32_e32 v122, v122, v122
	v_max_f32_e32 v123, v123, v123
	v_max_f32_e32 v122, 0xc2700000, v122
	v_max_f32_e32 v123, 0xc2700000, v123
	v_mul_f32_e32 v122, 0xbfb8aa3b, v122
	v_mul_f32_e32 v123, 0xbfb8aa3b, v123
	v_exp_f32_e32 v122, v122
	v_add_f32_e32 v126, 1.0, v126
	v_exp_f32_e32 v123, v123
	v_add_f32_e32 v127, 1.0, v127
	v_rcp_f32_e32 v126, v126
	v_rcp_f32_e32 v127, v127
	v_pk_add_f32 v[122:123], v[122:123], 1.0 op_sel_hi:[1,0]
	v_mul_f32_e32 v118, 0xbfb8aa3b, v118
	v_rcp_f32_e32 v132, v122
	v_rcp_f32_e32 v133, v123
	v_pk_mul_f32 v[122:123], v[126:127], v[122:123]
	v_mul_f32_e32 v126, 0xbfb8aa3b, v128
	v_mul_f32_e32 v127, 0xbfb8aa3b, v129
	v_mul_f32_e32 v119, 0xbfb8aa3b, v119
	v_exp_f32_e32 v126, v126
	v_exp_f32_e32 v127, v127
	v_exp_f32_e32 v118, v118
	v_exp_f32_e32 v119, v119
	v_mul_f32_e32 v120, 0xbfb8aa3b, v120
	v_mul_f32_e32 v121, 0xbfb8aa3b, v121
	v_max_f32_e32 v124, v124, v124
	v_max_f32_e32 v125, v125, v125
	v_max_f32_e32 v114, v114, v114
	v_max_f32_e32 v115, v115, v115
	v_exp_f32_e32 v120, v120
	v_exp_f32_e32 v121, v121
	v_max_f32_e32 v124, 0xc2700000, v124
	v_max_f32_e32 v125, 0xc2700000, v125
	v_max_f32_e32 v114, 0xc2700000, v114
	v_max_f32_e32 v115, 0xc2700000, v115
	v_max_f32_e32 v116, v116, v116
	v_max_f32_e32 v117, v117, v117
	v_mul_f32_e32 v124, 0xbfb8aa3b, v124
	v_mul_f32_e32 v125, 0xbfb8aa3b, v125
	v_mul_f32_e32 v114, 0xbfb8aa3b, v114
	v_mul_f32_e32 v115, 0xbfb8aa3b, v115
	v_max_f32_e32 v116, 0xc2700000, v116
	v_max_f32_e32 v117, 0xc2700000, v117
	v_exp_f32_e32 v124, v124
	v_add_f32_e32 v126, 1.0, v126
	v_exp_f32_e32 v125, v125
	v_add_f32_e32 v127, 1.0, v127
	v_exp_f32_e32 v114, v114
	v_add_f32_e32 v118, 1.0, v118
	v_exp_f32_e32 v115, v115
	v_add_f32_e32 v119, 1.0, v119
	v_mul_f32_e32 v116, 0xbfb8aa3b, v116
	v_mul_f32_e32 v117, 0xbfb8aa3b, v117
	v_rcp_f32_e32 v126, v126
	v_rcp_f32_e32 v127, v127
	v_rcp_f32_e32 v118, v118
	v_rcp_f32_e32 v119, v119
	v_exp_f32_e32 v116, v116
	v_add_f32_e32 v120, 1.0, v120
	v_exp_f32_e32 v117, v117
	v_add_f32_e32 v121, 1.0, v121
	v_mul_f32_e32 v110, 0xbfb8aa3b, v110
	v_mul_f32_e32 v111, 0xbfb8aa3b, v111
	v_rcp_f32_e32 v120, v120
	v_rcp_f32_e32 v121, v121
	v_exp_f32_e32 v110, v110
	v_exp_f32_e32 v111, v111
	v_max_f32_e32 v106, v106, v106
	v_max_f32_e32 v107, v107, v107
	v_or_b32_e32 v130, s77, v1
	v_pk_add_f32 v[124:125], v[124:125], 1.0 op_sel_hi:[1,0]
	v_pk_add_f32 v[114:115], v[114:115], 1.0 op_sel_hi:[1,0]
	v_max_f32_e32 v106, 0xc2700000, v106
	v_max_f32_e32 v107, 0xc2700000, v107
	s_lshl_b32 s3, s71, 7
	v_rcp_f32_e32 v128, v124
	v_rcp_f32_e32 v129, v125
	v_pk_mul_f32 v[124:125], v[126:127], v[124:125]
	v_rcp_f32_e32 v126, v114
	v_rcp_f32_e32 v127, v115
	v_pk_mul_f32 v[118:119], v[118:119], v[114:115]
	v_pk_add_f32 v[114:115], v[116:117], 1.0 op_sel_hi:[1,0]
	v_ashrrev_i32_e32 v131, 31, v130
	v_mul_f32_e32 v106, 0xbfb8aa3b, v106
	v_mul_f32_e32 v107, 0xbfb8aa3b, v107
	s_add_i32 s68, s3, 0xfffff800
	v_rcp_f32_e32 v134, v114
	v_pk_mul_f32 v[120:121], v[120:121], v[114:115]
	v_rcp_f32_e32 v135, v115
	v_lshlrev_b64 v[114:115], 12, v[130:131]
	v_exp_f32_e32 v106, v106
	v_add_f32_e32 v110, 1.0, v110
	v_exp_f32_e32 v107, v107
	v_add_f32_e32 v111, 1.0, v111
	v_lshl_add_u64 v[114:115], s[54:55], 0, v[114:115]
	s_lshl_b64 s[6:7], s[68:69], 1
	v_rcp_f32_e32 v110, v110
	v_rcp_f32_e32 v111, v111
	v_lshl_add_u64 v[114:115], v[114:115], 0, s[6:7]
	v_lshlrev_b32_e32 v146, 1, v148
	v_lshl_add_u64 v[114:115], v[114:115], 0, v[146:147]
	v_cvt_pk_bf16_f32 v116, v122, v123
	v_cvt_pk_bf16_f32 v117, v124, v125
	v_cvt_pk_bf16_f32 v118, v118, v119
	v_cvt_pk_bf16_f32 v119, v120, v121
	global_store_dwordx4 v[114:115], v[116:119], off sc1
	v_pk_add_f32 v[106:107], v[106:107], 1.0 op_sel_hi:[1,0]
	v_mul_f32_e32 v102, 0xbfb8aa3b, v102
	v_cvt_pk_bf16_f32 v116, v132, v133
	v_cvt_pk_bf16_f32 v117, v128, v129
	v_cvt_pk_bf16_f32 v118, v126, v127
	v_cvt_pk_bf16_f32 v119, v134, v135
	global_store_dwordx4 v[114:115], v[116:119], off offset:2048 sc1
	v_pk_mul_f32 v[110:111], v[110:111], v[106:107]
	v_mul_f32_e32 v103, 0xbfb8aa3b, v103
	v_rcp_f32_e32 v116, v106
	v_mul_f32_e32 v106, 0xbfb8aa3b, v112
	v_exp_f32_e32 v106, v106
	v_exp_f32_e32 v102, v102
	v_exp_f32_e32 v103, v103
	v_max_f32_e32 v108, v108, v108
	v_add_f32_e32 v106, 1.0, v106
	v_rcp_f32_e32 v112, v106
	v_mul_f32_e32 v106, 0xbfb8aa3b, v113
	v_exp_f32_e32 v106, v106
	v_max_f32_e32 v109, v109, v109
	v_max_f32_e32 v98, v98, v98
	v_max_f32_e32 v99, v99, v99
	v_max_f32_e32 v108, 0xc2700000, v108
	v_max_f32_e32 v109, 0xc2700000, v109
	v_max_f32_e32 v98, 0xc2700000, v98
	v_max_f32_e32 v99, 0xc2700000, v99
	v_mul_f32_e32 v108, 0xbfb8aa3b, v108
	v_mul_f32_e32 v109, 0xbfb8aa3b, v109
	v_mul_f32_e32 v98, 0xbfb8aa3b, v98
	v_mul_f32_e32 v99, 0xbfb8aa3b, v99
	v_exp_f32_e32 v108, v108
	v_exp_f32_e32 v109, v109
	v_add_f32_e32 v106, 1.0, v106
	v_exp_f32_e32 v98, v98
	v_add_f32_e32 v102, 1.0, v102
	v_exp_f32_e32 v99, v99
	v_add_f32_e32 v103, 1.0, v103
	v_rcp_f32_e32 v113, v106
	v_rcp_f32_e32 v102, v102
	v_rcp_f32_e32 v103, v103
	v_rcp_f32_e32 v117, v107
	v_pk_add_f32 v[106:107], v[108:109], 1.0 op_sel_hi:[1,0]
	v_pk_add_f32 v[98:99], v[98:99], 1.0 op_sel_hi:[1,0]
	v_pk_mul_f32 v[108:109], v[112:113], v[106:107]
	v_rcp_f32_e32 v113, v98
	v_pk_mul_f32 v[102:103], v[102:103], v[98:99]
	v_mul_f32_e32 v98, 0xbfb8aa3b, v104
	v_exp_f32_e32 v98, v98
	v_max_f32_e32 v100, v100, v100
	v_max_f32_e32 v101, v101, v101
	v_max_f32_e32 v100, 0xc2700000, v100
	v_add_f32_e32 v98, 1.0, v98
	v_rcp_f32_e32 v104, v98
; __device__ __forceinline__ u32x4 pack8(const f32x4 a, const f32x4 b) { u32x4 w; w.x = cvt_pk_bf16(a[0], a[1]); w.y = cvt_pk_bf16(a[2], a[3]); w.z = cvt_pk_bf16(b[0], b[1]); w.w = cvt_pk_bf16(b[2], b[3]); return w; }
;     __device__ __forceinline__ void operator()(const f32x4 (&acc)[2][2][4][2], const Unit& u, int wr, int wc, int fr, int fq) const {
;     ...
;         if (pn >= 16) {
; #pragma unroll
;             for (int ai = 0; ai < 2; ++ai)
; #pragma unroll
;                 for (int m = 0; m < 4; ++m) { const int r = row0 + ai * HALF + m * 16;
;                     f32x4 ra[2], gb[2];
; #pragma unroll
;                     for (int n = 0; n < 2; ++n)
; #pragma unroll
;                         for (int i = 0; i < 4; ++i) { const float ea = __expf(-acc[ai][0][m][n][i]), eb = __expf(-fmaxf(acc[ai][1][m][n][i], -60.f));
;                             gb[n][i] = __builtin_amdgcn_rcpf(1.f + eb); ra[n][i] = (1.f + eb) * __builtin_amdgcn_rcpf(1.f + ea); }
;                     bf16_t* gp = gab + (size_t)r * 2048 + (pn - 16) * 128 + c8;
;                     *(u32x4*)gp = pack8(ra[0], ra[1]); *(u32x4*)(gp + 1024) = pack8(gb[0], gb[1]); }
	v_mul_f32_e32 v98, 0xbfb8aa3b, v105
	v_exp_f32_e32 v98, v98
	v_max_f32_e32 v101, 0xc2700000, v101
	v_mul_f32_e32 v100, 0xbfb8aa3b, v100
	v_mul_f32_e32 v101, 0xbfb8aa3b, v101
	v_exp_f32_e32 v100, v100
	v_exp_f32_e32 v101, v101
	v_add_f32_e32 v98, 1.0, v98
	v_rcp_f32_e32 v105, v98
	v_mul_f32_e32 v94, 0xbfb8aa3b, v94
	v_mul_f32_e32 v95, 0xbfb8aa3b, v95
	v_exp_f32_e32 v94, v94
	v_exp_f32_e32 v95, v95
	v_rcp_f32_e32 v119, v99
	v_pk_add_f32 v[98:99], v[100:101], 1.0 op_sel_hi:[1,0]
	v_max_f32_e32 v90, v90, v90
	v_max_f32_e32 v91, v91, v91
	v_rcp_f32_e32 v120, v98
	v_pk_mul_f32 v[104:105], v[104:105], v[98:99]
	v_or_b32_e32 v98, 16, v130
	v_max_f32_e32 v90, 0xc2700000, v90
	v_max_f32_e32 v91, 0xc2700000, v91
	v_rcp_f32_e32 v121, v99
	v_ashrrev_i32_e32 v99, 31, v98
	v_mul_f32_e32 v90, 0xbfb8aa3b, v90
	v_mul_f32_e32 v91, 0xbfb8aa3b, v91
	v_rcp_f32_e32 v118, v106
	v_rcp_f32_e32 v112, v107
	v_lshlrev_b64 v[98:99], 12, v[98:99]
	v_exp_f32_e32 v90, v90
	v_add_f32_e32 v94, 1.0, v94
	v_exp_f32_e32 v91, v91
	v_add_f32_e32 v95, 1.0, v95
	v_lshl_add_u64 v[98:99], s[54:55], 0, v[98:99]
	v_rcp_f32_e32 v94, v94
	v_rcp_f32_e32 v95, v95
	v_lshl_add_u64 v[98:99], v[98:99], 0, s[6:7]
	v_lshl_add_u64 v[106:107], v[98:99], 0, v[146:147]
	v_cvt_pk_bf16_f32 v98, v110, v111
	v_cvt_pk_bf16_f32 v99, v108, v109
	v_cvt_pk_bf16_f32 v100, v102, v103
	v_cvt_pk_bf16_f32 v101, v104, v105
	global_store_dwordx4 v[106:107], v[98:101], off sc1
	v_pk_add_f32 v[90:91], v[90:91], 1.0 op_sel_hi:[1,0]
	v_mul_f32_e32 v86, 0xbfb8aa3b, v86
	v_cvt_pk_bf16_f32 v98, v116, v117
	v_cvt_pk_bf16_f32 v99, v118, v112
	v_cvt_pk_bf16_f32 v100, v113, v119
	v_cvt_pk_bf16_f32 v101, v120, v121
	global_store_dwordx4 v[106:107], v[98:101], off offset:2048 sc1
	v_pk_mul_f32 v[94:95], v[94:95], v[90:91]
	v_mul_f32_e32 v87, 0xbfb8aa3b, v87
	v_rcp_f32_e32 v98, v90
	v_mul_f32_e32 v90, 0xbfb8aa3b, v96
	v_exp_f32_e32 v90, v90
	v_exp_f32_e32 v86, v86
	v_exp_f32_e32 v87, v87
	v_max_f32_e32 v92, v92, v92
	v_add_f32_e32 v90, 1.0, v90
	v_rcp_f32_e32 v96, v90
	v_mul_f32_e32 v90, 0xbfb8aa3b, v97
	v_exp_f32_e32 v90, v90
	v_max_f32_e32 v93, v93, v93
	v_max_f32_e32 v82, v82, v82
	v_max_f32_e32 v83, v83, v83
	v_max_f32_e32 v92, 0xc2700000, v92
	v_max_f32_e32 v93, 0xc2700000, v93
	v_max_f32_e32 v82, 0xc2700000, v82
	v_max_f32_e32 v83, 0xc2700000, v83
	v_mul_f32_e32 v92, 0xbfb8aa3b, v92
	v_mul_f32_e32 v93, 0xbfb8aa3b, v93
	v_mul_f32_e32 v82, 0xbfb8aa3b, v82
	v_mul_f32_e32 v83, 0xbfb8aa3b, v83
	v_exp_f32_e32 v92, v92
	v_exp_f32_e32 v93, v93
	v_add_f32_e32 v90, 1.0, v90
	v_exp_f32_e32 v82, v82
	v_add_f32_e32 v86, 1.0, v86
	v_exp_f32_e32 v83, v83
	v_add_f32_e32 v87, 1.0, v87
	v_rcp_f32_e32 v97, v90
	v_rcp_f32_e32 v86, v86
	v_rcp_f32_e32 v87, v87
	v_rcp_f32_e32 v99, v91
	v_pk_add_f32 v[90:91], v[92:93], 1.0 op_sel_hi:[1,0]
	v_pk_add_f32 v[82:83], v[82:83], 1.0 op_sel_hi:[1,0]
	v_pk_mul_f32 v[92:93], v[96:97], v[90:91]
	v_rcp_f32_e32 v97, v82
	v_pk_mul_f32 v[86:87], v[86:87], v[82:83]
	v_mul_f32_e32 v82, 0xbfb8aa3b, v88
	v_exp_f32_e32 v82, v82
	v_max_f32_e32 v84, v84, v84
	v_max_f32_e32 v85, v85, v85
	v_max_f32_e32 v84, 0xc2700000, v84
	v_add_f32_e32 v82, 1.0, v82
	v_rcp_f32_e32 v88, v82
	v_mul_f32_e32 v82, 0xbfb8aa3b, v89
	v_exp_f32_e32 v82, v82
	v_max_f32_e32 v85, 0xc2700000, v85
	v_mul_f32_e32 v84, 0xbfb8aa3b, v84
	v_mul_f32_e32 v85, 0xbfb8aa3b, v85
	v_exp_f32_e32 v84, v84
	v_exp_f32_e32 v85, v85
	v_add_f32_e32 v82, 1.0, v82
	v_rcp_f32_e32 v89, v82
	v_mul_f32_e32 v78, 0xbfb8aa3b, v78
	v_mul_f32_e32 v79, 0xbfb8aa3b, v79
	v_exp_f32_e32 v78, v78
	v_exp_f32_e32 v79, v79
	v_rcp_f32_e32 v101, v83
	v_pk_add_f32 v[82:83], v[84:85], 1.0 op_sel_hi:[1,0]
	v_max_f32_e32 v74, v74, v74
	v_max_f32_e32 v75, v75, v75
	v_rcp_f32_e32 v102, v82
	v_pk_mul_f32 v[88:89], v[88:89], v[82:83]
	v_or_b32_e32 v82, 32, v130
	v_max_f32_e32 v74, 0xc2700000, v74
	v_max_f32_e32 v75, 0xc2700000, v75
	v_rcp_f32_e32 v103, v83
	v_ashrrev_i32_e32 v83, 31, v82
	v_mul_f32_e32 v74, 0xbfb8aa3b, v74
	v_mul_f32_e32 v75, 0xbfb8aa3b, v75
	v_rcp_f32_e32 v100, v90
	v_rcp_f32_e32 v96, v91
	v_lshlrev_b64 v[82:83], 12, v[82:83]
	v_exp_f32_e32 v74, v74
	v_add_f32_e32 v78, 1.0, v78
	v_exp_f32_e32 v75, v75
	v_add_f32_e32 v79, 1.0, v79
	v_lshl_add_u64 v[82:83], s[54:55], 0, v[82:83]
	v_rcp_f32_e32 v78, v78
	v_rcp_f32_e32 v79, v79
	v_lshl_add_u64 v[82:83], v[82:83], 0, s[6:7]
	v_lshl_add_u64 v[90:91], v[82:83], 0, v[146:147]
	v_cvt_pk_bf16_f32 v82, v94, v95
	v_cvt_pk_bf16_f32 v83, v92, v93
	v_cvt_pk_bf16_f32 v84, v86, v87
	v_cvt_pk_bf16_f32 v85, v88, v89
	global_store_dwordx4 v[90:91], v[82:85], off sc1
	v_pk_add_f32 v[74:75], v[74:75], 1.0 op_sel_hi:[1,0]
	v_mul_f32_e32 v70, 0xbfb8aa3b, v70
	v_cvt_pk_bf16_f32 v82, v98, v99
	v_cvt_pk_bf16_f32 v83, v100, v96
	v_cvt_pk_bf16_f32 v84, v97, v101
	v_cvt_pk_bf16_f32 v85, v102, v103
	global_store_dwordx4 v[90:91], v[82:85], off offset:2048 sc1
	v_pk_mul_f32 v[78:79], v[78:79], v[74:75]
	v_mul_f32_e32 v71, 0xbfb8aa3b, v71
	v_rcp_f32_e32 v82, v74
	v_mul_f32_e32 v74, 0xbfb8aa3b, v80
	v_exp_f32_e32 v74, v74
	v_exp_f32_e32 v70, v70
	v_exp_f32_e32 v71, v71
	v_max_f32_e32 v76, v76, v76
	v_add_f32_e32 v74, 1.0, v74
	v_rcp_f32_e32 v80, v74
	v_mul_f32_e32 v74, 0xbfb8aa3b, v81
	v_exp_f32_e32 v74, v74
	v_max_f32_e32 v77, v77, v77
	v_max_f32_e32 v66, v66, v66
	v_max_f32_e32 v67, v67, v67
	v_max_f32_e32 v76, 0xc2700000, v76
	v_max_f32_e32 v77, 0xc2700000, v77
	v_max_f32_e32 v66, 0xc2700000, v66
	v_max_f32_e32 v67, 0xc2700000, v67
	v_mul_f32_e32 v76, 0xbfb8aa3b, v76
	v_mul_f32_e32 v77, 0xbfb8aa3b, v77
	v_mul_f32_e32 v66, 0xbfb8aa3b, v66
	v_mul_f32_e32 v67, 0xbfb8aa3b, v67
	v_exp_f32_e32 v76, v76
	v_exp_f32_e32 v77, v77
	v_add_f32_e32 v74, 1.0, v74
; __device__ __forceinline__ u32x4 pack8(const f32x4 a, const f32x4 b) { u32x4 w; w.x = cvt_pk_bf16(a[0], a[1]); w.y = cvt_pk_bf16(a[2], a[3]); w.z = cvt_pk_bf16(b[0], b[1]); w.w = cvt_pk_bf16(b[2], b[3]); return w; }
;     __device__ __forceinline__ void operator()(const f32x4 (&acc)[2][2][4][2], const Unit& u, int wr, int wc, int fr, int fq) const {
;     ...
;         if (pn >= 16) {
; #pragma unroll
;             for (int ai = 0; ai < 2; ++ai)
; #pragma unroll
;                 for (int m = 0; m < 4; ++m) { const int r = row0 + ai * HALF + m * 16;
;                     f32x4 ra[2], gb[2];
; #pragma unroll
;                     for (int n = 0; n < 2; ++n)
; #pragma unroll
;                         for (int i = 0; i < 4; ++i) { const float ea = __expf(-acc[ai][0][m][n][i]), eb = __expf(-fmaxf(acc[ai][1][m][n][i], -60.f));
;                             gb[n][i] = __builtin_amdgcn_rcpf(1.f + eb); ra[n][i] = (1.f + eb) * __builtin_amdgcn_rcpf(1.f + ea); }
;                     bf16_t* gp = gab + (size_t)r * 2048 + (pn - 16) * 128 + c8;
;                     *(u32x4*)gp = pack8(ra[0], ra[1]); *(u32x4*)(gp + 1024) = pack8(gb[0], gb[1]); }
	v_exp_f32_e32 v66, v66
	v_add_f32_e32 v70, 1.0, v70
	v_exp_f32_e32 v67, v67
	v_add_f32_e32 v71, 1.0, v71
	v_rcp_f32_e32 v81, v74
	v_rcp_f32_e32 v70, v70
	v_rcp_f32_e32 v71, v71
	v_rcp_f32_e32 v83, v75
	v_pk_add_f32 v[74:75], v[76:77], 1.0 op_sel_hi:[1,0]
	v_pk_add_f32 v[66:67], v[66:67], 1.0 op_sel_hi:[1,0]
	v_pk_mul_f32 v[76:77], v[80:81], v[74:75]
	v_rcp_f32_e32 v81, v66
	v_pk_mul_f32 v[70:71], v[70:71], v[66:67]
	v_mul_f32_e32 v66, 0xbfb8aa3b, v72
	v_exp_f32_e32 v66, v66
	v_max_f32_e32 v68, v68, v68
	v_max_f32_e32 v69, v69, v69
	v_max_f32_e32 v68, 0xc2700000, v68
	v_add_f32_e32 v66, 1.0, v66
	v_rcp_f32_e32 v72, v66
	v_mul_f32_e32 v66, 0xbfb8aa3b, v73
	v_exp_f32_e32 v66, v66
	v_max_f32_e32 v69, 0xc2700000, v69
	v_mul_f32_e32 v68, 0xbfb8aa3b, v68
	v_mul_f32_e32 v69, 0xbfb8aa3b, v69
	v_exp_f32_e32 v68, v68
	v_exp_f32_e32 v69, v69
	v_add_f32_e32 v66, 1.0, v66
	v_rcp_f32_e32 v73, v66
	v_mul_f32_e32 v62, 0xbfb8aa3b, v62
	v_mul_f32_e32 v63, 0xbfb8aa3b, v63
	v_exp_f32_e32 v62, v62
	v_exp_f32_e32 v63, v63
	v_rcp_f32_e32 v85, v67
	v_pk_add_f32 v[66:67], v[68:69], 1.0 op_sel_hi:[1,0]
	v_max_f32_e32 v58, v58, v58
	v_max_f32_e32 v59, v59, v59
	v_rcp_f32_e32 v86, v66
	v_pk_mul_f32 v[72:73], v[72:73], v[66:67]
	v_or_b32_e32 v66, 48, v130
	v_max_f32_e32 v58, 0xc2700000, v58
	v_max_f32_e32 v59, 0xc2700000, v59
	v_rcp_f32_e32 v87, v67
	v_ashrrev_i32_e32 v67, 31, v66
	v_mul_f32_e32 v58, 0xbfb8aa3b, v58
	v_mul_f32_e32 v59, 0xbfb8aa3b, v59
	v_rcp_f32_e32 v84, v74
	v_rcp_f32_e32 v80, v75
	v_lshlrev_b64 v[66:67], 12, v[66:67]
	v_exp_f32_e32 v58, v58
	v_add_f32_e32 v62, 1.0, v62
	v_exp_f32_e32 v59, v59
	v_add_f32_e32 v63, 1.0, v63
	v_lshl_add_u64 v[66:67], s[54:55], 0, v[66:67]
	v_rcp_f32_e32 v62, v62
	v_rcp_f32_e32 v63, v63
	v_lshl_add_u64 v[66:67], v[66:67], 0, s[6:7]
	v_lshl_add_u64 v[74:75], v[66:67], 0, v[146:147]
	v_cvt_pk_bf16_f32 v66, v78, v79
	v_cvt_pk_bf16_f32 v67, v76, v77
	v_cvt_pk_bf16_f32 v68, v70, v71
	v_cvt_pk_bf16_f32 v69, v72, v73
	global_store_dwordx4 v[74:75], v[66:69], off sc1
	v_pk_add_f32 v[58:59], v[58:59], 1.0 op_sel_hi:[1,0]
	v_mul_f32_e32 v54, 0xbfb8aa3b, v54
	v_cvt_pk_bf16_f32 v66, v82, v83
	v_cvt_pk_bf16_f32 v67, v84, v80
	v_cvt_pk_bf16_f32 v68, v81, v85
	v_cvt_pk_bf16_f32 v69, v86, v87
	global_store_dwordx4 v[74:75], v[66:69], off offset:2048 sc1
	v_pk_mul_f32 v[62:63], v[62:63], v[58:59]
	v_mul_f32_e32 v55, 0xbfb8aa3b, v55
	v_rcp_f32_e32 v66, v58
	v_mul_f32_e32 v58, 0xbfb8aa3b, v64
	v_exp_f32_e32 v58, v58
	v_exp_f32_e32 v54, v54
	v_exp_f32_e32 v55, v55
	v_max_f32_e32 v60, v60, v60
	v_add_f32_e32 v58, 1.0, v58
	v_rcp_f32_e32 v64, v58
	v_mul_f32_e32 v58, 0xbfb8aa3b, v65
	v_exp_f32_e32 v58, v58
	v_max_f32_e32 v61, v61, v61
	v_max_f32_e32 v50, v50, v50
	v_max_f32_e32 v51, v51, v51
	v_max_f32_e32 v60, 0xc2700000, v60
	v_max_f32_e32 v61, 0xc2700000, v61
	v_max_f32_e32 v50, 0xc2700000, v50
	v_max_f32_e32 v51, 0xc2700000, v51
	v_mul_f32_e32 v60, 0xbfb8aa3b, v60
	v_mul_f32_e32 v61, 0xbfb8aa3b, v61
	v_mul_f32_e32 v50, 0xbfb8aa3b, v50
	v_mul_f32_e32 v51, 0xbfb8aa3b, v51
	v_exp_f32_e32 v60, v60
	v_exp_f32_e32 v61, v61
	v_add_f32_e32 v58, 1.0, v58
	v_exp_f32_e32 v50, v50
	v_add_f32_e32 v54, 1.0, v54
	v_exp_f32_e32 v51, v51
	v_add_f32_e32 v55, 1.0, v55
	v_rcp_f32_e32 v65, v58
	v_rcp_f32_e32 v54, v54
	v_rcp_f32_e32 v55, v55
	v_rcp_f32_e32 v67, v59
	v_pk_add_f32 v[58:59], v[60:61], 1.0 op_sel_hi:[1,0]
	v_pk_add_f32 v[50:51], v[50:51], 1.0 op_sel_hi:[1,0]
	v_pk_mul_f32 v[60:61], v[64:65], v[58:59]
	v_rcp_f32_e32 v65, v50
	v_pk_mul_f32 v[54:55], v[54:55], v[50:51]
	v_mul_f32_e32 v50, 0xbfb8aa3b, v56
	v_exp_f32_e32 v50, v50
	v_max_f32_e32 v52, v52, v52
	v_max_f32_e32 v53, v53, v53
	v_max_f32_e32 v52, 0xc2700000, v52
	v_add_f32_e32 v50, 1.0, v50
	v_rcp_f32_e32 v56, v50
	v_mul_f32_e32 v50, 0xbfb8aa3b, v57
	v_exp_f32_e32 v50, v50
	v_max_f32_e32 v53, 0xc2700000, v53
	v_mul_f32_e32 v52, 0xbfb8aa3b, v52
	v_mul_f32_e32 v53, 0xbfb8aa3b, v53
	v_exp_f32_e32 v52, v52
	v_exp_f32_e32 v53, v53
	v_mul_f32_e32 v46, 0xbfb8aa3b, v46
	v_mul_f32_e32 v47, 0xbfb8aa3b, v47
	v_exp_f32_e32 v46, v46
	v_exp_f32_e32 v47, v47
	v_add_f32_e32 v50, 1.0, v50
	v_max_f32_e32 v42, v42, v42
	v_max_f32_e32 v43, v43, v43
	v_rcp_f32_e32 v57, v50
	v_max_f32_e32 v42, 0xc2700000, v42
	v_max_f32_e32 v43, 0xc2700000, v43
	v_rcp_f32_e32 v69, v51
	v_pk_add_f32 v[50:51], v[52:53], 1.0 op_sel_hi:[1,0]
	v_mul_f32_e32 v42, 0xbfb8aa3b, v42
	v_mul_f32_e32 v43, 0xbfb8aa3b, v43
	v_rcp_f32_e32 v68, v58
	v_rcp_f32_e32 v64, v59
	v_rcp_f32_e32 v70, v50
	v_rcp_f32_e32 v71, v51
	v_exp_f32_e32 v42, v42
	v_add_f32_e32 v46, 1.0, v46
	v_exp_f32_e32 v43, v43
	v_add_f32_e32 v47, 1.0, v47
	s_mov_b32 s3, 0x80000
	v_rcp_f32_e32 v46, v46
	v_rcp_f32_e32 v47, v47
	v_pk_mul_f32 v[56:57], v[56:57], v[50:51]
	v_cvt_pk_bf16_f32 v52, v54, v55
	v_add_co_u32_e32 v54, vcc, s3, v114
	s_mov_b64 s[6:7], 0x80000
	v_cvt_pk_bf16_f32 v50, v62, v63
	v_cvt_pk_bf16_f32 v51, v60, v61
	v_cvt_pk_bf16_f32 v53, v56, v57
	v_addc_co_u32_e32 v55, vcc, 0, v115, vcc
	v_lshl_add_u64 v[58:59], v[114:115], 0, s[6:7]
	global_store_dwordx4 v[54:55], v[50:53], off sc1
	v_pk_add_f32 v[42:43], v[42:43], 1.0 op_sel_hi:[1,0]
	v_mul_f32_e32 v38, 0xbfb8aa3b, v38
	v_cvt_pk_bf16_f32 v50, v66, v67
	v_cvt_pk_bf16_f32 v51, v68, v64
	v_cvt_pk_bf16_f32 v52, v65, v69
	v_cvt_pk_bf16_f32 v53, v70, v71
	global_store_dwordx4 v[58:59], v[50:53], off offset:2048 sc1
	v_pk_mul_f32 v[46:47], v[46:47], v[42:43]
	v_mul_f32_e32 v39, 0xbfb8aa3b, v39
	v_rcp_f32_e32 v50, v42
	v_mul_f32_e32 v42, 0xbfb8aa3b, v48
	v_exp_f32_e32 v42, v42
	v_exp_f32_e32 v38, v38
	v_exp_f32_e32 v39, v39
	v_max_f32_e32 v44, v44, v44
	v_add_f32_e32 v42, 1.0, v42
	v_rcp_f32_e32 v48, v42
; __device__ __forceinline__ u32x4 pack8(const f32x4 a, const f32x4 b) { u32x4 w; w.x = cvt_pk_bf16(a[0], a[1]); w.y = cvt_pk_bf16(a[2], a[3]); w.z = cvt_pk_bf16(b[0], b[1]); w.w = cvt_pk_bf16(b[2], b[3]); return w; }
;     __device__ __forceinline__ void operator()(const f32x4 (&acc)[2][2][4][2], const Unit& u, int wr, int wc, int fr, int fq) const {
;     ...
;         if (pn >= 16) {
; #pragma unroll
;             for (int ai = 0; ai < 2; ++ai)
; #pragma unroll
;                 for (int m = 0; m < 4; ++m) { const int r = row0 + ai * HALF + m * 16;
;                     f32x4 ra[2], gb[2];
; #pragma unroll
;                     for (int n = 0; n < 2; ++n)
; #pragma unroll
;                         for (int i = 0; i < 4; ++i) { const float ea = __expf(-acc[ai][0][m][n][i]), eb = __expf(-fmaxf(acc[ai][1][m][n][i], -60.f));
;                             gb[n][i] = __builtin_amdgcn_rcpf(1.f + eb); ra[n][i] = (1.f + eb) * __builtin_amdgcn_rcpf(1.f + ea); }
;                     bf16_t* gp = gab + (size_t)r * 2048 + (pn - 16) * 128 + c8;
;                     *(u32x4*)gp = pack8(ra[0], ra[1]); *(u32x4*)(gp + 1024) = pack8(gb[0], gb[1]); }
	v_mul_f32_e32 v42, 0xbfb8aa3b, v49
	v_exp_f32_e32 v42, v42
	v_max_f32_e32 v45, v45, v45
	v_max_f32_e32 v34, v34, v34
	v_max_f32_e32 v35, v35, v35
	v_max_f32_e32 v44, 0xc2700000, v44
	v_max_f32_e32 v45, 0xc2700000, v45
	v_max_f32_e32 v34, 0xc2700000, v34
	v_max_f32_e32 v35, 0xc2700000, v35
	v_mul_f32_e32 v44, 0xbfb8aa3b, v44
	v_mul_f32_e32 v45, 0xbfb8aa3b, v45
	v_mul_f32_e32 v34, 0xbfb8aa3b, v34
	v_mul_f32_e32 v35, 0xbfb8aa3b, v35
	v_exp_f32_e32 v44, v44
	v_exp_f32_e32 v45, v45
	v_add_f32_e32 v42, 1.0, v42
	v_exp_f32_e32 v34, v34
	v_add_f32_e32 v38, 1.0, v38
	v_exp_f32_e32 v35, v35
	v_add_f32_e32 v39, 1.0, v39
	v_rcp_f32_e32 v49, v42
	v_rcp_f32_e32 v38, v38
	v_rcp_f32_e32 v39, v39
	v_rcp_f32_e32 v51, v43
	v_pk_add_f32 v[42:43], v[44:45], 1.0 op_sel_hi:[1,0]
	v_pk_add_f32 v[34:35], v[34:35], 1.0 op_sel_hi:[1,0]
	v_pk_mul_f32 v[44:45], v[48:49], v[42:43]
	v_rcp_f32_e32 v49, v34
	v_pk_mul_f32 v[38:39], v[38:39], v[34:35]
	v_mul_f32_e32 v34, 0xbfb8aa3b, v40
	v_exp_f32_e32 v34, v34
	v_max_f32_e32 v36, v36, v36
	v_max_f32_e32 v37, v37, v37
	v_max_f32_e32 v36, 0xc2700000, v36
	v_add_f32_e32 v34, 1.0, v34
	v_rcp_f32_e32 v40, v34
	v_mul_f32_e32 v34, 0xbfb8aa3b, v41
	v_exp_f32_e32 v34, v34
	v_max_f32_e32 v37, 0xc2700000, v37
	v_mul_f32_e32 v36, 0xbfb8aa3b, v36
	v_mul_f32_e32 v37, 0xbfb8aa3b, v37
	v_exp_f32_e32 v36, v36
	v_exp_f32_e32 v37, v37
	v_mul_f32_e32 v30, 0xbfb8aa3b, v30
	v_mul_f32_e32 v31, 0xbfb8aa3b, v31
	v_exp_f32_e32 v30, v30
	v_exp_f32_e32 v31, v31
	v_add_f32_e32 v34, 1.0, v34
	v_max_f32_e32 v26, v26, v26
	v_max_f32_e32 v27, v27, v27
	v_rcp_f32_e32 v41, v34
	v_max_f32_e32 v26, 0xc2700000, v26
	v_max_f32_e32 v27, 0xc2700000, v27
	v_rcp_f32_e32 v53, v35
	v_pk_add_f32 v[34:35], v[36:37], 1.0 op_sel_hi:[1,0]
	v_mul_f32_e32 v26, 0xbfb8aa3b, v26
	v_mul_f32_e32 v27, 0xbfb8aa3b, v27
	v_rcp_f32_e32 v52, v42
	v_rcp_f32_e32 v48, v43
	v_rcp_f32_e32 v54, v34
	v_rcp_f32_e32 v55, v35
	v_exp_f32_e32 v26, v26
	v_add_f32_e32 v30, 1.0, v30
	v_exp_f32_e32 v27, v27
	v_add_f32_e32 v31, 1.0, v31
	s_mov_b32 s3, 0x90000
	v_rcp_f32_e32 v30, v30
	v_rcp_f32_e32 v31, v31
	v_pk_mul_f32 v[40:41], v[40:41], v[34:35]
	v_cvt_pk_bf16_f32 v36, v38, v39
	v_add_co_u32_e32 v38, vcc, s3, v114
	s_mov_b64 s[6:7], 0x90000
	v_cvt_pk_bf16_f32 v34, v46, v47
	v_cvt_pk_bf16_f32 v35, v44, v45
	v_cvt_pk_bf16_f32 v37, v40, v41
	v_addc_co_u32_e32 v39, vcc, 0, v115, vcc
	v_lshl_add_u64 v[42:43], v[114:115], 0, s[6:7]
	global_store_dwordx4 v[38:39], v[34:37], off sc1
	v_pk_add_f32 v[26:27], v[26:27], 1.0 op_sel_hi:[1,0]
	v_mul_f32_e32 v22, 0xbfb8aa3b, v22
	v_cvt_pk_bf16_f32 v34, v50, v51
	v_cvt_pk_bf16_f32 v35, v52, v48
	v_cvt_pk_bf16_f32 v36, v49, v53
	v_cvt_pk_bf16_f32 v37, v54, v55
	global_store_dwordx4 v[42:43], v[34:37], off offset:2048 sc1
	v_pk_mul_f32 v[30:31], v[30:31], v[26:27]
	v_mul_f32_e32 v23, 0xbfb8aa3b, v23
	v_rcp_f32_e32 v34, v26
	v_mul_f32_e32 v26, 0xbfb8aa3b, v32
	v_exp_f32_e32 v26, v26
	v_exp_f32_e32 v22, v22
	v_exp_f32_e32 v23, v23
	v_max_f32_e32 v28, v28, v28
	v_add_f32_e32 v26, 1.0, v26
	v_rcp_f32_e32 v32, v26
	v_mul_f32_e32 v26, 0xbfb8aa3b, v33
	v_exp_f32_e32 v26, v26
	v_max_f32_e32 v29, v29, v29
	v_max_f32_e32 v18, v18, v18
	v_max_f32_e32 v19, v19, v19
	v_max_f32_e32 v28, 0xc2700000, v28
	v_max_f32_e32 v29, 0xc2700000, v29
	v_max_f32_e32 v18, 0xc2700000, v18
	v_max_f32_e32 v19, 0xc2700000, v19
	v_mul_f32_e32 v28, 0xbfb8aa3b, v28
	v_mul_f32_e32 v29, 0xbfb8aa3b, v29
	v_mul_f32_e32 v18, 0xbfb8aa3b, v18
	v_mul_f32_e32 v19, 0xbfb8aa3b, v19
	v_exp_f32_e32 v28, v28
	v_exp_f32_e32 v29, v29
	v_add_f32_e32 v26, 1.0, v26
	v_exp_f32_e32 v18, v18
	v_add_f32_e32 v22, 1.0, v22
	v_exp_f32_e32 v19, v19
	v_add_f32_e32 v23, 1.0, v23
	v_rcp_f32_e32 v33, v26
	v_rcp_f32_e32 v22, v22
	v_rcp_f32_e32 v23, v23
	v_rcp_f32_e32 v35, v27
	v_pk_add_f32 v[26:27], v[28:29], 1.0 op_sel_hi:[1,0]
	v_pk_add_f32 v[18:19], v[18:19], 1.0 op_sel_hi:[1,0]
	v_pk_mul_f32 v[28:29], v[32:33], v[26:27]
	v_rcp_f32_e32 v33, v18
	v_pk_mul_f32 v[22:23], v[22:23], v[18:19]
	v_mul_f32_e32 v18, 0xbfb8aa3b, v24
	v_exp_f32_e32 v18, v18
	v_max_f32_e32 v20, v20, v20
	v_max_f32_e32 v21, v21, v21
	v_max_f32_e32 v20, 0xc2700000, v20
; __device__ __forceinline__ u32x4 pack8(const f32x4 a, const f32x4 b) { u32x4 w; w.x = cvt_pk_bf16(a[0], a[1]); w.y = cvt_pk_bf16(a[2], a[3]); w.z = cvt_pk_bf16(b[0], b[1]); w.w = cvt_pk_bf16(b[2], b[3]); return w; }
;     __device__ __forceinline__ void operator()(const f32x4 (&acc)[2][2][4][2], const Unit& u, int wr, int wc, int fr, int fq) const {
;     ...
;         if (pn >= 16) {
; #pragma unroll
;             for (int ai = 0; ai < 2; ++ai)
; #pragma unroll
;                 for (int m = 0; m < 4; ++m) { const int r = row0 + ai * HALF + m * 16;
;                     f32x4 ra[2], gb[2];
; #pragma unroll
;                     for (int n = 0; n < 2; ++n)
; #pragma unroll
;                         for (int i = 0; i < 4; ++i) { const float ea = __expf(-acc[ai][0][m][n][i]), eb = __expf(-fmaxf(acc[ai][1][m][n][i], -60.f));
;                             gb[n][i] = __builtin_amdgcn_rcpf(1.f + eb); ra[n][i] = (1.f + eb) * __builtin_amdgcn_rcpf(1.f + ea); }
;                     bf16_t* gp = gab + (size_t)r * 2048 + (pn - 16) * 128 + c8;
;                     *(u32x4*)gp = pack8(ra[0], ra[1]); *(u32x4*)(gp + 1024) = pack8(gb[0], gb[1]); }
	v_add_f32_e32 v18, 1.0, v18
	v_rcp_f32_e32 v24, v18
	v_mul_f32_e32 v18, 0xbfb8aa3b, v25
	v_exp_f32_e32 v18, v18
	v_max_f32_e32 v21, 0xc2700000, v21
	v_mul_f32_e32 v20, 0xbfb8aa3b, v20
	v_mul_f32_e32 v21, 0xbfb8aa3b, v21
	v_exp_f32_e32 v20, v20
	v_exp_f32_e32 v21, v21
	v_mul_f32_e32 v14, 0xbfb8aa3b, v14
	v_mul_f32_e32 v15, 0xbfb8aa3b, v15
	v_exp_f32_e32 v14, v14
	v_exp_f32_e32 v15, v15
	v_add_f32_e32 v18, 1.0, v18
	v_max_f32_e32 v10, v10, v10
	v_max_f32_e32 v11, v11, v11
	v_rcp_f32_e32 v25, v18
	v_max_f32_e32 v10, 0xc2700000, v10
	v_max_f32_e32 v11, 0xc2700000, v11
	v_rcp_f32_e32 v37, v19
	v_pk_add_f32 v[18:19], v[20:21], 1.0 op_sel_hi:[1,0]
	v_mul_f32_e32 v10, 0xbfb8aa3b, v10
	v_mul_f32_e32 v11, 0xbfb8aa3b, v11
	v_rcp_f32_e32 v36, v26
	v_rcp_f32_e32 v32, v27
	v_rcp_f32_e32 v38, v18
	v_rcp_f32_e32 v39, v19
	v_exp_f32_e32 v10, v10
	v_add_f32_e32 v14, 1.0, v14
	v_exp_f32_e32 v11, v11
	v_add_f32_e32 v15, 1.0, v15
	s_mov_b32 s3, 0xa0000
	v_rcp_f32_e32 v14, v14
	v_rcp_f32_e32 v15, v15
	v_pk_mul_f32 v[24:25], v[24:25], v[18:19]
	v_cvt_pk_bf16_f32 v20, v22, v23
	v_add_co_u32_e32 v22, vcc, s3, v114
	s_mov_b64 s[6:7], 0xa0000
	v_cvt_pk_bf16_f32 v18, v30, v31
	v_cvt_pk_bf16_f32 v19, v28, v29
	v_cvt_pk_bf16_f32 v21, v24, v25
	v_addc_co_u32_e32 v23, vcc, 0, v115, vcc
	v_lshl_add_u64 v[26:27], v[114:115], 0, s[6:7]
	global_store_dwordx4 v[22:23], v[18:21], off sc1
	v_pk_add_f32 v[10:11], v[10:11], 1.0 op_sel_hi:[1,0]
	v_mul_f32_e32 v6, 0xbfb8aa3b, v6
	v_cvt_pk_bf16_f32 v18, v34, v35
	v_cvt_pk_bf16_f32 v19, v36, v32
	v_cvt_pk_bf16_f32 v20, v33, v37
	v_cvt_pk_bf16_f32 v21, v38, v39
	global_store_dwordx4 v[26:27], v[18:21], off offset:2048 sc1
	v_pk_mul_f32 v[14:15], v[14:15], v[10:11]
	v_mul_f32_e32 v7, 0xbfb8aa3b, v7
	v_rcp_f32_e32 v18, v10
	v_mul_f32_e32 v10, 0xbfb8aa3b, v16
	v_exp_f32_e32 v10, v10
	v_exp_f32_e32 v6, v6
	v_exp_f32_e32 v7, v7
	v_max_f32_e32 v12, v12, v12
	v_add_f32_e32 v10, 1.0, v10
	v_rcp_f32_e32 v16, v10
	v_mul_f32_e32 v10, 0xbfb8aa3b, v17
	v_exp_f32_e32 v10, v10
	v_max_f32_e32 v13, v13, v13
	v_max_f32_e32 v2, v2, v2
	v_max_f32_e32 v3, v3, v3
	v_max_f32_e32 v12, 0xc2700000, v12
	v_max_f32_e32 v13, 0xc2700000, v13
	v_max_f32_e32 v2, 0xc2700000, v2
	v_max_f32_e32 v3, 0xc2700000, v3
	v_mul_f32_e32 v12, 0xbfb8aa3b, v12
	v_mul_f32_e32 v13, 0xbfb8aa3b, v13
	v_mul_f32_e32 v2, 0xbfb8aa3b, v2
	v_mul_f32_e32 v3, 0xbfb8aa3b, v3
	v_exp_f32_e32 v12, v12
	v_exp_f32_e32 v13, v13
	v_add_f32_e32 v10, 1.0, v10
	v_exp_f32_e32 v2, v2
	v_add_f32_e32 v6, 1.0, v6
	v_exp_f32_e32 v3, v3
	v_add_f32_e32 v7, 1.0, v7
	v_rcp_f32_e32 v17, v10
	v_rcp_f32_e32 v6, v6
	v_rcp_f32_e32 v7, v7
	v_rcp_f32_e32 v19, v11
	v_pk_add_f32 v[10:11], v[12:13], 1.0 op_sel_hi:[1,0]
	v_pk_add_f32 v[2:3], v[2:3], 1.0 op_sel_hi:[1,0]
	v_pk_mul_f32 v[12:13], v[16:17], v[10:11]
	v_rcp_f32_e32 v17, v2
	v_pk_mul_f32 v[6:7], v[6:7], v[2:3]
	v_mul_f32_e32 v2, 0xbfb8aa3b, v8
	v_exp_f32_e32 v2, v2
	v_max_f32_e32 v4, v4, v4
	v_max_f32_e32 v5, v5, v5
	v_max_f32_e32 v4, 0xc2700000, v4
	v_add_f32_e32 v2, 1.0, v2
	v_rcp_f32_e32 v8, v2
	v_mul_f32_e32 v2, 0xbfb8aa3b, v9
	v_exp_f32_e32 v2, v2
	v_max_f32_e32 v5, 0xc2700000, v5
	v_mul_f32_e32 v4, 0xbfb8aa3b, v4
	v_mul_f32_e32 v5, 0xbfb8aa3b, v5
	v_exp_f32_e32 v4, v4
	v_exp_f32_e32 v5, v5
	v_add_f32_e32 v2, 1.0, v2
	v_rcp_f32_e32 v9, v2
	v_rcp_f32_e32 v21, v3
	v_pk_add_f32 v[2:3], v[4:5], 1.0 op_sel_hi:[1,0]
	v_rcp_f32_e32 v20, v10
	v_rcp_f32_e32 v16, v11
	v_rcp_f32_e32 v22, v2
	v_rcp_f32_e32 v23, v3
	s_mov_b32 s3, 0xb0000
	v_pk_mul_f32 v[8:9], v[8:9], v[2:3]
	v_cvt_pk_bf16_f32 v4, v6, v7
	v_add_co_u32_e32 v6, vcc, s3, v114
	s_mov_b64 s[6:7], 0xb0000
	v_cvt_pk_bf16_f32 v2, v14, v15
	v_cvt_pk_bf16_f32 v3, v12, v13
	v_cvt_pk_bf16_f32 v5, v8, v9
	v_addc_co_u32_e32 v7, vcc, 0, v115, vcc
	v_lshl_add_u64 v[10:11], v[114:115], 0, s[6:7]
	global_store_dwordx4 v[6:7], v[2:5], off sc1
	s_nop 1
	v_cvt_pk_bf16_f32 v2, v18, v19
	v_cvt_pk_bf16_f32 v3, v20, v16
	v_cvt_pk_bf16_f32 v4, v17, v21
	v_cvt_pk_bf16_f32 v5, v22, v23
	global_store_dwordx4 v[10:11], v[2:5], off offset:2048 sc1
	s_andn2_b64 vcc, exec, s[80:81]
	s_mov_b64 s[6:7], -1
	s_cbranch_vccnz .LBB0_686
	s_branch .LBB0_815

; __host__ __device__ __forceinline__ void tile_hp(int q, int bj, int& h, int& part) { if (q < 4) { h = q; part = bj; } else if (q < 6) { h = 2 * (q - 4) + bj; part = 2; } else { h = 2 * (q - 6) + bj; part = 3; } }
; __device__ __forceinline__ float sigmoidf_(float x) { return __builtin_amdgcn_rcpf(1.f + __expf(-x)); }
; __device__ __forceinline__ float siluf_(float x) { return x * __builtin_amdgcn_rcpf(1.f + __expf(-x)); }
; __device__ __forceinline__ u32x4 pack8(const f32x4 a, const f32x4 b) { u32x4 w; w.x = cvt_pk_bf16(a[0], a[1]); w.y = cvt_pk_bf16(a[2], a[3]); w.z = cvt_pk_bf16(b[0], b[1]); w.w = cvt_pk_bf16(b[2], b[3]); return w; }
;     __device__ __forceinline__ void operator()(const f32x4 (&acc)[2][2][4][2], const Unit& u, int wr, int wc, int fr, int fq) const {
;     ...
;         for (int bj = 0; bj < 2; ++bj) {
;             int h, part; tile_hp(q, bj, h, part);
;             const int mode = (part == 3) ? 3 : (grp == 0 ? (part == 0 ? 1 : (part == 1 ? 2 : 0)) : 0);
;             float lb[8];
; #pragma unroll
;             for (int i = 0; i < 8; ++i) lb[i] = 0.f;
;             if (mode == 2) {
; #pragma unroll
;                 for (int i = 0; i < 8; ++i) { const int ch = h * 128 + c8 + i; lb[i] = sigmoidf_(lbl[ch] - lbl[512 + ch]); }
;             }
; #pragma unroll
;             for (int ai = 0; ai < 2; ++ai)
; #pragma unroll
;                 for (int m = 0; m < 4; ++m) { const int r = row0 + ai * HALF + m * 16;
;                     f32x4 v0 = acc[ai][bj][m][0], v1 = acc[ai][bj][m][1];
;                     if (mode == 1) {
; #pragma unroll
;                         for (int i = 0; i < 4; ++i) { v0[i] = siluf_(v0[i]) * QSCALE; v1[i] = siluf_(v1[i]) * QSCALE; }
;                     } else if (mode == 2) {
; #pragma unroll
;                         for (int i = 0; i < 4; ++i) { v0[i] = __logf(lb[i] + (1.f - lb[i]) * sigmoidf_(v0[i])); v1[i] = __logf(lb[4 + i] + (1.f - lb[4 + i]) * sigmoidf_(v1[i])); }
;                     } else if (mode == 3) {
; #pragma unroll
;                         for (int i = 0; i < 4; ++i) { v0[i] = siluf_(v0[i]); v1[i] = siluf_(v1[i]); }
;                     }
;                     const u32x4 w = pack8(v0, v1);
;                     *(u32x4*)(base + ((size_t)((r >> 6) * 4 + h)) * 32768 + part * 8192 + (r & 63) * 128 + c8) = w;
.LBB0_706:
	s_and_b64 s[8:9], s[90:91], exec
	s_cselect_b32 s9, s27, s63
	s_cselect_b32 s8, s26, s62
	v_lshlrev_b32_e32 v146, 1, v148
	s_ashr_i32 s33, s77, 4
	v_lshl_add_u64 v[176:177], s[8:9], 0, v[146:147]
	s_add_i32 s8, s79, s33
	s_lshl_b32 s68, s4, 14
	s_ashr_i32 s9, s8, 31
	v_lshl_add_u64 v[178:179], v[176:177], 0, s[68:69]
	s_lshl_b64 s[8:9], s[8:9], 16
	v_lshl_add_u64 v[174:175], v[178:179], 0, s[8:9]
	v_lshlrev_b32_e32 v172, 1, v150
	v_mov_b32_e32 v173, v147
	v_cvt_pk_bf16_f32 v130, v130, v131
	v_cvt_pk_bf16_f32 v131, v132, v133
	v_cvt_pk_bf16_f32 v132, v134, v135
	v_cvt_pk_bf16_f32 v133, v136, v137
	v_lshl_add_u64 v[134:135], v[174:175], 0, v[172:173]
	global_store_dwordx4 v[134:135], v[130:133], off sc1
	s_andn2_b64 vcc, exec, s[86:87]
	s_mov_b64 s[66:67], -1
	v_cndmask_b32_e64 v130, 0, 1, s[86:87]
	v_cmp_ne_u32_e64 s[8:9], 1, v130
	s_cbranch_vccnz .LBB0_710
	v_mov_b64_e32 v[136:137], v[104:105]
	v_mov_b64_e32 v[132:133], v[112:113]
	s_and_b64 vcc, exec, s[6:7]
	v_mov_b64_e32 v[134:135], v[102:103]
	v_mov_b64_e32 v[130:131], v[110:111]
	s_cbranch_vccnz .LBB0_709
	v_mul_f32_e32 v131, 0xbfb8aa3b, v102
	v_mul_f32_e32 v132, 0xbfb8aa3b, v111
	v_exp_f32_e32 v131, v131
	v_exp_f32_e32 v132, v132
	v_mul_f32_e32 v133, 0xbfb8aa3b, v112
	v_mul_f32_e32 v135, 0xbfb8aa3b, v104
	v_add_f32_e32 v131, 1.0, v131
	v_rcp_f32_e32 v134, v131
	v_add_f32_e32 v131, 1.0, v132
	v_mul_f32_e32 v132, 0xbfb8aa3b, v103
	v_exp_f32_e32 v132, v132
	v_exp_f32_e32 v133, v133
	v_exp_f32_e32 v135, v135
	v_mul_f32_e32 v130, 0xbfb8aa3b, v110
	v_add_f32_e32 v166, 1.0, v132
	v_add_f32_e32 v132, 1.0, v133
	v_add_f32_e32 v133, 1.0, v135
	v_mul_f32_e32 v135, 0xbfb8aa3b, v113
	v_mul_f32_e32 v136, 0xbfb8aa3b, v105
	v_exp_f32_e32 v130, v130
	v_exp_f32_e32 v135, v135
	v_exp_f32_e32 v137, v136
	v_rcp_f32_e32 v136, v133
	v_add_f32_e32 v130, 1.0, v130
	v_add_f32_e32 v133, 1.0, v135
	v_add_f32_e32 v135, 1.0, v137
	v_rcp_f32_e32 v130, v130
	v_rcp_f32_e32 v131, v131
	v_rcp_f32_e32 v132, v132
	v_rcp_f32_e32 v133, v133
	v_rcp_f32_e32 v137, v135
	v_rcp_f32_e32 v135, v166
	v_pk_mul_f32 v[130:131], v[110:111], v[130:131]
	v_pk_mul_f32 v[132:133], v[112:113], v[132:133]
	v_pk_mul_f32 v[136:137], v[104:105], v[136:137]
	v_pk_mul_f32 v[134:135], v[102:103], v[134:135]

; __device__ __forceinline__ float sigmoidf_(float x) { return __builtin_amdgcn_rcpf(1.f + __expf(-x)); }
; __device__ __forceinline__ float siluf_(float x) { return x * __builtin_amdgcn_rcpf(1.f + __expf(-x)); }
; __device__ __forceinline__ u32x4 pack8(const f32x4 a, const f32x4 b) { u32x4 w; w.x = cvt_pk_bf16(a[0], a[1]); w.y = cvt_pk_bf16(a[2], a[3]); w.z = cvt_pk_bf16(b[0], b[1]); w.w = cvt_pk_bf16(b[2], b[3]); return w; }
;     __device__ __forceinline__ void operator()(const f32x4 (&acc)[2][2][4][2], const Unit& u, int wr, int wc, int fr, int fq) const {
;     ...
;             for (int ai = 0; ai < 2; ++ai)
; #pragma unroll
;                 for (int m = 0; m < 4; ++m) { const int r = row0 + ai * HALF + m * 16;
;                     f32x4 v0 = acc[ai][bj][m][0], v1 = acc[ai][bj][m][1];
;                     if (mode == 1) {
; #pragma unroll
;                         for (int i = 0; i < 4; ++i) { v0[i] = siluf_(v0[i]) * QSCALE; v1[i] = siluf_(v1[i]) * QSCALE; }
;                     } else if (mode == 2) {
; #pragma unroll
;                         for (int i = 0; i < 4; ++i) { v0[i] = __logf(lb[i] + (1.f - lb[i]) * sigmoidf_(v0[i])); v1[i] = __logf(lb[4 + i] + (1.f - lb[4 + i]) * sigmoidf_(v1[i])); }
;                     } else if (mode == 3) {
; #pragma unroll
;                         for (int i = 0; i < 4; ++i) { v0[i] = siluf_(v0[i]); v1[i] = siluf_(v1[i]); }
;                     }
;                     const u32x4 w = pack8(v0, v1);
;                     *(u32x4*)(base + ((size_t)((r >> 6) * 4 + h)) * 32768 + part * 8192 + (r & 63) * 128 + c8) = w;
.LBB0_712:
	v_lshlrev_b32_e32 v170, 1, v152
	v_mov_b32_e32 v171, v147
	v_cvt_pk_bf16_f32 v130, v130, v131
	v_cvt_pk_bf16_f32 v131, v132, v133
	v_cvt_pk_bf16_f32 v132, v134, v135
	v_cvt_pk_bf16_f32 v133, v136, v137
	v_lshl_add_u64 v[134:135], v[174:175], 0, v[170:171]
	s_and_b64 vcc, exec, s[8:9]
	s_mov_b64 s[66:67], -1
	global_store_dwordx4 v[134:135], v[130:133], off sc1
	s_cbranch_vccnz .LBB0_716
	v_mov_b64_e32 v[136:137], v[88:89]
	v_mov_b64_e32 v[132:133], v[96:97]
	s_and_b64 vcc, exec, s[6:7]
	v_mov_b64_e32 v[134:135], v[86:87]
	v_mov_b64_e32 v[130:131], v[94:95]
	s_cbranch_vccnz .LBB0_715
	v_mul_f32_e32 v131, 0xbfb8aa3b, v86
	v_mul_f32_e32 v132, 0xbfb8aa3b, v95
	v_exp_f32_e32 v131, v131
	v_exp_f32_e32 v132, v132
	v_mul_f32_e32 v133, 0xbfb8aa3b, v96
	v_mul_f32_e32 v135, 0xbfb8aa3b, v88
	v_add_f32_e32 v131, 1.0, v131
	v_rcp_f32_e32 v134, v131
	v_add_f32_e32 v131, 1.0, v132
	v_mul_f32_e32 v132, 0xbfb8aa3b, v87
	v_exp_f32_e32 v132, v132
	v_exp_f32_e32 v133, v133
	v_exp_f32_e32 v135, v135
	v_mul_f32_e32 v130, 0xbfb8aa3b, v94
	v_add_f32_e32 v166, 1.0, v132
	v_add_f32_e32 v132, 1.0, v133
	v_add_f32_e32 v133, 1.0, v135
	v_mul_f32_e32 v135, 0xbfb8aa3b, v97
	v_mul_f32_e32 v136, 0xbfb8aa3b, v89
	v_exp_f32_e32 v130, v130
	v_exp_f32_e32 v135, v135
	v_exp_f32_e32 v137, v136
	v_rcp_f32_e32 v136, v133
	v_add_f32_e32 v130, 1.0, v130
	v_add_f32_e32 v133, 1.0, v135
	v_add_f32_e32 v135, 1.0, v137
	v_rcp_f32_e32 v130, v130
	v_rcp_f32_e32 v131, v131
	v_rcp_f32_e32 v132, v132
	v_rcp_f32_e32 v133, v133
	v_rcp_f32_e32 v137, v135
	v_rcp_f32_e32 v135, v166
	v_pk_mul_f32 v[130:131], v[94:95], v[130:131]
	v_pk_mul_f32 v[132:133], v[96:97], v[132:133]
	v_pk_mul_f32 v[136:137], v[88:89], v[136:137]
	v_pk_mul_f32 v[134:135], v[86:87], v[134:135]

; __device__ __forceinline__ float sigmoidf_(float x) { return __builtin_amdgcn_rcpf(1.f + __expf(-x)); }
; __device__ __forceinline__ float siluf_(float x) { return x * __builtin_amdgcn_rcpf(1.f + __expf(-x)); }
; __device__ __forceinline__ u32x4 pack8(const f32x4 a, const f32x4 b) { u32x4 w; w.x = cvt_pk_bf16(a[0], a[1]); w.y = cvt_pk_bf16(a[2], a[3]); w.z = cvt_pk_bf16(b[0], b[1]); w.w = cvt_pk_bf16(b[2], b[3]); return w; }
;     __device__ __forceinline__ void operator()(const f32x4 (&acc)[2][2][4][2], const Unit& u, int wr, int wc, int fr, int fq) const {
;     ...
;             for (int ai = 0; ai < 2; ++ai)
; #pragma unroll
;                 for (int m = 0; m < 4; ++m) { const int r = row0 + ai * HALF + m * 16;
;                     f32x4 v0 = acc[ai][bj][m][0], v1 = acc[ai][bj][m][1];
;                     if (mode == 1) {
; #pragma unroll
;                         for (int i = 0; i < 4; ++i) { v0[i] = siluf_(v0[i]) * QSCALE; v1[i] = siluf_(v1[i]) * QSCALE; }
;                     } else if (mode == 2) {
; #pragma unroll
;                         for (int i = 0; i < 4; ++i) { v0[i] = __logf(lb[i] + (1.f - lb[i]) * sigmoidf_(v0[i])); v1[i] = __logf(lb[4 + i] + (1.f - lb[4 + i]) * sigmoidf_(v1[i])); }
;                     } else if (mode == 3) {
; #pragma unroll
;                         for (int i = 0; i < 4; ++i) { v0[i] = siluf_(v0[i]); v1[i] = siluf_(v1[i]); }
;                     }
;                     const u32x4 w = pack8(v0, v1);
;                     *(u32x4*)(base + ((size_t)((r >> 6) * 4 + h)) * 32768 + part * 8192 + (r & 63) * 128 + c8) = w;
.LBB0_718:
	v_lshlrev_b32_e32 v168, 1, v154
	v_mov_b32_e32 v169, v147
	v_cvt_pk_bf16_f32 v130, v130, v131
	v_cvt_pk_bf16_f32 v131, v132, v133
	v_cvt_pk_bf16_f32 v132, v134, v135
	v_cvt_pk_bf16_f32 v133, v136, v137
	v_lshl_add_u64 v[134:135], v[174:175], 0, v[168:169]
	s_and_b64 vcc, exec, s[8:9]
	s_mov_b64 s[66:67], -1
	global_store_dwordx4 v[134:135], v[130:133], off sc1
	s_cbranch_vccnz .LBB0_722
	v_mov_b64_e32 v[136:137], v[72:73]
	v_mov_b64_e32 v[132:133], v[80:81]
	s_and_b64 vcc, exec, s[6:7]
	v_mov_b64_e32 v[134:135], v[70:71]
	v_mov_b64_e32 v[130:131], v[78:79]
	s_cbranch_vccnz .LBB0_721
	v_mul_f32_e32 v131, 0xbfb8aa3b, v70
	v_mul_f32_e32 v132, 0xbfb8aa3b, v79
	v_exp_f32_e32 v131, v131
	v_exp_f32_e32 v132, v132
	v_mul_f32_e32 v133, 0xbfb8aa3b, v80
	v_mul_f32_e32 v135, 0xbfb8aa3b, v72
	v_add_f32_e32 v131, 1.0, v131
	v_rcp_f32_e32 v134, v131
	v_add_f32_e32 v131, 1.0, v132
	v_mul_f32_e32 v132, 0xbfb8aa3b, v71
	v_exp_f32_e32 v132, v132
	v_exp_f32_e32 v133, v133
	v_exp_f32_e32 v135, v135
	v_mul_f32_e32 v130, 0xbfb8aa3b, v78
	v_add_f32_e32 v166, 1.0, v132
	v_add_f32_e32 v132, 1.0, v133
	v_add_f32_e32 v133, 1.0, v135
	v_mul_f32_e32 v135, 0xbfb8aa3b, v81
	v_mul_f32_e32 v136, 0xbfb8aa3b, v73
	v_exp_f32_e32 v130, v130
	v_exp_f32_e32 v135, v135
	v_exp_f32_e32 v137, v136
	v_rcp_f32_e32 v136, v133
	v_add_f32_e32 v130, 1.0, v130
	v_add_f32_e32 v133, 1.0, v135
	v_add_f32_e32 v135, 1.0, v137
	v_rcp_f32_e32 v130, v130
	v_rcp_f32_e32 v131, v131
	v_rcp_f32_e32 v132, v132
	v_rcp_f32_e32 v133, v133
	v_rcp_f32_e32 v137, v135
	v_rcp_f32_e32 v135, v166
	v_pk_mul_f32 v[130:131], v[78:79], v[130:131]
	v_pk_mul_f32 v[132:133], v[80:81], v[132:133]
	v_pk_mul_f32 v[136:137], v[72:73], v[136:137]
	v_pk_mul_f32 v[134:135], v[70:71], v[134:135]

; __device__ __forceinline__ float sigmoidf_(float x) { return __builtin_amdgcn_rcpf(1.f + __expf(-x)); }
; __device__ __forceinline__ float siluf_(float x) { return x * __builtin_amdgcn_rcpf(1.f + __expf(-x)); }
; __device__ __forceinline__ u32x4 pack8(const f32x4 a, const f32x4 b) { u32x4 w; w.x = cvt_pk_bf16(a[0], a[1]); w.y = cvt_pk_bf16(a[2], a[3]); w.z = cvt_pk_bf16(b[0], b[1]); w.w = cvt_pk_bf16(b[2], b[3]); return w; }
;     __device__ __forceinline__ void operator()(const f32x4 (&acc)[2][2][4][2], const Unit& u, int wr, int wc, int fr, int fq) const {
;     ...
;             for (int ai = 0; ai < 2; ++ai)
; #pragma unroll
;                 for (int m = 0; m < 4; ++m) { const int r = row0 + ai * HALF + m * 16;
;                     f32x4 v0 = acc[ai][bj][m][0], v1 = acc[ai][bj][m][1];
;                     if (mode == 1) {
; #pragma unroll
;                         for (int i = 0; i < 4; ++i) { v0[i] = siluf_(v0[i]) * QSCALE; v1[i] = siluf_(v1[i]) * QSCALE; }
;                     } else if (mode == 2) {
; #pragma unroll
;                         for (int i = 0; i < 4; ++i) { v0[i] = __logf(lb[i] + (1.f - lb[i]) * sigmoidf_(v0[i])); v1[i] = __logf(lb[4 + i] + (1.f - lb[4 + i]) * sigmoidf_(v1[i])); }
;                     } else if (mode == 3) {
; #pragma unroll
;                         for (int i = 0; i < 4; ++i) { v0[i] = siluf_(v0[i]); v1[i] = siluf_(v1[i]); }
;                     }
;                     const u32x4 w = pack8(v0, v1);
;                     *(u32x4*)(base + ((size_t)((r >> 6) * 4 + h)) * 32768 + part * 8192 + (r & 63) * 128 + c8) = w;
;                     if (grp == 1 && part < 3 && m == 3 && fr >= 13) *(u32x4*)(halo + (size_t)(r >> 6) * 4608 + (fr - 13) * 1536 + h * 384 + part * 128 + c8) = w;
.LBB0_724:
	s_cmp_gt_i32 s71, 7
	s_cselect_b64 s[86:87], -1, 0
	s_ashr_i32 s46, s77, 6
	s_and_b64 s[66:67], s[86:87], s[94:95]
	s_mul_i32 s94, s79, 0x180
	s_mul_hi_i32 vcc_hi, s46, 0x2400
	s_mul_i32 vcc_lo, s46, 0x2400
	v_lshlrev_b32_e32 v166, 1, v156
	v_mov_b32_e32 v167, v147
	s_ashr_i32 s95, s94, 31
	s_lshl_b32 s4, s4, 7
	v_cvt_pk_bf16_f32 v130, v130, v131
	v_cvt_pk_bf16_f32 v131, v132, v133
	v_cvt_pk_bf16_f32 v132, v134, v135
	v_cvt_pk_bf16_f32 v133, v136, v137
	v_lshl_add_u64 v[134:135], v[174:175], 0, v[166:167]
	s_and_b64 s[96:97], s[66:67], s[0:1]
	v_lshl_add_u64 v[174:175], v[158:159], 0, vcc
	global_store_dwordx4 v[134:135], v[130:133], off sc1
	s_and_saveexec_b64 s[66:67], s[96:97]
	s_cbranch_execz .LBB0_726
	v_lshl_add_u64 v[134:135], s[94:95], 1, v[174:175]
	s_lshl_b32 s68, s4, 1
	v_lshl_add_u64 v[134:135], v[134:135], 0, s[68:69]
	v_lshl_add_u64 v[134:135], v[134:135], 0, v[146:147]
	v_add_co_u32_e32 v134, vcc, 0xffff7000, v134
	s_nop 1
	v_addc_co_u32_e32 v135, vcc, -1, v135, vcc
	global_store_dwordx4 v[134:135], v[130:133], off offset:-3072 sc1

; __device__ __forceinline__ float sigmoidf_(float x) { return __builtin_amdgcn_rcpf(1.f + __expf(-x)); }
; __device__ __forceinline__ float siluf_(float x) { return x * __builtin_amdgcn_rcpf(1.f + __expf(-x)); }
; __device__ __forceinline__ u32x4 pack8(const f32x4 a, const f32x4 b) { u32x4 w; w.x = cvt_pk_bf16(a[0], a[1]); w.y = cvt_pk_bf16(a[2], a[3]); w.z = cvt_pk_bf16(b[0], b[1]); w.w = cvt_pk_bf16(b[2], b[3]); return w; }
;     __device__ __forceinline__ void operator()(const f32x4 (&acc)[2][2][4][2], const Unit& u, int wr, int wc, int fr, int fq) const {
;     ...
;             for (int ai = 0; ai < 2; ++ai)
; #pragma unroll
;                 for (int m = 0; m < 4; ++m) { const int r = row0 + ai * HALF + m * 16;
;                     f32x4 v0 = acc[ai][bj][m][0], v1 = acc[ai][bj][m][1];
;                     if (mode == 1) {
; #pragma unroll
;                         for (int i = 0; i < 4; ++i) { v0[i] = siluf_(v0[i]) * QSCALE; v1[i] = siluf_(v1[i]) * QSCALE; }
;                     } else if (mode == 2) {
; #pragma unroll
;                         for (int i = 0; i < 4; ++i) { v0[i] = __logf(lb[i] + (1.f - lb[i]) * sigmoidf_(v0[i])); v1[i] = __logf(lb[4 + i] + (1.f - lb[4 + i]) * sigmoidf_(v1[i])); }
;                     } else if (mode == 3) {
; #pragma unroll
;                         for (int i = 0; i < 4; ++i) { v0[i] = siluf_(v0[i]); v1[i] = siluf_(v1[i]); }
;                     }
;                     const u32x4 w = pack8(v0, v1);
;                     *(u32x4*)(base + ((size_t)((r >> 6) * 4 + h)) * 32768 + part * 8192 + (r & 63) * 128 + c8) = w;
.LBB0_732:
	s_add_i32 s68, s77, 0x80
	s_ashr_i32 s46, s68, 4
	s_add_i32 s66, s79, s46
	s_ashr_i32 s67, s66, 31
	s_lshl_b64 s[66:67], s[66:67], 16
	v_lshl_add_u64 v[178:179], v[178:179], 0, s[66:67]
	v_mov_b32_e32 v173, v147
	v_cvt_pk_bf16_f32 v130, v130, v131
	v_cvt_pk_bf16_f32 v131, v132, v133
	v_cvt_pk_bf16_f32 v132, v134, v135
	v_cvt_pk_bf16_f32 v133, v136, v137
	v_lshl_add_u64 v[134:135], v[178:179], 0, v[172:173]
	s_and_b64 vcc, exec, s[8:9]
	s_mov_b64 s[66:67], -1
	global_store_dwordx4 v[134:135], v[130:133], off sc1
	s_cbranch_vccnz .LBB0_736
	v_mov_b64_e32 v[136:137], v[40:41]
	v_mov_b64_e32 v[132:133], v[48:49]
	s_and_b64 vcc, exec, s[6:7]
	v_mov_b64_e32 v[134:135], v[38:39]
	v_mov_b64_e32 v[130:131], v[46:47]
	s_cbranch_vccnz .LBB0_735
	v_mul_f32_e32 v131, 0xbfb8aa3b, v38
	v_mul_f32_e32 v132, 0xbfb8aa3b, v47
	v_exp_f32_e32 v131, v131
	v_exp_f32_e32 v132, v132
	v_mul_f32_e32 v133, 0xbfb8aa3b, v48
	v_mul_f32_e32 v135, 0xbfb8aa3b, v40
	v_add_f32_e32 v131, 1.0, v131
	v_rcp_f32_e32 v134, v131
	v_add_f32_e32 v131, 1.0, v132
	v_mul_f32_e32 v132, 0xbfb8aa3b, v39
	v_exp_f32_e32 v132, v132
	v_exp_f32_e32 v133, v133
	v_exp_f32_e32 v135, v135
	v_mul_f32_e32 v130, 0xbfb8aa3b, v46
	v_add_f32_e32 v167, 1.0, v132
	v_add_f32_e32 v132, 1.0, v133
	v_add_f32_e32 v133, 1.0, v135
	v_mul_f32_e32 v135, 0xbfb8aa3b, v49
	v_mul_f32_e32 v136, 0xbfb8aa3b, v41
	v_exp_f32_e32 v130, v130
	v_exp_f32_e32 v135, v135
	v_exp_f32_e32 v137, v136
	v_rcp_f32_e32 v136, v133
	v_add_f32_e32 v130, 1.0, v130
	v_add_f32_e32 v133, 1.0, v135
	v_add_f32_e32 v135, 1.0, v137
	v_rcp_f32_e32 v130, v130
	v_rcp_f32_e32 v131, v131
	v_rcp_f32_e32 v132, v132
	v_rcp_f32_e32 v133, v133
	v_rcp_f32_e32 v137, v135
	v_rcp_f32_e32 v135, v167
	v_pk_mul_f32 v[130:131], v[46:47], v[130:131]
	v_pk_mul_f32 v[132:133], v[48:49], v[132:133]
	v_pk_mul_f32 v[136:137], v[40:41], v[136:137]
	v_pk_mul_f32 v[134:135], v[38:39], v[134:135]

; __device__ __forceinline__ float sigmoidf_(float x) { return __builtin_amdgcn_rcpf(1.f + __expf(-x)); }
; __device__ __forceinline__ float siluf_(float x) { return x * __builtin_amdgcn_rcpf(1.f + __expf(-x)); }
; __device__ __forceinline__ u32x4 pack8(const f32x4 a, const f32x4 b) { u32x4 w; w.x = cvt_pk_bf16(a[0], a[1]); w.y = cvt_pk_bf16(a[2], a[3]); w.z = cvt_pk_bf16(b[0], b[1]); w.w = cvt_pk_bf16(b[2], b[3]); return w; }
;     __device__ __forceinline__ void operator()(const f32x4 (&acc)[2][2][4][2], const Unit& u, int wr, int wc, int fr, int fq) const {
;     ...
;             for (int ai = 0; ai < 2; ++ai)
; #pragma unroll
;                 for (int m = 0; m < 4; ++m) { const int r = row0 + ai * HALF + m * 16;
;                     f32x4 v0 = acc[ai][bj][m][0], v1 = acc[ai][bj][m][1];
;                     if (mode == 1) {
; #pragma unroll
;                         for (int i = 0; i < 4; ++i) { v0[i] = siluf_(v0[i]) * QSCALE; v1[i] = siluf_(v1[i]) * QSCALE; }
;                     } else if (mode == 2) {
; #pragma unroll
;                         for (int i = 0; i < 4; ++i) { v0[i] = __logf(lb[i] + (1.f - lb[i]) * sigmoidf_(v0[i])); v1[i] = __logf(lb[4 + i] + (1.f - lb[4 + i]) * sigmoidf_(v1[i])); }
;                     } else if (mode == 3) {
; #pragma unroll
;                         for (int i = 0; i < 4; ++i) { v0[i] = siluf_(v0[i]); v1[i] = siluf_(v1[i]); }
;                     }
;                     const u32x4 w = pack8(v0, v1);
;                     *(u32x4*)(base + ((size_t)((r >> 6) * 4 + h)) * 32768 + part * 8192 + (r & 63) * 128 + c8) = w;
.LBB0_738:
	v_mov_b32_e32 v171, v147
	v_cvt_pk_bf16_f32 v130, v130, v131
	v_cvt_pk_bf16_f32 v131, v132, v133
	v_cvt_pk_bf16_f32 v132, v134, v135
	v_cvt_pk_bf16_f32 v133, v136, v137
	v_lshl_add_u64 v[134:135], v[178:179], 0, v[170:171]
	s_and_b64 vcc, exec, s[8:9]
	s_mov_b64 s[66:67], -1
	global_store_dwordx4 v[134:135], v[130:133], off sc1
	s_cbranch_vccnz .LBB0_742
	v_mov_b64_e32 v[136:137], v[24:25]
	v_mov_b64_e32 v[132:133], v[32:33]
	s_and_b64 vcc, exec, s[6:7]
	v_mov_b64_e32 v[134:135], v[22:23]
	v_mov_b64_e32 v[130:131], v[30:31]
	s_cbranch_vccnz .LBB0_741
	v_mul_f32_e32 v131, 0xbfb8aa3b, v22
	v_mul_f32_e32 v132, 0xbfb8aa3b, v31
	v_exp_f32_e32 v131, v131
	v_exp_f32_e32 v132, v132
	v_mul_f32_e32 v133, 0xbfb8aa3b, v32
	v_mul_f32_e32 v135, 0xbfb8aa3b, v24
	v_add_f32_e32 v131, 1.0, v131
	v_rcp_f32_e32 v134, v131
	v_add_f32_e32 v131, 1.0, v132
	v_mul_f32_e32 v132, 0xbfb8aa3b, v23
	v_exp_f32_e32 v132, v132
	v_exp_f32_e32 v133, v133
	v_exp_f32_e32 v135, v135
	v_mul_f32_e32 v130, 0xbfb8aa3b, v30
	v_add_f32_e32 v167, 1.0, v132
	v_add_f32_e32 v132, 1.0, v133
	v_add_f32_e32 v133, 1.0, v135
	v_mul_f32_e32 v135, 0xbfb8aa3b, v33
	v_mul_f32_e32 v136, 0xbfb8aa3b, v25
	v_exp_f32_e32 v130, v130
	v_exp_f32_e32 v135, v135
	v_exp_f32_e32 v137, v136
	v_rcp_f32_e32 v136, v133
	v_add_f32_e32 v130, 1.0, v130
	v_add_f32_e32 v133, 1.0, v135
	v_add_f32_e32 v135, 1.0, v137
	v_rcp_f32_e32 v130, v130
	v_rcp_f32_e32 v131, v131
	v_rcp_f32_e32 v132, v132
	v_rcp_f32_e32 v133, v133
	v_rcp_f32_e32 v137, v135
	v_rcp_f32_e32 v135, v167
	v_pk_mul_f32 v[130:131], v[30:31], v[130:131]
	v_pk_mul_f32 v[132:133], v[32:33], v[132:133]
	v_pk_mul_f32 v[136:137], v[24:25], v[136:137]
	v_pk_mul_f32 v[134:135], v[22:23], v[134:135]

; __device__ __forceinline__ float sigmoidf_(float x) { return __builtin_amdgcn_rcpf(1.f + __expf(-x)); }
; __device__ __forceinline__ float siluf_(float x) { return x * __builtin_amdgcn_rcpf(1.f + __expf(-x)); }
; __device__ __forceinline__ u32x4 pack8(const f32x4 a, const f32x4 b) { u32x4 w; w.x = cvt_pk_bf16(a[0], a[1]); w.y = cvt_pk_bf16(a[2], a[3]); w.z = cvt_pk_bf16(b[0], b[1]); w.w = cvt_pk_bf16(b[2], b[3]); return w; }
;     __device__ __forceinline__ void operator()(const f32x4 (&acc)[2][2][4][2], const Unit& u, int wr, int wc, int fr, int fq) const {
;     ...
;             for (int ai = 0; ai < 2; ++ai)
; #pragma unroll
;                 for (int m = 0; m < 4; ++m) { const int r = row0 + ai * HALF + m * 16;
;                     f32x4 v0 = acc[ai][bj][m][0], v1 = acc[ai][bj][m][1];
;                     if (mode == 1) {
; #pragma unroll
;                         for (int i = 0; i < 4; ++i) { v0[i] = siluf_(v0[i]) * QSCALE; v1[i] = siluf_(v1[i]) * QSCALE; }
;                     } else if (mode == 2) {
; #pragma unroll
;                         for (int i = 0; i < 4; ++i) { v0[i] = __logf(lb[i] + (1.f - lb[i]) * sigmoidf_(v0[i])); v1[i] = __logf(lb[4 + i] + (1.f - lb[4 + i]) * sigmoidf_(v1[i])); }
;                     } else if (mode == 3) {
; #pragma unroll
;                         for (int i = 0; i < 4; ++i) { v0[i] = siluf_(v0[i]); v1[i] = siluf_(v1[i]); }
;                     }
;                     const u32x4 w = pack8(v0, v1);
;                     *(u32x4*)(base + ((size_t)((r >> 6) * 4 + h)) * 32768 + part * 8192 + (r & 63) * 128 + c8) = w;
.LBB0_744:
	v_mov_b32_e32 v169, v147
	v_cvt_pk_bf16_f32 v130, v130, v131
	v_cvt_pk_bf16_f32 v131, v132, v133
	v_cvt_pk_bf16_f32 v132, v134, v135
	v_cvt_pk_bf16_f32 v133, v136, v137
	v_lshl_add_u64 v[134:135], v[178:179], 0, v[168:169]
	s_and_b64 vcc, exec, s[8:9]
	s_mov_b64 s[8:9], -1
	global_store_dwordx4 v[134:135], v[130:133], off sc1
	s_cbranch_vccnz .LBB0_748
	v_mov_b64_e32 v[136:137], v[8:9]
	v_mov_b64_e32 v[132:133], v[16:17]
	s_and_b64 vcc, exec, s[6:7]
	v_mov_b64_e32 v[134:135], v[6:7]
	v_mov_b64_e32 v[130:131], v[14:15]
	s_cbranch_vccnz .LBB0_747
	v_mul_f32_e32 v131, 0xbfb8aa3b, v6
	v_mul_f32_e32 v132, 0xbfb8aa3b, v15
	v_exp_f32_e32 v131, v131
	v_exp_f32_e32 v132, v132
	v_mul_f32_e32 v133, 0xbfb8aa3b, v16
	v_mul_f32_e32 v135, 0xbfb8aa3b, v8
	v_add_f32_e32 v131, 1.0, v131
	v_rcp_f32_e32 v134, v131
	v_add_f32_e32 v131, 1.0, v132
	v_mul_f32_e32 v132, 0xbfb8aa3b, v7
	v_exp_f32_e32 v132, v132
	v_exp_f32_e32 v133, v133
	v_exp_f32_e32 v135, v135
	v_mul_f32_e32 v130, 0xbfb8aa3b, v14
	v_add_f32_e32 v167, 1.0, v132
	v_add_f32_e32 v132, 1.0, v133
	v_add_f32_e32 v133, 1.0, v135
	v_mul_f32_e32 v135, 0xbfb8aa3b, v17
	v_mul_f32_e32 v136, 0xbfb8aa3b, v9
	v_exp_f32_e32 v130, v130
	v_exp_f32_e32 v135, v135
	v_exp_f32_e32 v137, v136
	v_rcp_f32_e32 v136, v133
	v_add_f32_e32 v130, 1.0, v130
	v_add_f32_e32 v133, 1.0, v135
	v_add_f32_e32 v135, 1.0, v137
	v_rcp_f32_e32 v130, v130
	v_rcp_f32_e32 v131, v131
	v_rcp_f32_e32 v132, v132
	v_rcp_f32_e32 v133, v133
	v_rcp_f32_e32 v137, v135
	v_rcp_f32_e32 v135, v167
	v_pk_mul_f32 v[130:131], v[14:15], v[130:131]
	v_pk_mul_f32 v[132:133], v[16:17], v[132:133]
	v_pk_mul_f32 v[136:137], v[8:9], v[136:137]
	v_pk_mul_f32 v[134:135], v[6:7], v[134:135]

; __device__ __forceinline__ float sigmoidf_(float x) { return __builtin_amdgcn_rcpf(1.f + __expf(-x)); }
; __device__ __forceinline__ float siluf_(float x) { return x * __builtin_amdgcn_rcpf(1.f + __expf(-x)); }
; __device__ __forceinline__ u32x4 pack8(const f32x4 a, const f32x4 b) { u32x4 w; w.x = cvt_pk_bf16(a[0], a[1]); w.y = cvt_pk_bf16(a[2], a[3]); w.z = cvt_pk_bf16(b[0], b[1]); w.w = cvt_pk_bf16(b[2], b[3]); return w; }
;     __device__ __forceinline__ void operator()(const f32x4 (&acc)[2][2][4][2], const Unit& u, int wr, int wc, int fr, int fq) const {
;     ...
;             for (int ai = 0; ai < 2; ++ai)
; #pragma unroll
;                 for (int m = 0; m < 4; ++m) { const int r = row0 + ai * HALF + m * 16;
;                     f32x4 v0 = acc[ai][bj][m][0], v1 = acc[ai][bj][m][1];
;                     if (mode == 1) {
; #pragma unroll
;                         for (int i = 0; i < 4; ++i) { v0[i] = siluf_(v0[i]) * QSCALE; v1[i] = siluf_(v1[i]) * QSCALE; }
;                     } else if (mode == 2) {
; #pragma unroll
;                         for (int i = 0; i < 4; ++i) { v0[i] = __logf(lb[i] + (1.f - lb[i]) * sigmoidf_(v0[i])); v1[i] = __logf(lb[4 + i] + (1.f - lb[4 + i]) * sigmoidf_(v1[i])); }
;                     } else if (mode == 3) {
; #pragma unroll
;                         for (int i = 0; i < 4; ++i) { v0[i] = siluf_(v0[i]); v1[i] = siluf_(v1[i]); }
;                     }
;                     const u32x4 w = pack8(v0, v1);
;                     *(u32x4*)(base + ((size_t)((r >> 6) * 4 + h)) * 32768 + part * 8192 + (r & 63) * 128 + c8) = w;
;                     if (grp == 1 && part < 3 && m == 3 && fr >= 13) *(u32x4*)(halo + (size_t)(r >> 6) * 4608 + (fr - 13) * 1536 + h * 384 + part * 128 + c8) = w;
.LBB0_750:
	s_ashr_i32 s6, s68, 6
	v_mov_b32_e32 v167, v147
	s_mul_hi_i32 s7, s6, 0x2400
	s_mulk_i32 s6, 0x2400
	v_cvt_pk_bf16_f32 v130, v130, v131
	v_cvt_pk_bf16_f32 v131, v132, v133
	v_cvt_pk_bf16_f32 v132, v134, v135
	v_cvt_pk_bf16_f32 v133, v136, v137
	v_lshl_add_u64 v[134:135], v[178:179], 0, v[166:167]
	global_store_dwordx4 v[134:135], v[130:133], off sc1
	v_lshl_add_u64 v[134:135], v[158:159], 0, s[6:7]
	s_and_saveexec_b64 s[6:7], s[96:97]
	s_cbranch_execz .LBB0_752
	v_lshl_add_u64 v[136:137], s[94:95], 1, v[134:135]
	s_lshl_b32 s68, s4, 1
	v_lshl_add_u64 v[136:137], v[136:137], 0, s[68:69]
	v_lshl_add_u64 v[136:137], v[136:137], 0, v[146:147]
	v_add_co_u32_e32 v136, vcc, 0xffff7000, v136
	s_nop 1
	v_addc_co_u32_e32 v137, vcc, -1, v137, vcc
	global_store_dwordx4 v[136:137], v[130:133], off offset:-3072 sc1

; __device__ __forceinline__ float sigmoidf_(float x) { return __builtin_amdgcn_rcpf(1.f + __expf(-x)); }
; __device__ __forceinline__ float siluf_(float x) { return x * __builtin_amdgcn_rcpf(1.f + __expf(-x)); }
; __device__ __forceinline__ u32x4 pack8(const f32x4 a, const f32x4 b) { u32x4 w; w.x = cvt_pk_bf16(a[0], a[1]); w.y = cvt_pk_bf16(a[2], a[3]); w.z = cvt_pk_bf16(b[0], b[1]); w.w = cvt_pk_bf16(b[2], b[3]); return w; }
;     __device__ __forceinline__ void operator()(const f32x4 (&acc)[2][2][4][2], const Unit& u, int wr, int wc, int fr, int fq) const {
;     ...
;             for (int ai = 0; ai < 2; ++ai)
; #pragma unroll
;                 for (int m = 0; m < 4; ++m) { const int r = row0 + ai * HALF + m * 16;
;                     f32x4 v0 = acc[ai][bj][m][0], v1 = acc[ai][bj][m][1];
;                     if (mode == 1) {
; #pragma unroll
;                         for (int i = 0; i < 4; ++i) { v0[i] = siluf_(v0[i]) * QSCALE; v1[i] = siluf_(v1[i]) * QSCALE; }
;                     } else if (mode == 2) {
; #pragma unroll
;                         for (int i = 0; i < 4; ++i) { v0[i] = __logf(lb[i] + (1.f - lb[i]) * sigmoidf_(v0[i])); v1[i] = __logf(lb[4 + i] + (1.f - lb[4 + i]) * sigmoidf_(v1[i])); }
;                     } else if (mode == 3) {
; #pragma unroll
;                         for (int i = 0; i < 4; ++i) { v0[i] = siluf_(v0[i]); v1[i] = siluf_(v1[i]); }
;                     }
;                     const u32x4 w = pack8(v0, v1);
;                     *(u32x4*)(base + ((size_t)((r >> 6) * 4 + h)) * 32768 + part * 8192 + (r & 63) * 128 + c8) = w;
.LBB0_767:
	s_add_i32 s10, s3, s33
	s_lshl_b32 s68, s66, 14
	s_ashr_i32 s11, s10, 31
	v_lshl_add_u64 v[136:137], v[176:177], 0, s[68:69]
	s_lshl_b64 s[10:11], s[10:11], 16
	v_lshl_add_u64 v[176:177], v[136:137], 0, s[10:11]
	v_mov_b32_e32 v173, v147
	v_cvt_pk_bf16_f32 v130, v130, v131
	v_cvt_pk_bf16_f32 v131, v178, v179
	v_cvt_pk_bf16_f32 v132, v132, v133
	v_cvt_pk_bf16_f32 v133, v180, v181
	v_lshl_add_u64 v[178:179], v[176:177], 0, v[172:173]
	s_and_b64 vcc, exec, s[8:9]
	s_mov_b64 s[10:11], -1
	global_store_dwordx4 v[178:179], v[130:133], off sc1
	s_cbranch_vccnz .LBB0_771
	s_and_b64 vcc, exec, s[6:7]
	v_mov_b32_e32 v181, v101
	v_mov_b32_e32 v180, v100
	v_mov_b32_e32 v133, v99
	v_mov_b32_e32 v132, v98
	v_mov_b32_e32 v179, v109
	v_mov_b32_e32 v178, v108
	v_mov_b32_e32 v131, v107
	v_mov_b32_e32 v130, v106
	s_cbranch_vccnz .LBB0_770
	v_mul_f32_e32 v167, 0xbfb8aa3b, v108
	v_mul_f32_e32 v131, 0xbfb8aa3b, v98
	v_exp_f32_e32 v167, v167
	v_mul_f32_e32 v169, 0xbfb8aa3b, v100
	v_mul_f32_e32 v132, 0xbfb8aa3b, v107
	v_exp_f32_e32 v131, v131
	v_exp_f32_e32 v169, v169
	v_exp_f32_e32 v133, v132
	v_add_f32_e32 v167, 1.0, v167
	v_add_f32_e32 v131, 1.0, v131
	v_rcp_f32_e32 v178, v167
	v_add_f32_e32 v167, 1.0, v169
	v_mul_f32_e32 v169, 0xbfb8aa3b, v109
	v_mul_f32_e32 v130, 0xbfb8aa3b, v106
	v_rcp_f32_e32 v132, v131
	v_add_f32_e32 v131, 1.0, v133
	v_mul_f32_e32 v133, 0xbfb8aa3b, v99
	v_exp_f32_e32 v169, v169
	v_mul_f32_e32 v171, 0xbfb8aa3b, v101
	v_exp_f32_e32 v130, v130
	v_exp_f32_e32 v133, v133
	v_exp_f32_e32 v171, v171
	v_rcp_f32_e32 v180, v167
	v_add_f32_e32 v167, 1.0, v169
	v_add_f32_e32 v130, 1.0, v130
	v_add_f32_e32 v133, 1.0, v133
	v_rcp_f32_e32 v179, v167
	v_add_f32_e32 v167, 1.0, v171
	v_rcp_f32_e32 v130, v130
	v_rcp_f32_e32 v131, v131
	v_rcp_f32_e32 v181, v167
	v_rcp_f32_e32 v133, v133
	v_pk_mul_f32 v[178:179], v[108:109], v[178:179]
	v_pk_mul_f32 v[130:131], v[106:107], v[130:131]
	v_pk_mul_f32 v[180:181], v[100:101], v[180:181]
	v_pk_mul_f32 v[132:133], v[98:99], v[132:133]

; __device__ __forceinline__ float sigmoidf_(float x) { return __builtin_amdgcn_rcpf(1.f + __expf(-x)); }
; __device__ __forceinline__ float siluf_(float x) { return x * __builtin_amdgcn_rcpf(1.f + __expf(-x)); }
; __device__ __forceinline__ u32x4 pack8(const f32x4 a, const f32x4 b) { u32x4 w; w.x = cvt_pk_bf16(a[0], a[1]); w.y = cvt_pk_bf16(a[2], a[3]); w.z = cvt_pk_bf16(b[0], b[1]); w.w = cvt_pk_bf16(b[2], b[3]); return w; }
;     __device__ __forceinline__ void operator()(const f32x4 (&acc)[2][2][4][2], const Unit& u, int wr, int wc, int fr, int fq) const {
;     ...
;             for (int ai = 0; ai < 2; ++ai)
; #pragma unroll
;                 for (int m = 0; m < 4; ++m) { const int r = row0 + ai * HALF + m * 16;
;                     f32x4 v0 = acc[ai][bj][m][0], v1 = acc[ai][bj][m][1];
;                     if (mode == 1) {
; #pragma unroll
;                         for (int i = 0; i < 4; ++i) { v0[i] = siluf_(v0[i]) * QSCALE; v1[i] = siluf_(v1[i]) * QSCALE; }
;                     } else if (mode == 2) {
; #pragma unroll
;                         for (int i = 0; i < 4; ++i) { v0[i] = __logf(lb[i] + (1.f - lb[i]) * sigmoidf_(v0[i])); v1[i] = __logf(lb[4 + i] + (1.f - lb[4 + i]) * sigmoidf_(v1[i])); }
;                     } else if (mode == 3) {
; #pragma unroll
;                         for (int i = 0; i < 4; ++i) { v0[i] = siluf_(v0[i]); v1[i] = siluf_(v1[i]); }
;                     }
;                     const u32x4 w = pack8(v0, v1);
;                     *(u32x4*)(base + ((size_t)((r >> 6) * 4 + h)) * 32768 + part * 8192 + (r & 63) * 128 + c8) = w;
.LBB0_773:
	v_mov_b32_e32 v171, v147
	v_cvt_pk_bf16_f32 v130, v130, v131
	v_cvt_pk_bf16_f32 v131, v178, v179
	v_cvt_pk_bf16_f32 v132, v132, v133
	v_cvt_pk_bf16_f32 v133, v180, v181
	v_lshl_add_u64 v[178:179], v[176:177], 0, v[170:171]
	s_and_b64 vcc, exec, s[8:9]
	s_mov_b64 s[10:11], -1
	global_store_dwordx4 v[178:179], v[130:133], off sc1
	s_cbranch_vccnz .LBB0_777
	s_and_b64 vcc, exec, s[6:7]
	v_mov_b32_e32 v181, v85
	v_mov_b32_e32 v180, v84
	v_mov_b32_e32 v133, v83
	v_mov_b32_e32 v132, v82
	v_mov_b32_e32 v179, v93
	v_mov_b32_e32 v178, v92
	v_mov_b32_e32 v131, v91
	v_mov_b32_e32 v130, v90
	s_cbranch_vccnz .LBB0_776
	v_mul_f32_e32 v167, 0xbfb8aa3b, v92
	v_mul_f32_e32 v131, 0xbfb8aa3b, v82
	v_exp_f32_e32 v167, v167
	v_mul_f32_e32 v169, 0xbfb8aa3b, v84
	v_mul_f32_e32 v132, 0xbfb8aa3b, v91
	v_exp_f32_e32 v131, v131
	v_exp_f32_e32 v169, v169
	v_exp_f32_e32 v133, v132
	v_add_f32_e32 v167, 1.0, v167
	v_add_f32_e32 v131, 1.0, v131
	v_rcp_f32_e32 v178, v167
	v_add_f32_e32 v167, 1.0, v169
	v_mul_f32_e32 v169, 0xbfb8aa3b, v93
	v_mul_f32_e32 v130, 0xbfb8aa3b, v90
	v_rcp_f32_e32 v132, v131
	v_add_f32_e32 v131, 1.0, v133
	v_mul_f32_e32 v133, 0xbfb8aa3b, v83
	v_exp_f32_e32 v169, v169
	v_mul_f32_e32 v171, 0xbfb8aa3b, v85
	v_exp_f32_e32 v130, v130
	v_exp_f32_e32 v133, v133
	v_exp_f32_e32 v171, v171
	v_rcp_f32_e32 v180, v167
	v_add_f32_e32 v167, 1.0, v169
	v_add_f32_e32 v130, 1.0, v130
	v_add_f32_e32 v133, 1.0, v133
	v_rcp_f32_e32 v179, v167
	v_add_f32_e32 v167, 1.0, v171
	v_rcp_f32_e32 v130, v130
	v_rcp_f32_e32 v131, v131
	v_rcp_f32_e32 v181, v167
	v_rcp_f32_e32 v133, v133
	v_pk_mul_f32 v[178:179], v[92:93], v[178:179]
	v_pk_mul_f32 v[130:131], v[90:91], v[130:131]
	v_pk_mul_f32 v[180:181], v[84:85], v[180:181]
	v_pk_mul_f32 v[132:133], v[82:83], v[132:133]

; __device__ __forceinline__ float sigmoidf_(float x) { return __builtin_amdgcn_rcpf(1.f + __expf(-x)); }
; __device__ __forceinline__ float siluf_(float x) { return x * __builtin_amdgcn_rcpf(1.f + __expf(-x)); }
; __device__ __forceinline__ u32x4 pack8(const f32x4 a, const f32x4 b) { u32x4 w; w.x = cvt_pk_bf16(a[0], a[1]); w.y = cvt_pk_bf16(a[2], a[3]); w.z = cvt_pk_bf16(b[0], b[1]); w.w = cvt_pk_bf16(b[2], b[3]); return w; }
;     __device__ __forceinline__ void operator()(const f32x4 (&acc)[2][2][4][2], const Unit& u, int wr, int wc, int fr, int fq) const {
;     ...
;             for (int ai = 0; ai < 2; ++ai)
; #pragma unroll
;                 for (int m = 0; m < 4; ++m) { const int r = row0 + ai * HALF + m * 16;
;                     f32x4 v0 = acc[ai][bj][m][0], v1 = acc[ai][bj][m][1];
;                     if (mode == 1) {
; #pragma unroll
;                         for (int i = 0; i < 4; ++i) { v0[i] = siluf_(v0[i]) * QSCALE; v1[i] = siluf_(v1[i]) * QSCALE; }
;                     } else if (mode == 2) {
; #pragma unroll
;                         for (int i = 0; i < 4; ++i) { v0[i] = __logf(lb[i] + (1.f - lb[i]) * sigmoidf_(v0[i])); v1[i] = __logf(lb[4 + i] + (1.f - lb[4 + i]) * sigmoidf_(v1[i])); }
;                     } else if (mode == 3) {
; #pragma unroll
;                         for (int i = 0; i < 4; ++i) { v0[i] = siluf_(v0[i]); v1[i] = siluf_(v1[i]); }
;                     }
;                     const u32x4 w = pack8(v0, v1);
;                     *(u32x4*)(base + ((size_t)((r >> 6) * 4 + h)) * 32768 + part * 8192 + (r & 63) * 128 + c8) = w;
.LBB0_779:
	v_mov_b32_e32 v169, v147
	v_cvt_pk_bf16_f32 v130, v130, v131
	v_cvt_pk_bf16_f32 v131, v178, v179
	v_cvt_pk_bf16_f32 v132, v132, v133
	v_cvt_pk_bf16_f32 v133, v180, v181
	v_lshl_add_u64 v[178:179], v[176:177], 0, v[168:169]
	s_and_b64 vcc, exec, s[8:9]
	s_mov_b64 s[10:11], -1
	global_store_dwordx4 v[178:179], v[130:133], off sc1
	s_cbranch_vccnz .LBB0_783
	s_and_b64 vcc, exec, s[6:7]
	v_mov_b32_e32 v181, v69
	v_mov_b32_e32 v180, v68
	v_mov_b32_e32 v133, v67
	v_mov_b32_e32 v132, v66
	v_mov_b32_e32 v179, v77
	v_mov_b32_e32 v178, v76
	v_mov_b32_e32 v131, v75
	v_mov_b32_e32 v130, v74
	s_cbranch_vccnz .LBB0_782
	v_mul_f32_e32 v167, 0xbfb8aa3b, v76
	v_mul_f32_e32 v131, 0xbfb8aa3b, v66
	v_exp_f32_e32 v167, v167
	v_mul_f32_e32 v169, 0xbfb8aa3b, v68
	v_mul_f32_e32 v132, 0xbfb8aa3b, v75
	v_exp_f32_e32 v131, v131
	v_exp_f32_e32 v169, v169
	v_exp_f32_e32 v133, v132
	v_add_f32_e32 v167, 1.0, v167
	v_add_f32_e32 v131, 1.0, v131
	v_rcp_f32_e32 v178, v167
	v_add_f32_e32 v167, 1.0, v169
	v_mul_f32_e32 v169, 0xbfb8aa3b, v77
	v_mul_f32_e32 v130, 0xbfb8aa3b, v74
	v_rcp_f32_e32 v132, v131
	v_add_f32_e32 v131, 1.0, v133
	v_mul_f32_e32 v133, 0xbfb8aa3b, v67
	v_exp_f32_e32 v169, v169
	v_mul_f32_e32 v171, 0xbfb8aa3b, v69
	v_exp_f32_e32 v130, v130
	v_exp_f32_e32 v133, v133
	v_exp_f32_e32 v171, v171
	v_rcp_f32_e32 v180, v167
	v_add_f32_e32 v167, 1.0, v169
	v_add_f32_e32 v130, 1.0, v130
	v_add_f32_e32 v133, 1.0, v133
	v_rcp_f32_e32 v179, v167
	v_add_f32_e32 v167, 1.0, v171
	v_rcp_f32_e32 v130, v130
	v_rcp_f32_e32 v131, v131
	v_rcp_f32_e32 v181, v167
	v_rcp_f32_e32 v133, v133
	v_pk_mul_f32 v[178:179], v[76:77], v[178:179]
	v_pk_mul_f32 v[130:131], v[74:75], v[130:131]
	v_pk_mul_f32 v[180:181], v[68:69], v[180:181]
	v_pk_mul_f32 v[132:133], v[66:67], v[132:133]

; __device__ __forceinline__ float sigmoidf_(float x) { return __builtin_amdgcn_rcpf(1.f + __expf(-x)); }
; __device__ __forceinline__ float siluf_(float x) { return x * __builtin_amdgcn_rcpf(1.f + __expf(-x)); }
; __device__ __forceinline__ u32x4 pack8(const f32x4 a, const f32x4 b) { u32x4 w; w.x = cvt_pk_bf16(a[0], a[1]); w.y = cvt_pk_bf16(a[2], a[3]); w.z = cvt_pk_bf16(b[0], b[1]); w.w = cvt_pk_bf16(b[2], b[3]); return w; }
;     __device__ __forceinline__ void operator()(const f32x4 (&acc)[2][2][4][2], const Unit& u, int wr, int wc, int fr, int fq) const {
;     ...
;             for (int ai = 0; ai < 2; ++ai)
; #pragma unroll
;                 for (int m = 0; m < 4; ++m) { const int r = row0 + ai * HALF + m * 16;
;                     f32x4 v0 = acc[ai][bj][m][0], v1 = acc[ai][bj][m][1];
;                     if (mode == 1) {
; #pragma unroll
;                         for (int i = 0; i < 4; ++i) { v0[i] = siluf_(v0[i]) * QSCALE; v1[i] = siluf_(v1[i]) * QSCALE; }
;                     } else if (mode == 2) {
; #pragma unroll
;                         for (int i = 0; i < 4; ++i) { v0[i] = __logf(lb[i] + (1.f - lb[i]) * sigmoidf_(v0[i])); v1[i] = __logf(lb[4 + i] + (1.f - lb[4 + i]) * sigmoidf_(v1[i])); }
;                     } else if (mode == 3) {
; #pragma unroll
;                         for (int i = 0; i < 4; ++i) { v0[i] = siluf_(v0[i]); v1[i] = siluf_(v1[i]); }
;                     }
;                     const u32x4 w = pack8(v0, v1);
;                     *(u32x4*)(base + ((size_t)((r >> 6) * 4 + h)) * 32768 + part * 8192 + (r & 63) * 128 + c8) = w;
;                     if (grp == 1 && part < 3 && m == 3 && fr >= 13) *(u32x4*)(halo + (size_t)(r >> 6) * 4608 + (fr - 13) * 1536 + h * 384 + part * 128 + c8) = w;
.LBB0_785:
	s_and_b64 s[10:11], s[86:87], s[88:89]
	s_mul_i32 s86, s3, 0x180
	v_mov_b32_e32 v167, v147
	s_ashr_i32 s87, s86, 31
	s_lshl_b32 s66, s66, 7
	v_cvt_pk_bf16_f32 v130, v130, v131
	v_cvt_pk_bf16_f32 v131, v178, v179
	v_cvt_pk_bf16_f32 v132, v132, v133
	v_cvt_pk_bf16_f32 v133, v180, v181
	v_lshl_add_u64 v[176:177], v[176:177], 0, v[166:167]
	s_and_b64 s[88:89], s[10:11], s[0:1]
	global_store_dwordx4 v[176:177], v[130:133], off sc1
	s_and_saveexec_b64 s[10:11], s[88:89]
	s_cbranch_execz .LBB0_787
	v_lshl_add_u64 v[174:175], s[86:87], 1, v[174:175]
	s_lshl_b32 s68, s66, 1
	v_lshl_add_u64 v[174:175], v[174:175], 0, s[68:69]
	v_lshl_add_u64 v[174:175], v[174:175], 0, v[146:147]
	v_add_co_u32_e32 v174, vcc, 0xffff7000, v174
	s_nop 1
	v_addc_co_u32_e32 v175, vcc, -1, v175, vcc
	global_store_dwordx4 v[174:175], v[130:133], off offset:-3072 sc1

; __device__ __forceinline__ float sigmoidf_(float x) { return __builtin_amdgcn_rcpf(1.f + __expf(-x)); }
; __device__ __forceinline__ float siluf_(float x) { return x * __builtin_amdgcn_rcpf(1.f + __expf(-x)); }
; __device__ __forceinline__ u32x4 pack8(const f32x4 a, const f32x4 b) { u32x4 w; w.x = cvt_pk_bf16(a[0], a[1]); w.y = cvt_pk_bf16(a[2], a[3]); w.z = cvt_pk_bf16(b[0], b[1]); w.w = cvt_pk_bf16(b[2], b[3]); return w; }
;     __device__ __forceinline__ void operator()(const f32x4 (&acc)[2][2][4][2], const Unit& u, int wr, int wc, int fr, int fq) const {
;     ...
;             for (int ai = 0; ai < 2; ++ai)
; #pragma unroll
;                 for (int m = 0; m < 4; ++m) { const int r = row0 + ai * HALF + m * 16;
;                     f32x4 v0 = acc[ai][bj][m][0], v1 = acc[ai][bj][m][1];
;                     if (mode == 1) {
; #pragma unroll
;                         for (int i = 0; i < 4; ++i) { v0[i] = siluf_(v0[i]) * QSCALE; v1[i] = siluf_(v1[i]) * QSCALE; }
;                     } else if (mode == 2) {
; #pragma unroll
;                         for (int i = 0; i < 4; ++i) { v0[i] = __logf(lb[i] + (1.f - lb[i]) * sigmoidf_(v0[i])); v1[i] = __logf(lb[4 + i] + (1.f - lb[4 + i]) * sigmoidf_(v1[i])); }
;                     } else if (mode == 3) {
; #pragma unroll
;                         for (int i = 0; i < 4; ++i) { v0[i] = siluf_(v0[i]); v1[i] = siluf_(v1[i]); }
;                     }
;                     const u32x4 w = pack8(v0, v1);
;                     *(u32x4*)(base + ((size_t)((r >> 6) * 4 + h)) * 32768 + part * 8192 + (r & 63) * 128 + c8) = w;
.LBB0_793:
	s_add_i32 s10, s3, s46
	s_ashr_i32 s11, s10, 31
	s_lshl_b64 s[10:11], s[10:11], 16
	v_lshl_add_u64 v[136:137], v[136:137], 0, s[10:11]
	v_mov_b32_e32 v173, v147
	v_cvt_pk_bf16_f32 v130, v130, v131
	v_cvt_pk_bf16_f32 v131, v174, v175
	v_cvt_pk_bf16_f32 v132, v132, v133
	v_cvt_pk_bf16_f32 v133, v176, v177
	v_lshl_add_u64 v[172:173], v[136:137], 0, v[172:173]
	s_and_b64 vcc, exec, s[8:9]
	s_mov_b64 s[10:11], -1
	global_store_dwordx4 v[172:173], v[130:133], off sc1
	s_cbranch_vccnz .LBB0_797
	s_and_b64 vcc, exec, s[6:7]
	v_mov_b32_e32 v175, v37
	v_mov_b32_e32 v174, v36
	v_mov_b32_e32 v133, v35
	v_mov_b32_e32 v132, v34
	v_mov_b32_e32 v173, v45
	v_mov_b32_e32 v172, v44
	v_mov_b32_e32 v131, v43
	v_mov_b32_e32 v130, v42
	s_cbranch_vccnz .LBB0_796
	v_mul_f32_e32 v167, 0xbfb8aa3b, v44
	v_mul_f32_e32 v131, 0xbfb8aa3b, v34
	v_exp_f32_e32 v167, v167
	v_mul_f32_e32 v169, 0xbfb8aa3b, v36
	v_mul_f32_e32 v132, 0xbfb8aa3b, v43
	v_exp_f32_e32 v131, v131
	v_exp_f32_e32 v169, v169
	v_exp_f32_e32 v133, v132
	v_add_f32_e32 v167, 1.0, v167
	v_add_f32_e32 v131, 1.0, v131
	v_rcp_f32_e32 v172, v167
	v_add_f32_e32 v167, 1.0, v169
	v_mul_f32_e32 v169, 0xbfb8aa3b, v45
	v_mul_f32_e32 v130, 0xbfb8aa3b, v42
	v_rcp_f32_e32 v132, v131
	v_add_f32_e32 v131, 1.0, v133
	v_mul_f32_e32 v133, 0xbfb8aa3b, v35
	v_exp_f32_e32 v169, v169
	v_mul_f32_e32 v171, 0xbfb8aa3b, v37
	v_exp_f32_e32 v130, v130
	v_exp_f32_e32 v133, v133
	v_exp_f32_e32 v171, v171
	v_rcp_f32_e32 v174, v167
	v_add_f32_e32 v167, 1.0, v169
	v_add_f32_e32 v130, 1.0, v130
	v_add_f32_e32 v133, 1.0, v133
	v_rcp_f32_e32 v173, v167
	v_add_f32_e32 v167, 1.0, v171
	v_rcp_f32_e32 v130, v130
	v_rcp_f32_e32 v131, v131
	v_rcp_f32_e32 v175, v167
	v_rcp_f32_e32 v133, v133
	v_pk_mul_f32 v[172:173], v[44:45], v[172:173]
	v_pk_mul_f32 v[130:131], v[42:43], v[130:131]
	v_pk_mul_f32 v[174:175], v[36:37], v[174:175]
	v_pk_mul_f32 v[132:133], v[34:35], v[132:133]

; __device__ __forceinline__ float sigmoidf_(float x) { return __builtin_amdgcn_rcpf(1.f + __expf(-x)); }
; __device__ __forceinline__ float siluf_(float x) { return x * __builtin_amdgcn_rcpf(1.f + __expf(-x)); }
; __device__ __forceinline__ u32x4 pack8(const f32x4 a, const f32x4 b) { u32x4 w; w.x = cvt_pk_bf16(a[0], a[1]); w.y = cvt_pk_bf16(a[2], a[3]); w.z = cvt_pk_bf16(b[0], b[1]); w.w = cvt_pk_bf16(b[2], b[3]); return w; }
;     __device__ __forceinline__ void operator()(const f32x4 (&acc)[2][2][4][2], const Unit& u, int wr, int wc, int fr, int fq) const {
;     ...
;             for (int ai = 0; ai < 2; ++ai)
; #pragma unroll
;                 for (int m = 0; m < 4; ++m) { const int r = row0 + ai * HALF + m * 16;
;                     f32x4 v0 = acc[ai][bj][m][0], v1 = acc[ai][bj][m][1];
;                     if (mode == 1) {
; #pragma unroll
;                         for (int i = 0; i < 4; ++i) { v0[i] = siluf_(v0[i]) * QSCALE; v1[i] = siluf_(v1[i]) * QSCALE; }
;                     } else if (mode == 2) {
; #pragma unroll
;                         for (int i = 0; i < 4; ++i) { v0[i] = __logf(lb[i] + (1.f - lb[i]) * sigmoidf_(v0[i])); v1[i] = __logf(lb[4 + i] + (1.f - lb[4 + i]) * sigmoidf_(v1[i])); }
;                     } else if (mode == 3) {
; #pragma unroll
;                         for (int i = 0; i < 4; ++i) { v0[i] = siluf_(v0[i]); v1[i] = siluf_(v1[i]); }
;                     }
;                     const u32x4 w = pack8(v0, v1);
;                     *(u32x4*)(base + ((size_t)((r >> 6) * 4 + h)) * 32768 + part * 8192 + (r & 63) * 128 + c8) = w;
.LBB0_799:
	v_mov_b32_e32 v171, v147
	v_cvt_pk_bf16_f32 v130, v130, v131
	v_cvt_pk_bf16_f32 v131, v172, v173
	v_cvt_pk_bf16_f32 v132, v132, v133
	v_cvt_pk_bf16_f32 v133, v174, v175
	v_lshl_add_u64 v[170:171], v[136:137], 0, v[170:171]
	s_and_b64 vcc, exec, s[8:9]
	s_mov_b64 s[10:11], -1
	global_store_dwordx4 v[170:171], v[130:133], off sc1
	s_cbranch_vccnz .LBB0_803
	s_and_b64 vcc, exec, s[6:7]
	v_mov_b32_e32 v173, v21
	v_mov_b32_e32 v172, v20
	v_mov_b32_e32 v133, v19
	v_mov_b32_e32 v132, v18
	v_mov_b32_e32 v171, v29
	v_mov_b32_e32 v170, v28
	v_mov_b32_e32 v131, v27
	v_mov_b32_e32 v130, v26
	s_cbranch_vccnz .LBB0_802
	v_mul_f32_e32 v167, 0xbfb8aa3b, v28
	v_mul_f32_e32 v131, 0xbfb8aa3b, v18
	v_exp_f32_e32 v167, v167
	v_mul_f32_e32 v169, 0xbfb8aa3b, v20
	v_mul_f32_e32 v132, 0xbfb8aa3b, v27
	v_exp_f32_e32 v131, v131
	v_exp_f32_e32 v169, v169
	v_exp_f32_e32 v133, v132
	v_add_f32_e32 v167, 1.0, v167
	v_add_f32_e32 v131, 1.0, v131
	v_rcp_f32_e32 v170, v167
	v_add_f32_e32 v167, 1.0, v169
	v_mul_f32_e32 v169, 0xbfb8aa3b, v29
	v_mul_f32_e32 v130, 0xbfb8aa3b, v26
	v_rcp_f32_e32 v132, v131
	v_add_f32_e32 v131, 1.0, v133
	v_mul_f32_e32 v133, 0xbfb8aa3b, v19
	v_exp_f32_e32 v169, v169
	v_mul_f32_e32 v171, 0xbfb8aa3b, v21
	v_exp_f32_e32 v130, v130
	v_exp_f32_e32 v133, v133
	v_exp_f32_e32 v173, v171
	v_rcp_f32_e32 v172, v167
	v_add_f32_e32 v167, 1.0, v169
	v_add_f32_e32 v130, 1.0, v130
	v_add_f32_e32 v133, 1.0, v133
	v_rcp_f32_e32 v171, v167
	v_add_f32_e32 v167, 1.0, v173
	v_rcp_f32_e32 v130, v130
	v_rcp_f32_e32 v131, v131
	v_rcp_f32_e32 v173, v167
	v_rcp_f32_e32 v133, v133
	v_pk_mul_f32 v[170:171], v[28:29], v[170:171]
	v_pk_mul_f32 v[130:131], v[26:27], v[130:131]
	v_pk_mul_f32 v[172:173], v[20:21], v[172:173]
	v_pk_mul_f32 v[132:133], v[18:19], v[132:133]

; __device__ __forceinline__ float sigmoidf_(float x) { return __builtin_amdgcn_rcpf(1.f + __expf(-x)); }
; __device__ __forceinline__ float siluf_(float x) { return x * __builtin_amdgcn_rcpf(1.f + __expf(-x)); }
; __device__ __forceinline__ u32x4 pack8(const f32x4 a, const f32x4 b) { u32x4 w; w.x = cvt_pk_bf16(a[0], a[1]); w.y = cvt_pk_bf16(a[2], a[3]); w.z = cvt_pk_bf16(b[0], b[1]); w.w = cvt_pk_bf16(b[2], b[3]); return w; }
;     __device__ __forceinline__ void operator()(const f32x4 (&acc)[2][2][4][2], const Unit& u, int wr, int wc, int fr, int fq) const {
;     ...
;             for (int ai = 0; ai < 2; ++ai)
; #pragma unroll
;                 for (int m = 0; m < 4; ++m) { const int r = row0 + ai * HALF + m * 16;
;                     f32x4 v0 = acc[ai][bj][m][0], v1 = acc[ai][bj][m][1];
;                     if (mode == 1) {
; #pragma unroll
;                         for (int i = 0; i < 4; ++i) { v0[i] = siluf_(v0[i]) * QSCALE; v1[i] = siluf_(v1[i]) * QSCALE; }
;                     } else if (mode == 2) {
; #pragma unroll
;                         for (int i = 0; i < 4; ++i) { v0[i] = __logf(lb[i] + (1.f - lb[i]) * sigmoidf_(v0[i])); v1[i] = __logf(lb[4 + i] + (1.f - lb[4 + i]) * sigmoidf_(v1[i])); }
;                     } else if (mode == 3) {
; #pragma unroll
;                         for (int i = 0; i < 4; ++i) { v0[i] = siluf_(v0[i]); v1[i] = siluf_(v1[i]); }
;                     }
;                     const u32x4 w = pack8(v0, v1);
;                     *(u32x4*)(base + ((size_t)((r >> 6) * 4 + h)) * 32768 + part * 8192 + (r & 63) * 128 + c8) = w;
.LBB0_805:
	v_mov_b32_e32 v169, v147
	v_cvt_pk_bf16_f32 v130, v130, v131
	v_cvt_pk_bf16_f32 v131, v170, v171
	v_cvt_pk_bf16_f32 v132, v132, v133
	v_cvt_pk_bf16_f32 v133, v172, v173
	v_lshl_add_u64 v[168:169], v[136:137], 0, v[168:169]
	s_and_b64 vcc, exec, s[8:9]
	s_mov_b64 s[8:9], -1
	global_store_dwordx4 v[168:169], v[130:133], off sc1
	s_cbranch_vccnz .LBB0_809
	s_and_b64 vcc, exec, s[6:7]
	v_mov_b32_e32 v171, v5
	v_mov_b32_e32 v170, v4
	v_mov_b32_e32 v133, v3
	v_mov_b32_e32 v132, v2
	v_mov_b32_e32 v169, v13
	v_mov_b32_e32 v168, v12
	v_mov_b32_e32 v131, v11
	v_mov_b32_e32 v130, v10
	s_cbranch_vccnz .LBB0_808
	v_mul_f32_e32 v167, 0xbfb8aa3b, v12
	v_mul_f32_e32 v131, 0xbfb8aa3b, v2
	v_exp_f32_e32 v167, v167
	v_mul_f32_e32 v168, 0xbfb8aa3b, v4
	v_mul_f32_e32 v132, 0xbfb8aa3b, v11
	v_exp_f32_e32 v131, v131
	v_exp_f32_e32 v169, v168
	v_exp_f32_e32 v133, v132
	v_add_f32_e32 v167, 1.0, v167
	v_add_f32_e32 v131, 1.0, v131
	v_rcp_f32_e32 v168, v167
	v_add_f32_e32 v167, 1.0, v169
	v_mul_f32_e32 v169, 0xbfb8aa3b, v13
	v_mul_f32_e32 v130, 0xbfb8aa3b, v10
	v_rcp_f32_e32 v132, v131
	v_add_f32_e32 v131, 1.0, v133
	v_mul_f32_e32 v133, 0xbfb8aa3b, v3
	v_exp_f32_e32 v169, v169
	v_mul_f32_e32 v170, 0xbfb8aa3b, v5
	v_exp_f32_e32 v130, v130
	v_exp_f32_e32 v133, v133
	v_exp_f32_e32 v171, v170
	v_rcp_f32_e32 v170, v167
	v_add_f32_e32 v167, 1.0, v169
	v_add_f32_e32 v130, 1.0, v130
	v_add_f32_e32 v133, 1.0, v133
	v_rcp_f32_e32 v169, v167
	v_add_f32_e32 v167, 1.0, v171
	v_rcp_f32_e32 v130, v130
	v_rcp_f32_e32 v131, v131
	v_rcp_f32_e32 v171, v167
	v_rcp_f32_e32 v133, v133
	v_pk_mul_f32 v[168:169], v[12:13], v[168:169]
	v_pk_mul_f32 v[130:131], v[10:11], v[130:131]
	v_pk_mul_f32 v[170:171], v[4:5], v[170:171]
	v_pk_mul_f32 v[132:133], v[2:3], v[132:133]

; __device__ __forceinline__ float sigmoidf_(float x) { return __builtin_amdgcn_rcpf(1.f + __expf(-x)); }
; __device__ __forceinline__ float siluf_(float x) { return x * __builtin_amdgcn_rcpf(1.f + __expf(-x)); }
; __device__ __forceinline__ u32x4 pack8(const f32x4 a, const f32x4 b) { u32x4 w; w.x = cvt_pk_bf16(a[0], a[1]); w.y = cvt_pk_bf16(a[2], a[3]); w.z = cvt_pk_bf16(b[0], b[1]); w.w = cvt_pk_bf16(b[2], b[3]); return w; }
;     __device__ __forceinline__ void operator()(const f32x4 (&acc)[2][2][4][2], const Unit& u, int wr, int wc, int fr, int fq) const {
;     ...
;             for (int ai = 0; ai < 2; ++ai)
; #pragma unroll
;                 for (int m = 0; m < 4; ++m) { const int r = row0 + ai * HALF + m * 16;
;                     f32x4 v0 = acc[ai][bj][m][0], v1 = acc[ai][bj][m][1];
;                     if (mode == 1) {
; #pragma unroll
;                         for (int i = 0; i < 4; ++i) { v0[i] = siluf_(v0[i]) * QSCALE; v1[i] = siluf_(v1[i]) * QSCALE; }
;                     } else if (mode == 2) {
; #pragma unroll
;                         for (int i = 0; i < 4; ++i) { v0[i] = __logf(lb[i] + (1.f - lb[i]) * sigmoidf_(v0[i])); v1[i] = __logf(lb[4 + i] + (1.f - lb[4 + i]) * sigmoidf_(v1[i])); }
;                     } else if (mode == 3) {
; #pragma unroll
;                         for (int i = 0; i < 4; ++i) { v0[i] = siluf_(v0[i]); v1[i] = siluf_(v1[i]); }
;                     }
;                     const u32x4 w = pack8(v0, v1);
;                     *(u32x4*)(base + ((size_t)((r >> 6) * 4 + h)) * 32768 + part * 8192 + (r & 63) * 128 + c8) = w;
;                     if (grp == 1 && part < 3 && m == 3 && fr >= 13) *(u32x4*)(halo + (size_t)(r >> 6) * 4608 + (fr - 13) * 1536 + h * 384 + part * 128 + c8) = w;
.LBB0_811:
	v_mov_b32_e32 v167, v147
	v_cvt_pk_bf16_f32 v130, v130, v131
	v_cvt_pk_bf16_f32 v131, v168, v169
	v_cvt_pk_bf16_f32 v132, v132, v133
	v_cvt_pk_bf16_f32 v133, v170, v171
	v_lshl_add_u64 v[136:137], v[136:137], 0, v[166:167]
	global_store_dwordx4 v[136:137], v[130:133], off sc1
	s_and_saveexec_b64 s[6:7], s[88:89]
	s_cbranch_execz .LBB0_813
	v_lshl_add_u64 v[134:135], s[86:87], 1, v[134:135]
	s_lshl_b32 s68, s66, 1
	v_lshl_add_u64 v[134:135], v[134:135], 0, s[68:69]
	v_lshl_add_u64 v[134:135], v[134:135], 0, v[146:147]
	v_add_co_u32_e32 v134, vcc, 0xffff7000, v134
	s_nop 1
	v_addc_co_u32_e32 v135, vcc, -1, v135, vcc
	global_store_dwordx4 v[134:135], v[130:133], off offset:-3072 sc1
